# pipelined attention loop + GEMM K-loop frag ring + hyena helper-wave L2 prefetch
# speedup vs baseline: 1.0690x; 1.0690x over previous
; DI f32x16 zero16() { f32x16 z; for (int i = 0; i < 16; ++i) z[i] = 0.f; return z; }
; template <bool AT>
; DI void gemm_main(f32x16 (&acc)[2][4], const u16* __restrict__ R, int ldr, const u16* __restrict__ Cm, int ldc,
;                   const u16* __restrict__ RT, int ldrt, int K, char* smem, int tid) {
;     ...
; #pragma unroll
;   for (int a = 0; a < 2; ++a)
; #pragma unroll
;     for (int b = 0; b < 4; ++b) acc[a][b] = zero16();
;   const int nk = K / 64;
; #pragma unroll
;   for (int i = 0; i < 4; ++i) {
;     const int cid = tid + NT * i;
;     const int row = cid >> 3, kc = cid & 7;
;     if (AT) {
;       const int kr = cid >> 5, tc = cid & 31;
;       rr[i] = *(const u32x4*)(RT + (size_t)kr * ldrt + tc * 8);
;     } else {
;       rr[i] = *(const u32x4*)(R + (size_t)row * ldr + kc * 8);
;     }
;     cr[i] = *(const u32x4*)(Cm + (size_t)row * ldc + kc * 8);
;   }
;   for (int kt = -1; kt < nk; ++kt) {
;     if (kt + 1 < nk) {
;       const int ks1 = kt + 1;
;       u16* Rs = S0 + (ks1 & 1) * STG;
;       u16* Cs = Rs + 256 * 72;
; #pragma unroll
;       for (int i = 0; i < 4; ++i) {
;         const int cid = tid + NT * i;
;         const int row = cid >> 3, kc = cid & 7;
;         if (AT && ks1 < 8) {
;           const int kr = cid >> 5, tc = cid & 31;
;           *(u32x4*)(Rs + kr * 264 + tc * 8) = rr[i];
;         } else {
;           *(u32x4*)(Rs + row * 72 + kc * 8) = rr[i];
;         }
;         *(u32x4*)(Cs + row * 72 + kc * 8) = cr[i];
;       }
.LBB0_328:
	s_or_b64 exec, exec, s[8:9]
	v_lshlrev_b32_e32 v0, 3, v176
	v_and_b32_e32 v0, 56, v0
	s_lshr_b32 s77, s88, 6
	s_lshl_b32 s56, s74, 8
	s_lshl_b32 s8, s78, 19
	v_lshlrev_b32_e32 v188, 1, v0
	v_add_u32_e32 v0, 0x200, v176
	s_add_u32 s8, s36, s8
	v_ashrrev_i32_e32 v36, 3, v0
	v_add_u32_e32 v0, 0x400, v176
	s_addc_u32 s9, s37, 0
	s_lshl_b64 s[78:79], s[56:57], 11
	v_readlane_b32 s80, v248, 29
	v_ashrrev_i32_e32 v32, 3, v176
	v_ashrrev_i32_e32 v40, 3, v0
	v_add_u32_e32 v0, 0x600, v176
	s_add_u32 s78, s80, s78
	v_readlane_b32 s80, v248, 30
	v_ashrrev_i32_e32 v33, 31, v32
	v_ashrrev_i32_e32 v37, 31, v36
	v_ashrrev_i32_e32 v44, 3, v0
	s_addc_u32 s79, s80, s79
	v_lshl_add_u64 v[12:13], s[8:9], 0, v[188:189]
	v_lshlrev_b64 v[34:35], 11, v[32:33]
	v_lshlrev_b64 v[38:39], 11, v[36:37]
	v_ashrrev_i32_e32 v41, 31, v40
	v_ashrrev_i32_e32 v45, 31, v44
	v_lshl_add_u64 v[28:29], s[78:79], 0, v[188:189]
	v_lshlrev_b64 v[42:43], 11, v[40:41]
	v_lshlrev_b64 v[46:47], 11, v[44:45]
	v_lshl_add_u64 v[52:53], v[12:13], 0, v[38:39]
	v_lshl_add_u64 v[54:55], v[12:13], 0, v[34:35]
	v_lshl_add_u64 v[48:49], v[12:13], 0, v[46:47]
	v_lshl_add_u64 v[50:51], v[12:13], 0, v[42:43]
	global_load_dwordx4 v[8:11], v[52:53], off
	global_load_dwordx4 v[12:15], v[54:55], off
	v_lshl_add_u64 v[56:57], v[28:29], 0, v[34:35]
	global_load_dwordx4 v[16:19], v[56:57], off
	v_lshl_add_u64 v[58:59], v[28:29], 0, v[38:39]
	global_load_dwordx4 v[20:23], v[58:59], off
	s_waitcnt lgkmcnt(0)
	global_load_dwordx4 v[0:3], v[48:49], off
	global_load_dwordx4 v[4:7], v[50:51], off
	v_lshl_add_u64 v[60:61], v[28:29], 0, v[42:43]
	global_load_dwordx4 v[24:27], v[60:61], off
	v_lshl_add_u64 v[62:63], v[28:29], 0, v[46:47]
	global_load_dwordx4 v[28:31], v[62:63], off
	global_load_dwordx4 v[144:147], v[54:55], off offset:128
	global_load_dwordx4 v[136:139], v[52:53], off offset:128
	global_load_dwordx4 v[132:135], v[50:51], off offset:128
	global_load_dwordx4 v[128:131], v[48:49], off offset:128
	global_load_dwordx4 v[152:155], v[56:57], off offset:128
	global_load_dwordx4 v[148:151], v[58:59], off offset:128
	global_load_dwordx4 v[140:143], v[60:61], off offset:128
	global_load_dwordx4 v[156:159], v[62:63], off offset:128
	v_and_b32_e32 v177, 31, v176
	v_lshrrev_b32_e32 v33, 1, v176
	s_mov_b32 s8, 0xfffffc0
	v_and_or_b32 v45, v33, s8, v177
	s_movk_i32 s8, 0x48
	v_mul_lo_u32 v185, v32, s8
	v_mul_lo_u32 v184, v36, s8
	v_mul_lo_u32 v183, v40, s8
	v_mul_lo_u32 v182, v44, s8
	s_lshl_b32 s8, s11, 8
	s_and_b32 s8, s8, 0xfffffc00
	s_mov_b32 s9, s57
	v_add_u32_e32 v186, 0, v188
	s_or_b32 s8, s8, s10
	v_lshlrev_b32_e32 v37, 1, v176
	v_lshlrev_b32_e32 v41, 4, v176
	v_lshl_add_u32 v36, v185, 1, v186
	s_lshl_b64 s[8:9], s[8:9], 11
	v_and_b32_e32 v178, 16, v33
	v_and_or_b32 v33, v37, s95, v177
	v_lshl_add_u32 v37, v184, 1, v186
	v_lshl_add_u32 v40, v183, 1, v186
	v_lshl_add_u32 v44, v182, 1, v186
	v_mul_u32_u24_e32 v179, 0x90, v33
	v_lshl_add_u64 v[32:33], v[46:47], 0, s[8:9]
	v_mul_lo_u32 v180, v45, s94
	v_add_u32_e32 v181, 0, v178
	s_mov_b32 s78, 0
	s_waitcnt vmcnt(14)
	ds_write_b128 v36, v[12:15]
	s_waitcnt vmcnt(13)
	ds_write_b128 v36, v[16:19] offset:36864
	ds_write_b128 v37, v[8:11]
	s_waitcnt vmcnt(12)
	ds_write_b128 v37, v[20:23] offset:36864
	s_waitcnt vmcnt(10)
	ds_write_b128 v40, v[4:7]
	s_waitcnt vmcnt(9)
	ds_write_b128 v40, v[24:27] offset:36864
	ds_write_b128 v44, v[0:3]
	s_waitcnt vmcnt(8)
	ds_write_b128 v44, v[28:31] offset:36864
	v_and_b32_e32 v2, 0x70, v41
	v_lshl_add_u64 v[0:1], v[42:43], 0, s[8:9]
	v_or_b32_e32 v0, v0, v2
	v_lshl_add_u64 v[162:163], s[72:73], 0, v[0:1]
	v_lshl_add_u64 v[0:1], v[38:39], 0, s[8:9]
	v_or_b32_e32 v0, v0, v2
	v_lshl_add_u64 v[164:165], s[72:73], 0, v[0:1]
	v_lshl_add_u64 v[0:1], v[34:35], 0, s[8:9]
	v_readlane_b32 s8, v248, 36
	v_or_b32_e32 v0, v0, v2
	s_add_u32 s8, s8, s64
	v_readlane_b32 s9, v248, 38
	v_or_b32_e32 v32, v32, v2
	v_lshl_add_u64 v[166:167], s[72:73], 0, v[0:1]
	v_or_b32_e32 v46, v46, v2
	s_addc_u32 s9, s9, 0
	v_or_b32_e32 v42, v42, v2
	v_or_b32_e32 v38, v38, v2
	v_or_b32_e32 v34, v34, v2
	v_mov_b32_e32 v0, 0
	v_lshl_add_u64 v[160:161], s[72:73], 0, v[32:33]
	v_lshl_add_u64 v[168:169], s[8:9], 0, v[46:47]
	v_lshl_add_u64 v[170:171], s[8:9], 0, v[42:43]
	v_lshl_add_u64 v[172:173], s[8:9], 0, v[38:39]
	v_lshl_add_u64 v[174:175], s[8:9], 0, v[34:35]
	s_mov_b64 s[8:9], 0
	v_mov_b32_e32 v1, v0
	v_mov_b32_e32 v2, v0
	v_mov_b32_e32 v3, v0
	v_mov_b32_e32 v4, v0
	v_mov_b32_e32 v5, v0
	v_mov_b32_e32 v6, v0
	v_mov_b32_e32 v7, v0
	v_mov_b32_e32 v8, v0
	v_mov_b32_e32 v9, v0
	v_mov_b32_e32 v10, v0
	v_mov_b32_e32 v11, v0
	v_mov_b32_e32 v12, v0
	v_mov_b32_e32 v13, v0
	v_mov_b32_e32 v14, v0
	v_mov_b32_e32 v15, v0
	v_mov_b32_e32 v16, v0
	v_mov_b32_e32 v17, v0
	v_mov_b32_e32 v18, v0
	v_mov_b32_e32 v19, v0
	v_mov_b32_e32 v20, v0
	v_mov_b32_e32 v21, v0
	v_mov_b32_e32 v22, v0
	v_mov_b32_e32 v23, v0
	v_mov_b32_e32 v24, v0
	v_mov_b32_e32 v25, v0
	v_mov_b32_e32 v26, v0
	v_mov_b32_e32 v27, v0
	v_mov_b32_e32 v28, v0
	v_mov_b32_e32 v29, v0
	v_mov_b32_e32 v30, v0
	v_mov_b32_e32 v31, v0
	v_mov_b32_e32 v32, v0
	v_mov_b32_e32 v33, v0
	v_mov_b32_e32 v34, v0
	v_mov_b32_e32 v35, v0
	v_mov_b32_e32 v36, v0
	v_mov_b32_e32 v37, v0
	v_mov_b32_e32 v38, v0
	v_mov_b32_e32 v39, v0
	v_mov_b32_e32 v40, v0
	v_mov_b32_e32 v41, v0
	v_mov_b32_e32 v42, v0
	v_mov_b32_e32 v43, v0
	v_mov_b32_e32 v44, v0
	v_mov_b32_e32 v45, v0
	v_mov_b32_e32 v46, v0
	v_mov_b32_e32 v47, v0
	v_mov_b32_e32 v48, v0
	v_mov_b32_e32 v49, v0
	v_mov_b32_e32 v50, v0
	v_mov_b32_e32 v51, v0
	v_mov_b32_e32 v52, v0
	v_mov_b32_e32 v53, v0
	v_mov_b32_e32 v54, v0
	v_mov_b32_e32 v55, v0
	v_mov_b32_e32 v56, v0
	v_mov_b32_e32 v57, v0
; template <bool AT>
; DI void gemm_main(f32x16 (&acc)[2][4], const u16* __restrict__ R, int ldr, const u16* __restrict__ Cm, int ldc,
;                   const u16* __restrict__ RT, int ldrt, int K, char* smem, int tid) {
;     ...
;   for (int kt = -1; kt < nk; ++kt) {
;     if (kt + 1 < nk) {
;       const int ks1 = kt + 1;
;       u16* Rs = S0 + (ks1 & 1) * STG;
;       u16* Cs = Rs + 256 * 72;
; #pragma unroll
;       for (int i = 0; i < 4; ++i) {
;         const int cid = tid + NT * i;
;         const int row = cid >> 3, kc = cid & 7;
;         if (AT && ks1 < 8) {
;           const int kr = cid >> 5, tc = cid & 31;
;           *(u32x4*)(Rs + kr * 264 + tc * 8) = rr[i];
;         } else {
;           *(u32x4*)(Rs + row * 72 + kc * 8) = rr[i];
;         }
;         *(u32x4*)(Cs + row * 72 + kc * 8) = cr[i];
;       }
;     }
;     if (kt + 2 < nk) {
;       const int kn = kt + 2;
; #pragma unroll
;       for (int i = 0; i < 4; ++i) {
;         const int cid = tid + NT * i;
;         const int row = cid >> 3, kc = cid & 7;
;         if (AT && kn < 8) {
;           const int kr = cid >> 5, tc = cid & 31;
;           rr[i] = *(const u32x4*)(RT + (size_t)(kn * 64 + kr) * ldrt + tc * 8);
;         } else {
;           rr[i] = *(const u32x4*)(R + (size_t)row * ldr + kn * 64 + kc * 8);
;         }
;         cr[i] = *(const u32x4*)(Cm + (size_t)row * ldc + kn * 64 + kc * 8);
;       }
;     }
;     __builtin_amdgcn_sched_barrier(0x38F);
;     if (kt >= 0) {
;       const u16* Rs = S0 + (kt & 1) * STG;
;       const u16* Cs = Rs + 256 * 72;
;       const u16* RTs = Rs;
; #pragma unroll
;       for (int ks = 0; ks < 4; ++ks) {
;         bf16x8 rf[2];
; #pragma unroll
;         for (int rb = 0; rb < 2; ++rb) {
;           if (AT && kt < 8) {
;             const u16* src = RTs + (16 * ks + 8 * g) * 264 + 64 * wr + 32 * rb + li;
;             bf16x8 t;
; #pragma unroll
;             for (int j = 0; j < 8; ++j) t[j] = (short)src[j * 264];
;             rf[rb] = t;
;           } else {
;             rf[rb] = *(const bf16x8*)(Rs + (64 * wr + 32 * rb + li) * 72 + 16 * ks + 8 * g);
;           }
;         }
; #pragma unroll
;         for (int cb = 0; cb < 4; ++cb) {
;           const bf16x8 cfv = *(const bf16x8*)(Cs + (128 * wc + 32 * cb + li) * 72 + 16 * ks + 8 * g);
; #pragma unroll
;           for (int rb = 0; rb < 2; ++rb) acc[rb][cb] = MFMA(rf[rb], cfv, acc[rb][cb]);
	v_mov_b32_e32 v58, v0
	v_mov_b32_e32 v59, v0
	v_mov_b32_e32 v60, v0
	v_mov_b32_e32 v61, v0
	v_mov_b32_e32 v62, v0
	v_mov_b32_e32 v63, v0
	v_mov_b32_e32 v64, v0
	v_mov_b32_e32 v65, v0
	v_mov_b32_e32 v66, v0
	v_mov_b32_e32 v67, v0
	v_mov_b32_e32 v68, v0
	v_mov_b32_e32 v69, v0
	v_mov_b32_e32 v70, v0
	v_mov_b32_e32 v71, v0
	v_mov_b32_e32 v72, v0
	v_mov_b32_e32 v73, v0
	v_mov_b32_e32 v74, v0
	v_mov_b32_e32 v75, v0
	v_mov_b32_e32 v76, v0
	v_mov_b32_e32 v77, v0
	v_mov_b32_e32 v78, v0
	v_mov_b32_e32 v79, v0
	v_mov_b32_e32 v80, v0
	v_mov_b32_e32 v81, v0
	v_mov_b32_e32 v82, v0
	v_mov_b32_e32 v83, v0
	v_mov_b32_e32 v84, v0
	v_mov_b32_e32 v85, v0
	v_mov_b32_e32 v86, v0
	v_mov_b32_e32 v87, v0
	v_mov_b32_e32 v88, v0
	v_mov_b32_e32 v89, v0
	v_mov_b32_e32 v90, v0
	v_mov_b32_e32 v91, v0
	v_mov_b32_e32 v92, v0
	v_mov_b32_e32 v93, v0
	v_mov_b32_e32 v94, v0
	v_mov_b32_e32 v95, v0
	v_mov_b32_e32 v96, v0
	v_mov_b32_e32 v97, v0
	v_mov_b32_e32 v98, v0
	v_mov_b32_e32 v99, v0
	v_mov_b32_e32 v100, v0
	v_mov_b32_e32 v101, v0
	v_mov_b32_e32 v102, v0
	v_mov_b32_e32 v103, v0
	v_mov_b32_e32 v104, v0
	v_mov_b32_e32 v105, v0
	v_mov_b32_e32 v106, v0
	v_mov_b32_e32 v107, v0
	v_mov_b32_e32 v108, v0
	v_mov_b32_e32 v109, v0
	v_mov_b32_e32 v110, v0
	v_mov_b32_e32 v111, v0
	v_mov_b32_e32 v112, v0
	v_mov_b32_e32 v113, v0
	v_mov_b32_e32 v114, v0
	v_mov_b32_e32 v115, v0
	v_mov_b32_e32 v116, v0
	v_mov_b32_e32 v117, v0
	v_mov_b32_e32 v118, v0
	v_mov_b32_e32 v119, v0
	v_mov_b32_e32 v120, v0
	v_mov_b32_e32 v121, v0
	v_mov_b32_e32 v122, v0
	v_mov_b32_e32 v123, v0
	v_mov_b32_e32 v124, v0
	v_mov_b32_e32 v125, v0
	v_mov_b32_e32 v126, v0
	v_mov_b32_e32 v127, v0
	s_waitcnt lgkmcnt(0)
	s_barrier
	v_add_u32_e32 v187, v181, v180
	v_add_u32_e32 v190, v181, v179
	v_lshl_add_u32 v191, v185, 1, v186
	v_lshl_add_u32 v196, v184, 1, v186
	v_lshl_add_u32 v197, v183, 1, v186
	v_lshl_add_u32 v249, v182, 1, v186
	v_add_u32_e32 v191, 0x12000, v191
	v_add_u32_e32 v196, 0x12000, v196
	v_add_u32_e32 v197, 0x12000, v197
	v_add_u32_e32 v249, 0x12000, v249
	s_movk_i32 s78, 7
.Lgt_loop:
	ds_read_b128 v[192:195], v187 offset:0
	ds_read_b128 v[220:223], v187 offset:4608
	ds_read_b128 v[232:235], v190 offset:36864
	ds_read_b128 v[236:239], v190 offset:41472
	ds_read_b128 v[240:243], v190 offset:46080
	ds_read_b128 v[244:247], v190 offset:50688
	ds_read_b128 v[224:227], v187 offset:32
	ds_read_b128 v[228:231], v187 offset:4640
	s_waitcnt lgkmcnt(5)
	v_mfma_f32_32x32x16_bf16 v[112:127], v[192:195], v[232:235], v[112:127]
	v_mfma_f32_32x32x16_bf16 v[48:63], v[220:223], v[232:235], v[48:63]
	ds_read_b128 v[232:235], v190 offset:36896
	s_waitcnt vmcnt(0)
	ds_write_b128 v191, v[144:147]
	s_waitcnt lgkmcnt(6)
	v_mfma_f32_32x32x16_bf16 v[96:111], v[192:195], v[236:239], v[96:111]
	v_mfma_f32_32x32x16_bf16 v[32:47], v[220:223], v[236:239], v[32:47]
	ds_read_b128 v[236:239], v190 offset:41504
	ds_write_b128 v191, v[152:155] offset:36864
	s_waitcnt lgkmcnt(7)
	v_mfma_f32_32x32x16_bf16 v[80:95], v[192:195], v[240:243], v[80:95]
	v_mfma_f32_32x32x16_bf16 v[16:31], v[220:223], v[240:243], v[16:31]
	ds_read_b128 v[240:243], v190 offset:46112
	ds_write_b128 v196, v[136:139]
	s_waitcnt lgkmcnt(8)
	v_mfma_f32_32x32x16_bf16 v[64:79], v[192:195], v[244:247], v[64:79]
	v_mfma_f32_32x32x16_bf16 v[0:15], v[220:223], v[244:247], v[0:15]
	ds_read_b128 v[244:247], v190 offset:50720
	ds_write_b128 v196, v[148:151] offset:36864
	ds_read_b128 v[192:195], v187 offset:64
	ds_read_b128 v[220:223], v187 offset:4672
	s_waitcnt lgkmcnt(9)
	v_mfma_f32_32x32x16_bf16 v[112:127], v[224:227], v[232:235], v[112:127]
	v_mfma_f32_32x32x16_bf16 v[48:63], v[228:231], v[232:235], v[48:63]
	ds_read_b128 v[232:235], v190 offset:36928
	ds_write_b128 v197, v[132:135]
	s_waitcnt lgkmcnt(9)
	v_mfma_f32_32x32x16_bf16 v[96:111], v[224:227], v[236:239], v[96:111]
	v_mfma_f32_32x32x16_bf16 v[32:47], v[228:231], v[236:239], v[32:47]
	ds_read_b128 v[236:239], v190 offset:41536
	ds_write_b128 v197, v[140:143] offset:36864
	s_waitcnt lgkmcnt(9)
	v_mfma_f32_32x32x16_bf16 v[80:95], v[224:227], v[240:243], v[80:95]
	v_mfma_f32_32x32x16_bf16 v[16:31], v[228:231], v[240:243], v[16:31]
	ds_read_b128 v[240:243], v190 offset:46144
	ds_write_b128 v249, v[128:131]
	s_waitcnt lgkmcnt(9)
	v_mfma_f32_32x32x16_bf16 v[64:79], v[224:227], v[244:247], v[64:79]
	v_mfma_f32_32x32x16_bf16 v[0:15], v[228:231], v[244:247], v[0:15]
	ds_read_b128 v[244:247], v190 offset:50752
	ds_write_b128 v249, v[156:159] offset:36864
	ds_read_b128 v[224:227], v187 offset:96
	ds_read_b128 v[228:231], v187 offset:4704
	s_waitcnt lgkmcnt(9)
	v_mfma_f32_32x32x16_bf16 v[112:127], v[192:195], v[232:235], v[112:127]
	v_mfma_f32_32x32x16_bf16 v[48:63], v[220:223], v[232:235], v[48:63]
	ds_read_b128 v[232:235], v190 offset:36960
	v_subrev_u32_e32 v191, 0x12000, v191
	global_load_dwordx4 v[144:147], v[174:175], off
	v_lshl_add_u64 v[174:175], v[174:175], 0, s[58:59]
	s_waitcnt lgkmcnt(8)
	v_mfma_f32_32x32x16_bf16 v[96:111], v[192:195], v[236:239], v[96:111]
	v_mfma_f32_32x32x16_bf16 v[32:47], v[220:223], v[236:239], v[32:47]
	ds_read_b128 v[236:239], v190 offset:41568
	v_subrev_u32_e32 v196, 0x12000, v196
	global_load_dwordx4 v[152:155], v[166:167], off
	v_lshl_add_u64 v[166:167], v[166:167], 0, s[58:59]
	s_waitcnt lgkmcnt(7)
	v_mfma_f32_32x32x16_bf16 v[80:95], v[192:195], v[240:243], v[80:95]
	v_mfma_f32_32x32x16_bf16 v[16:31], v[220:223], v[240:243], v[16:31]
	ds_read_b128 v[240:243], v190 offset:46176
	v_subrev_u32_e32 v197, 0x12000, v197
	global_load_dwordx4 v[136:139], v[172:173], off
	v_lshl_add_u64 v[172:173], v[172:173], 0, s[58:59]
	s_waitcnt lgkmcnt(6)
; template <bool AT>
; DI void gemm_main(f32x16 (&acc)[2][4], const u16* __restrict__ R, int ldr, const u16* __restrict__ Cm, int ldc,
;                   const u16* __restrict__ RT, int ldrt, int K, char* smem, int tid) {
;     ...
;   for (int kt = -1; kt < nk; ++kt) {
;     if (kt + 1 < nk) {
;       const int ks1 = kt + 1;
;       u16* Rs = S0 + (ks1 & 1) * STG;
;       u16* Cs = Rs + 256 * 72;
; #pragma unroll
;       for (int i = 0; i < 4; ++i) {
;         const int cid = tid + NT * i;
;         const int row = cid >> 3, kc = cid & 7;
;         if (AT && ks1 < 8) {
;           const int kr = cid >> 5, tc = cid & 31;
;           *(u32x4*)(Rs + kr * 264 + tc * 8) = rr[i];
;         } else {
;           *(u32x4*)(Rs + row * 72 + kc * 8) = rr[i];
;         }
;         *(u32x4*)(Cs + row * 72 + kc * 8) = cr[i];
;       }
;     }
;     if (kt + 2 < nk) {
;       const int kn = kt + 2;
; #pragma unroll
;       for (int i = 0; i < 4; ++i) {
;         const int cid = tid + NT * i;
;         const int row = cid >> 3, kc = cid & 7;
;         if (AT && kn < 8) {
;           const int kr = cid >> 5, tc = cid & 31;
;           rr[i] = *(const u32x4*)(RT + (size_t)(kn * 64 + kr) * ldrt + tc * 8);
;         } else {
;           rr[i] = *(const u32x4*)(R + (size_t)row * ldr + kn * 64 + kc * 8);
;         }
;         cr[i] = *(const u32x4*)(Cm + (size_t)row * ldc + kn * 64 + kc * 8);
;       }
;     }
;     __builtin_amdgcn_sched_barrier(0x38F);
;     if (kt >= 0) {
;       const u16* Rs = S0 + (kt & 1) * STG;
;       const u16* Cs = Rs + 256 * 72;
;       const u16* RTs = Rs;
; #pragma unroll
;       for (int ks = 0; ks < 4; ++ks) {
;         bf16x8 rf[2];
; #pragma unroll
;         for (int rb = 0; rb < 2; ++rb) {
;           if (AT && kt < 8) {
;             const u16* src = RTs + (16 * ks + 8 * g) * 264 + 64 * wr + 32 * rb + li;
;             bf16x8 t;
; #pragma unroll
;             for (int j = 0; j < 8; ++j) t[j] = (short)src[j * 264];
;             rf[rb] = t;
;           } else {
;             rf[rb] = *(const bf16x8*)(Rs + (64 * wr + 32 * rb + li) * 72 + 16 * ks + 8 * g);
;           }
;         }
; #pragma unroll
;         for (int cb = 0; cb < 4; ++cb) {
;           const bf16x8 cfv = *(const bf16x8*)(Cs + (128 * wc + 32 * cb + li) * 72 + 16 * ks + 8 * g);
; #pragma unroll
;           for (int rb = 0; rb < 2; ++rb) acc[rb][cb] = MFMA(rf[rb], cfv, acc[rb][cb]);
	v_mfma_f32_32x32x16_bf16 v[64:79], v[192:195], v[244:247], v[64:79]
	v_mfma_f32_32x32x16_bf16 v[0:15], v[220:223], v[244:247], v[0:15]
	ds_read_b128 v[244:247], v190 offset:50784
	v_subrev_u32_e32 v249, 0x12000, v249
	global_load_dwordx4 v[148:151], v[164:165], off
	v_lshl_add_u64 v[164:165], v[164:165], 0, s[58:59]
	v_add_u32_e32 v187, 0x12000, v187
	v_add_u32_e32 v190, 0x12000, v190
	s_waitcnt lgkmcnt(3)
	v_mfma_f32_32x32x16_bf16 v[112:127], v[224:227], v[232:235], v[112:127]
	v_mfma_f32_32x32x16_bf16 v[48:63], v[228:231], v[232:235], v[48:63]
	global_load_dwordx4 v[132:135], v[170:171], off
	v_lshl_add_u64 v[170:171], v[170:171], 0, s[58:59]
	s_waitcnt lgkmcnt(2)
	v_mfma_f32_32x32x16_bf16 v[96:111], v[224:227], v[236:239], v[96:111]
	v_mfma_f32_32x32x16_bf16 v[32:47], v[228:231], v[236:239], v[32:47]
	global_load_dwordx4 v[140:143], v[162:163], off
	v_lshl_add_u64 v[162:163], v[162:163], 0, s[58:59]
	s_waitcnt lgkmcnt(1)
	v_mfma_f32_32x32x16_bf16 v[80:95], v[224:227], v[240:243], v[80:95]
	v_mfma_f32_32x32x16_bf16 v[16:31], v[228:231], v[240:243], v[16:31]
	global_load_dwordx4 v[128:131], v[168:169], off
	v_lshl_add_u64 v[168:169], v[168:169], 0, s[58:59]
	s_waitcnt lgkmcnt(0)
	v_mfma_f32_32x32x16_bf16 v[64:79], v[224:227], v[244:247], v[64:79]
	v_mfma_f32_32x32x16_bf16 v[0:15], v[228:231], v[244:247], v[0:15]
	global_load_dwordx4 v[156:159], v[160:161], off
	v_lshl_add_u64 v[160:161], v[160:161], 0, s[58:59]
	s_waitcnt lgkmcnt(0)
	s_barrier
	ds_read_b128 v[192:195], v187 offset:0
	ds_read_b128 v[220:223], v187 offset:4608
	ds_read_b128 v[232:235], v190 offset:36864
	ds_read_b128 v[236:239], v190 offset:41472
	ds_read_b128 v[240:243], v190 offset:46080
	ds_read_b128 v[244:247], v190 offset:50688
	ds_read_b128 v[224:227], v187 offset:32
	ds_read_b128 v[228:231], v187 offset:4640
	s_waitcnt lgkmcnt(5)
	v_mfma_f32_32x32x16_bf16 v[112:127], v[192:195], v[232:235], v[112:127]
	v_mfma_f32_32x32x16_bf16 v[48:63], v[220:223], v[232:235], v[48:63]
	ds_read_b128 v[232:235], v190 offset:36896
	s_waitcnt vmcnt(0)
	ds_write_b128 v191, v[144:147]
	s_waitcnt lgkmcnt(6)
	v_mfma_f32_32x32x16_bf16 v[96:111], v[192:195], v[236:239], v[96:111]
	v_mfma_f32_32x32x16_bf16 v[32:47], v[220:223], v[236:239], v[32:47]
	ds_read_b128 v[236:239], v190 offset:41504
	ds_write_b128 v191, v[152:155] offset:36864
	s_waitcnt lgkmcnt(7)
	v_mfma_f32_32x32x16_bf16 v[80:95], v[192:195], v[240:243], v[80:95]
	v_mfma_f32_32x32x16_bf16 v[16:31], v[220:223], v[240:243], v[16:31]
	ds_read_b128 v[240:243], v190 offset:46112
	ds_write_b128 v196, v[136:139]
	s_waitcnt lgkmcnt(8)
	v_mfma_f32_32x32x16_bf16 v[64:79], v[192:195], v[244:247], v[64:79]
	v_mfma_f32_32x32x16_bf16 v[0:15], v[220:223], v[244:247], v[0:15]
	ds_read_b128 v[244:247], v190 offset:50720
	ds_write_b128 v196, v[148:151] offset:36864
	ds_read_b128 v[192:195], v187 offset:64
	ds_read_b128 v[220:223], v187 offset:4672
	s_waitcnt lgkmcnt(9)
	v_mfma_f32_32x32x16_bf16 v[112:127], v[224:227], v[232:235], v[112:127]
	v_mfma_f32_32x32x16_bf16 v[48:63], v[228:231], v[232:235], v[48:63]
	ds_read_b128 v[232:235], v190 offset:36928
	ds_write_b128 v197, v[132:135]
	s_waitcnt lgkmcnt(9)
	v_mfma_f32_32x32x16_bf16 v[96:111], v[224:227], v[236:239], v[96:111]
	v_mfma_f32_32x32x16_bf16 v[32:47], v[228:231], v[236:239], v[32:47]
	ds_read_b128 v[236:239], v190 offset:41536
	ds_write_b128 v197, v[140:143] offset:36864
	s_waitcnt lgkmcnt(9)
	v_mfma_f32_32x32x16_bf16 v[80:95], v[224:227], v[240:243], v[80:95]
	v_mfma_f32_32x32x16_bf16 v[16:31], v[228:231], v[240:243], v[16:31]
	ds_read_b128 v[240:243], v190 offset:46144
	ds_write_b128 v249, v[128:131]
	s_waitcnt lgkmcnt(9)
	v_mfma_f32_32x32x16_bf16 v[64:79], v[224:227], v[244:247], v[64:79]
	v_mfma_f32_32x32x16_bf16 v[0:15], v[228:231], v[244:247], v[0:15]
	ds_read_b128 v[244:247], v190 offset:50752
	ds_write_b128 v249, v[156:159] offset:36864
	ds_read_b128 v[224:227], v187 offset:96
	ds_read_b128 v[228:231], v187 offset:4704
	s_waitcnt lgkmcnt(9)
	v_mfma_f32_32x32x16_bf16 v[112:127], v[192:195], v[232:235], v[112:127]
	v_mfma_f32_32x32x16_bf16 v[48:63], v[220:223], v[232:235], v[48:63]
	ds_read_b128 v[232:235], v190 offset:36960
	v_add_u32_e32 v191, 0x12000, v191
	global_load_dwordx4 v[144:147], v[174:175], off
	v_lshl_add_u64 v[174:175], v[174:175], 0, s[58:59]
	s_waitcnt lgkmcnt(8)
	v_mfma_f32_32x32x16_bf16 v[96:111], v[192:195], v[236:239], v[96:111]
	v_mfma_f32_32x32x16_bf16 v[32:47], v[220:223], v[236:239], v[32:47]
	ds_read_b128 v[236:239], v190 offset:41568
	v_add_u32_e32 v196, 0x12000, v196
	global_load_dwordx4 v[152:155], v[166:167], off
	v_lshl_add_u64 v[166:167], v[166:167], 0, s[58:59]
	s_waitcnt lgkmcnt(7)
	v_mfma_f32_32x32x16_bf16 v[80:95], v[192:195], v[240:243], v[80:95]
	v_mfma_f32_32x32x16_bf16 v[16:31], v[220:223], v[240:243], v[16:31]
	ds_read_b128 v[240:243], v190 offset:46176
	v_add_u32_e32 v197, 0x12000, v197
	global_load_dwordx4 v[136:139], v[172:173], off
	v_lshl_add_u64 v[172:173], v[172:173], 0, s[58:59]
	s_waitcnt lgkmcnt(6)
	v_mfma_f32_32x32x16_bf16 v[64:79], v[192:195], v[244:247], v[64:79]
	v_mfma_f32_32x32x16_bf16 v[0:15], v[220:223], v[244:247], v[0:15]
	ds_read_b128 v[244:247], v190 offset:50784
	v_add_u32_e32 v249, 0x12000, v249
	global_load_dwordx4 v[148:151], v[164:165], off
	v_lshl_add_u64 v[164:165], v[164:165], 0, s[58:59]
	v_subrev_u32_e32 v187, 0x12000, v187
	v_subrev_u32_e32 v190, 0x12000, v190
	s_waitcnt lgkmcnt(3)
	v_mfma_f32_32x32x16_bf16 v[112:127], v[224:227], v[232:235], v[112:127]
	v_mfma_f32_32x32x16_bf16 v[48:63], v[228:231], v[232:235], v[48:63]
	global_load_dwordx4 v[132:135], v[170:171], off
	v_lshl_add_u64 v[170:171], v[170:171], 0, s[58:59]
	s_waitcnt lgkmcnt(2)
	v_mfma_f32_32x32x16_bf16 v[96:111], v[224:227], v[236:239], v[96:111]
	v_mfma_f32_32x32x16_bf16 v[32:47], v[228:231], v[236:239], v[32:47]
	global_load_dwordx4 v[140:143], v[162:163], off
	v_lshl_add_u64 v[162:163], v[162:163], 0, s[58:59]
	s_waitcnt lgkmcnt(1)
	v_mfma_f32_32x32x16_bf16 v[80:95], v[224:227], v[240:243], v[80:95]
	v_mfma_f32_32x32x16_bf16 v[16:31], v[228:231], v[240:243], v[16:31]
	global_load_dwordx4 v[128:131], v[168:169], off
	v_lshl_add_u64 v[168:169], v[168:169], 0, s[58:59]
	s_waitcnt lgkmcnt(0)
	v_mfma_f32_32x32x16_bf16 v[64:79], v[224:227], v[244:247], v[64:79]
	v_mfma_f32_32x32x16_bf16 v[0:15], v[228:231], v[244:247], v[0:15]
	global_load_dwordx4 v[156:159], v[160:161], off
	v_lshl_add_u64 v[160:161], v[160:161], 0, s[58:59]
	s_waitcnt lgkmcnt(0)
	s_barrier
; template <bool AT>
; DI void gemm_main(f32x16 (&acc)[2][4], const u16* __restrict__ R, int ldr, const u16* __restrict__ Cm, int ldc,
;                   const u16* __restrict__ RT, int ldrt, int K, char* smem, int tid) {
;     ...
;   for (int kt = -1; kt < nk; ++kt) {
;     if (kt + 1 < nk) {
;       const int ks1 = kt + 1;
;       u16* Rs = S0 + (ks1 & 1) * STG;
;       u16* Cs = Rs + 256 * 72;
; #pragma unroll
;       for (int i = 0; i < 4; ++i) {
;         const int cid = tid + NT * i;
;         const int row = cid >> 3, kc = cid & 7;
;         if (AT && ks1 < 8) {
;           const int kr = cid >> 5, tc = cid & 31;
;           *(u32x4*)(Rs + kr * 264 + tc * 8) = rr[i];
;         } else {
;           *(u32x4*)(Rs + row * 72 + kc * 8) = rr[i];
;         }
;         *(u32x4*)(Cs + row * 72 + kc * 8) = cr[i];
;       }
;     }
;     if (kt + 2 < nk) {
;       const int kn = kt + 2;
; #pragma unroll
;       for (int i = 0; i < 4; ++i) {
;         const int cid = tid + NT * i;
;         const int row = cid >> 3, kc = cid & 7;
;         if (AT && kn < 8) {
;           const int kr = cid >> 5, tc = cid & 31;
;           rr[i] = *(const u32x4*)(RT + (size_t)(kn * 64 + kr) * ldrt + tc * 8);
;         } else {
;           rr[i] = *(const u32x4*)(R + (size_t)row * ldr + kn * 64 + kc * 8);
;         }
;         cr[i] = *(const u32x4*)(Cm + (size_t)row * ldc + kn * 64 + kc * 8);
;       }
;     }
;     __builtin_amdgcn_sched_barrier(0x38F);
;     if (kt >= 0) {
;       const u16* Rs = S0 + (kt & 1) * STG;
;       const u16* Cs = Rs + 256 * 72;
;       const u16* RTs = Rs;
; #pragma unroll
;       for (int ks = 0; ks < 4; ++ks) {
;         bf16x8 rf[2];
; #pragma unroll
;         for (int rb = 0; rb < 2; ++rb) {
;           if (AT && kt < 8) {
;             const u16* src = RTs + (16 * ks + 8 * g) * 264 + 64 * wr + 32 * rb + li;
;             bf16x8 t;
; #pragma unroll
;             for (int j = 0; j < 8; ++j) t[j] = (short)src[j * 264];
;             rf[rb] = t;
;           } else {
;             rf[rb] = *(const bf16x8*)(Rs + (64 * wr + 32 * rb + li) * 72 + 16 * ks + 8 * g);
;           }
;         }
; #pragma unroll
;         for (int cb = 0; cb < 4; ++cb) {
;           const bf16x8 cfv = *(const bf16x8*)(Cs + (128 * wc + 32 * cb + li) * 72 + 16 * ks + 8 * g);
; #pragma unroll
;           for (int rb = 0; rb < 2; ++rb) acc[rb][cb] = MFMA(rf[rb], cfv, acc[rb][cb]);
	s_add_i32 s78, s78, -1
	s_cmp_lg_u32 s78, 0
	s_cbranch_scc1 .Lgt_loop
	s_add_i32 s8, 0, 0x12000
	v_add_u32_e32 v160, s8, v188
	v_lshlrev_b32_e32 v162, 1, v185
	v_add_u32_e32 v161, s90, v188
	v_add_u32_e32 v163, v160, v162
	s_waitcnt vmcnt(7)
	ds_write_b128 v163, v[144:147]
	v_add_u32_e32 v144, v161, v162
	s_waitcnt vmcnt(6)
	ds_write_b128 v144, v[152:155]
	v_lshlrev_b32_e32 v144, 1, v184
	v_add_u32_e32 v145, v160, v144
	s_waitcnt vmcnt(5)
	ds_write_b128 v145, v[136:139]
	v_add_u32_e32 v136, v161, v144
	s_waitcnt vmcnt(4)
	ds_write_b128 v136, v[148:151]
	v_lshlrev_b32_e32 v136, 1, v183
	v_add_u32_e32 v137, v160, v136
	s_waitcnt vmcnt(3)
	ds_write_b128 v137, v[132:135]
	v_add_u32_e32 v132, v161, v136
	s_waitcnt vmcnt(2)
	ds_write_b128 v132, v[140:143]
	v_lshlrev_b32_e32 v132, 1, v182
	v_add_u32_e32 v133, v160, v132
	s_waitcnt vmcnt(1)
	ds_write_b128 v133, v[128:131]
	v_add_u32_e32 v128, v161, v132
	s_waitcnt vmcnt(0)
	ds_write_b128 v128, v[156:159]
	v_add_u32_e32 v140, v181, v180
	ds_read_b128 v[128:131], v140
	ds_read_b128 v[136:139], v140 offset:4608
	v_add_u32_e32 v141, v181, v179
	ds_read_b128 v[132:135], v141 offset:36864
	s_waitcnt lgkmcnt(0)
	v_mfma_f32_32x32x16_bf16 v[112:127], v[128:131], v[132:135], v[112:127]
	v_bfe_u32 v145, v176, 6, 1
	s_cmp_lt_u32 s11, 12
	v_mfma_f32_32x32x16_bf16 v[48:63], v[136:139], v[132:135], v[48:63]
	ds_read_b128 v[132:135], v141 offset:41472
	s_waitcnt lgkmcnt(0)
	v_mfma_f32_32x32x16_bf16 v[96:111], v[128:131], v[132:135], v[96:111]
	v_mfma_f32_32x32x16_bf16 v[32:47], v[136:139], v[132:135], v[32:47]
	ds_read_b128 v[132:135], v141 offset:46080
	s_waitcnt lgkmcnt(0)
	v_mfma_f32_32x32x16_bf16 v[80:95], v[128:131], v[132:135], v[80:95]
	v_mfma_f32_32x32x16_bf16 v[16:31], v[136:139], v[132:135], v[16:31]
	ds_read_b128 v[132:135], v141 offset:50688
	s_waitcnt lgkmcnt(0)
	v_mfma_f32_32x32x16_bf16 v[64:79], v[128:131], v[132:135], v[64:79]
	v_mfma_f32_32x32x16_bf16 v[0:15], v[136:139], v[132:135], v[0:15]
	ds_read_b128 v[128:131], v140 offset:32
	ds_read_b128 v[132:135], v141 offset:36896
	ds_read_b128 v[136:139], v140 offset:4640
	s_waitcnt lgkmcnt(1)
	v_mfma_f32_32x32x16_bf16 v[112:127], v[128:131], v[132:135], v[112:127]
	s_waitcnt lgkmcnt(0)
	v_mfma_f32_32x32x16_bf16 v[48:63], v[136:139], v[132:135], v[48:63]
	ds_read_b128 v[132:135], v141 offset:41504
	s_waitcnt lgkmcnt(0)
	v_mfma_f32_32x32x16_bf16 v[96:111], v[128:131], v[132:135], v[96:111]
	v_mfma_f32_32x32x16_bf16 v[32:47], v[136:139], v[132:135], v[32:47]
	ds_read_b128 v[132:135], v141 offset:46112
	s_waitcnt lgkmcnt(0)
	v_mfma_f32_32x32x16_bf16 v[80:95], v[128:131], v[132:135], v[80:95]
	v_mfma_f32_32x32x16_bf16 v[16:31], v[136:139], v[132:135], v[16:31]
	ds_read_b128 v[132:135], v141 offset:50720
	s_waitcnt lgkmcnt(0)
	v_mfma_f32_32x32x16_bf16 v[64:79], v[128:131], v[132:135], v[64:79]
	v_mfma_f32_32x32x16_bf16 v[0:15], v[136:139], v[132:135], v[0:15]
	ds_read_b128 v[128:131], v140 offset:64
	ds_read_b128 v[132:135], v141 offset:36928
	ds_read_b128 v[136:139], v140 offset:4672
	s_waitcnt lgkmcnt(1)
	v_mfma_f32_32x32x16_bf16 v[112:127], v[128:131], v[132:135], v[112:127]
	s_waitcnt lgkmcnt(0)
	v_mfma_f32_32x32x16_bf16 v[48:63], v[136:139], v[132:135], v[48:63]
	ds_read_b128 v[132:135], v141 offset:41536
	s_waitcnt lgkmcnt(0)
	v_mfma_f32_32x32x16_bf16 v[96:111], v[128:131], v[132:135], v[96:111]
	v_mfma_f32_32x32x16_bf16 v[32:47], v[136:139], v[132:135], v[32:47]
	ds_read_b128 v[132:135], v141 offset:46144
	s_waitcnt lgkmcnt(0)
	v_mfma_f32_32x32x16_bf16 v[80:95], v[128:131], v[132:135], v[80:95]
	v_mfma_f32_32x32x16_bf16 v[16:31], v[136:139], v[132:135], v[16:31]
	ds_read_b128 v[132:135], v141 offset:50752
	s_waitcnt lgkmcnt(0)
	v_mfma_f32_32x32x16_bf16 v[64:79], v[128:131], v[132:135], v[64:79]
	v_mfma_f32_32x32x16_bf16 v[0:15], v[136:139], v[132:135], v[0:15]
	ds_read_b128 v[128:131], v140 offset:96
	ds_read_b128 v[132:135], v141 offset:36960
	ds_read_b128 v[136:139], v140 offset:4704
	v_add3_u32 v140, s8, v178, v180
	s_mov_b64 s[8:9], -1
	s_waitcnt lgkmcnt(1)
	v_mfma_f32_32x32x16_bf16 v[112:127], v[128:131], v[132:135], v[112:127]
	s_waitcnt lgkmcnt(0)
	v_mfma_f32_32x32x16_bf16 v[48:63], v[136:139], v[132:135], v[48:63]
	ds_read_b128 v[132:135], v141 offset:41568
	s_waitcnt lgkmcnt(0)
	v_mfma_f32_32x32x16_bf16 v[96:111], v[128:131], v[132:135], v[96:111]
	v_mfma_f32_32x32x16_bf16 v[32:47], v[136:139], v[132:135], v[32:47]
	ds_read_b128 v[132:135], v141 offset:46176
	s_waitcnt lgkmcnt(0)
	v_mfma_f32_32x32x16_bf16 v[80:95], v[128:131], v[132:135], v[80:95]
	v_mfma_f32_32x32x16_bf16 v[16:31], v[136:139], v[132:135], v[16:31]
	ds_read_b128 v[132:135], v141 offset:50784
	s_waitcnt lgkmcnt(0)
	s_barrier
; #define MFMA(a, b, c) __builtin_amdgcn_mfma_f32_32x32x16_bf16((a), (b), (c), 0, 0, 0)
; DI u16 f2bf(float a) { return (u16)(pack2(a, 0.f) & 0xffffu); }
; DI int crow(int reg, int g) { return (reg & 3) + 8 * (reg >> 2) + 4 * g; }
; DI float siluf(float x) { return x * __builtin_amdgcn_rcpf(1.f + __expf(-x)); }
; template <bool AT>
; DI void gemm_main(f32x16 (&acc)[2][4], const u16* __restrict__ R, int ldr, const u16* __restrict__ Cm, int ldc,
;                   const u16* __restrict__ RT, int ldrt, int K, char* smem, int tid) {
;     ...
;     if (kt >= 0) {
;       const u16* Rs = S0 + (kt & 1) * STG;
;       const u16* Cs = Rs + 256 * 72;
;       const u16* RTs = Rs;
; #pragma unroll
;       for (int ks = 0; ks < 4; ++ks) {
;         bf16x8 rf[2];
; #pragma unroll
;         for (int rb = 0; rb < 2; ++rb) {
;           if (AT && kt < 8) {
;             const u16* src = RTs + (16 * ks + 8 * g) * 264 + 64 * wr + 32 * rb + li;
;             bf16x8 t;
; #pragma unroll
;             for (int j = 0; j < 8; ++j) t[j] = (short)src[j * 264];
;             rf[rb] = t;
;           } else {
;             rf[rb] = *(const bf16x8*)(Rs + (64 * wr + 32 * rb + li) * 72 + 16 * ks + 8 * g);
;           }
;         }
; #pragma unroll
;         for (int cb = 0; cb < 4; ++cb) {
;           const bf16x8 cfv = *(const bf16x8*)(Cs + (128 * wc + 32 * cb + li) * 72 + 16 * ks + 8 * g);
; #pragma unroll
;           for (int rb = 0; rb < 2; ++rb) acc[rb][cb] = MFMA(rf[rb], cfv, acc[rb][cb]);
;         }
;       }
;     }
;     __syncthreads();
; template <bool TR>
; DI void gemm_in_tile(const P& p, int l, int id, char* smem) {
;     ...
;   } else {
; #pragma unroll
;     for (int rb = 0; rb < 2; ++rb) {
; #pragma unroll
;       for (int reg = 0; reg < 16; ++reg) {
;         if ((reg & 7) == 0) asm volatile("" ::: "memory");
;         const int rl = 64 * wr + 32 * rb + crow(reg, g);
;         const int tok = m0 + rl;
;         const float rs = rs_s[rl];
; #pragma unroll
;         for (int cb = 0; cb < 4; ++cb) {
;           const int col = n0 - 3584 + 128 * wc + 32 * cb + li;
;           p.AG[(size_t)tok * 512 + col] = f2bf(siluf(acc[rb][cb][reg] * rs));
	v_add3_u32 v141, s90, v178, v179
	v_mfma_f32_32x32x16_bf16 v[64:79], v[128:131], v[132:135], v[64:79]
	ds_read_b128 v[128:131], v140
	v_mfma_f32_32x32x16_bf16 v[0:15], v[136:139], v[132:135], v[0:15]
	ds_read_b128 v[136:139], v140 offset:4608
	ds_read_b128 v[132:135], v141
	s_waitcnt lgkmcnt(0)
	v_mfma_f32_32x32x16_bf16 v[112:127], v[128:131], v[132:135], v[112:127]
	v_mfma_f32_32x32x16_bf16 v[48:63], v[136:139], v[132:135], v[48:63]
	ds_read_b128 v[132:135], v141 offset:4608
	s_waitcnt lgkmcnt(0)
	v_mfma_f32_32x32x16_bf16 v[96:111], v[128:131], v[132:135], v[96:111]
	v_mfma_f32_32x32x16_bf16 v[32:47], v[136:139], v[132:135], v[32:47]
	ds_read_b128 v[132:135], v141 offset:9216
	s_waitcnt lgkmcnt(0)
	v_mfma_f32_32x32x16_bf16 v[80:95], v[128:131], v[132:135], v[80:95]
	v_mfma_f32_32x32x16_bf16 v[16:31], v[136:139], v[132:135], v[16:31]
	ds_read_b128 v[132:135], v141 offset:13824
	s_waitcnt lgkmcnt(0)
	v_mfma_f32_32x32x16_bf16 v[64:79], v[128:131], v[132:135], v[64:79]
	v_mfma_f32_32x32x16_bf16 v[0:15], v[136:139], v[132:135], v[0:15]
	ds_read_b128 v[128:131], v140 offset:32
	ds_read_b128 v[132:135], v141 offset:32
	ds_read_b128 v[136:139], v140 offset:4640
	s_waitcnt lgkmcnt(1)
	v_mfma_f32_32x32x16_bf16 v[112:127], v[128:131], v[132:135], v[112:127]
	s_waitcnt lgkmcnt(0)
	v_mfma_f32_32x32x16_bf16 v[48:63], v[136:139], v[132:135], v[48:63]
	ds_read_b128 v[132:135], v141 offset:4640
	s_waitcnt lgkmcnt(0)
	v_mfma_f32_32x32x16_bf16 v[96:111], v[128:131], v[132:135], v[96:111]
	v_mfma_f32_32x32x16_bf16 v[32:47], v[136:139], v[132:135], v[32:47]
	ds_read_b128 v[132:135], v141 offset:9248
	s_waitcnt lgkmcnt(0)
	v_mfma_f32_32x32x16_bf16 v[80:95], v[128:131], v[132:135], v[80:95]
	v_mfma_f32_32x32x16_bf16 v[16:31], v[136:139], v[132:135], v[16:31]
	ds_read_b128 v[132:135], v141 offset:13856
	s_waitcnt lgkmcnt(0)
	v_mfma_f32_32x32x16_bf16 v[64:79], v[128:131], v[132:135], v[64:79]
	v_mfma_f32_32x32x16_bf16 v[0:15], v[136:139], v[132:135], v[0:15]
	ds_read_b128 v[128:131], v140 offset:64
	ds_read_b128 v[132:135], v141 offset:64
	ds_read_b128 v[136:139], v140 offset:4672
	s_waitcnt lgkmcnt(1)
	v_mfma_f32_32x32x16_bf16 v[112:127], v[128:131], v[132:135], v[112:127]
	s_waitcnt lgkmcnt(0)
	v_mfma_f32_32x32x16_bf16 v[48:63], v[136:139], v[132:135], v[48:63]
	ds_read_b128 v[132:135], v141 offset:4672
	s_waitcnt lgkmcnt(0)
	v_mfma_f32_32x32x16_bf16 v[96:111], v[128:131], v[132:135], v[96:111]
	v_mfma_f32_32x32x16_bf16 v[32:47], v[136:139], v[132:135], v[32:47]
	ds_read_b128 v[132:135], v141 offset:9280
	s_waitcnt lgkmcnt(0)
	v_mfma_f32_32x32x16_bf16 v[80:95], v[128:131], v[132:135], v[80:95]
	v_mfma_f32_32x32x16_bf16 v[16:31], v[136:139], v[132:135], v[16:31]
	ds_read_b128 v[132:135], v141 offset:13888
	s_waitcnt lgkmcnt(0)
	v_mfma_f32_32x32x16_bf16 v[64:79], v[128:131], v[132:135], v[64:79]
	v_mfma_f32_32x32x16_bf16 v[0:15], v[136:139], v[132:135], v[0:15]
	ds_read_b128 v[128:131], v140 offset:96
	ds_read_b128 v[132:135], v141 offset:96
	ds_read_b128 v[136:139], v140 offset:4704
	v_ashrrev_i32_e32 v140, 7, v176
	s_waitcnt lgkmcnt(1)
	v_mfma_f32_32x32x16_bf16 v[112:127], v[128:131], v[132:135], v[112:127]
	s_waitcnt lgkmcnt(0)
	v_mfma_f32_32x32x16_bf16 v[48:63], v[136:139], v[132:135], v[48:63]
	ds_read_b128 v[132:135], v141 offset:4704
	s_waitcnt lgkmcnt(0)
	v_mfma_f32_32x32x16_bf16 v[96:111], v[128:131], v[132:135], v[96:111]
	v_mfma_f32_32x32x16_bf16 v[32:47], v[136:139], v[132:135], v[32:47]
	ds_read_b128 v[132:135], v141 offset:9312
	s_waitcnt lgkmcnt(0)
	v_mfma_f32_32x32x16_bf16 v[80:95], v[128:131], v[132:135], v[80:95]
	v_mfma_f32_32x32x16_bf16 v[16:31], v[136:139], v[132:135], v[16:31]
	ds_read_b128 v[132:135], v141 offset:13920
	v_bfe_u32 v141, v176, 5, 1
	s_waitcnt lgkmcnt(0)
	s_barrier
	v_mfma_f32_32x32x16_bf16 v[64:79], v[128:131], v[132:135], v[64:79]
	v_lshlrev_b32_e32 v128, 6, v140
	v_lshl_or_b32 v144, v141, 2, v128
	v_mfma_f32_32x32x16_bf16 v[0:15], v[136:139], v[132:135], v[0:15]
	s_cbranch_scc1 .LBB0_332
	s_add_i32 s8, s56, 0xfffff200
	v_lshlrev_b32_e32 v128, 7, v145
	v_or3_b32 v132, v128, s8, v177
	s_add_i32 s8, 0, 0x24000
	v_lshl_add_u32 v128, v144, 2, s8
	ds_read_b128 v[128:131], v128
	v_add_u32_e32 v140, s76, v144
	v_ashrrev_i32_e32 v141, 31, v140
	v_lshlrev_b64 v[134:135], 10, v[140:141]
	v_lshl_add_u64 v[142:143], s[30:31], 0, v[134:135]
	s_waitcnt lgkmcnt(0)
; DI u16 f2bf(float a) { return (u16)(pack2(a, 0.f) & 0xffffu); }
; DI int crow(int reg, int g) { return (reg & 3) + 8 * (reg >> 2) + 4 * g; }
; DI float siluf(float x) { return x * __builtin_amdgcn_rcpf(1.f + __expf(-x)); }
; template <bool TR>
; DI void gemm_in_tile(const P& p, int l, int id, char* smem) {
;     ...
; #pragma unroll
;     for (int rb = 0; rb < 2; ++rb) {
; #pragma unroll
;       for (int reg = 0; reg < 16; ++reg) {
;         if ((reg & 7) == 0) asm volatile("" ::: "memory");
;         const int rl = 64 * wr + 32 * rb + crow(reg, g);
;         const int tok = m0 + rl;
;         const float rs = rs_s[rl];
; #pragma unroll
;         for (int cb = 0; cb < 4; ++cb) {
;           const int col = n0 - 3584 + 128 * wc + 32 * cb + li;
;           p.AG[(size_t)tok * 512 + col] = f2bf(siluf(acc[rb][cb][reg] * rs));
;         }
;       }
;     }
	v_mul_f32_e32 v133, v112, v128
	v_mul_f32_e32 v134, 0xbfb8aa3b, v133
	v_exp_f32_e32 v134, v134
	s_nop 0
	v_add_f32_e32 v134, 1.0, v134
	v_rcp_f32_e32 v134, v134
	s_nop 0
	v_mul_f32_e32 v133, v133, v134
	v_cvt_pk_bf16_f32 v136, v133, s0
	v_ashrrev_i32_e32 v133, 31, v132
	v_lshlrev_b64 v[138:139], 1, v[132:133]
	v_lshl_add_u64 v[134:135], v[142:143], 0, v[138:139]
	v_mul_f32_e32 v133, v96, v128
	global_store_short v[134:135], v136, off
	v_mul_f32_e32 v135, 0xbfb8aa3b, v133
	v_exp_f32_e32 v135, v135
	v_or_b32_e32 v134, 32, v132
	v_add_f32_e32 v135, 1.0, v135
	v_rcp_f32_e32 v135, v135
	s_nop 0
	v_mul_f32_e32 v133, v133, v135
	v_ashrrev_i32_e32 v135, 31, v134
	v_lshlrev_b64 v[136:137], 1, v[134:135]
	v_cvt_pk_bf16_f32 v133, v133, s0
	v_lshl_add_u64 v[134:135], v[142:143], 0, v[136:137]
	global_store_short v[134:135], v133, off
	v_mul_f32_e32 v133, v80, v128
	v_mul_f32_e32 v135, 0xbfb8aa3b, v133
	v_exp_f32_e32 v135, v135
	v_or_b32_e32 v134, 64, v132
	v_mul_f32_e32 v128, v64, v128
	v_or_b32_e32 v132, 0x60, v132
	v_add_f32_e32 v135, 1.0, v135
	v_rcp_f32_e32 v135, v135
	s_nop 0
	v_mul_f32_e32 v133, v133, v135
	v_ashrrev_i32_e32 v135, 31, v134
	v_lshlrev_b64 v[134:135], 1, v[134:135]
	v_cvt_pk_bf16_f32 v133, v133, s0
	v_lshl_add_u64 v[146:147], v[142:143], 0, v[134:135]
	global_store_short v[146:147], v133, off
	v_mul_f32_e32 v133, 0xbfb8aa3b, v128
	v_exp_f32_e32 v133, v133
	s_nop 0
	v_add_f32_e32 v133, 1.0, v133
	v_rcp_f32_e32 v133, v133
	s_nop 0
	v_mul_f32_e32 v128, v128, v133
	v_ashrrev_i32_e32 v133, 31, v132
	v_lshlrev_b64 v[132:133], 1, v[132:133]
	v_cvt_pk_bf16_f32 v128, v128, s0
	v_lshl_add_u64 v[142:143], v[142:143], 0, v[132:133]
	global_store_short v[142:143], v128, off
	v_mul_f32_e32 v128, v113, v129
	v_mul_f32_e32 v141, 0xbfb8aa3b, v128
	v_exp_f32_e32 v141, v141
	v_add_u32_e32 v142, 1, v140
	v_ashrrev_i32_e32 v143, 31, v142
	v_lshlrev_b64 v[142:143], 10, v[142:143]
	v_add_f32_e32 v141, 1.0, v141
	v_rcp_f32_e32 v141, v141
	v_lshl_add_u64 v[142:143], s[30:31], 0, v[142:143]
	v_lshl_add_u64 v[146:147], v[142:143], 0, v[138:139]
	v_mul_f32_e32 v128, v128, v141
	v_cvt_pk_bf16_f32 v128, v128, s0
	global_store_short v[146:147], v128, off
	v_mul_f32_e32 v128, v97, v129
	v_mul_f32_e32 v141, 0xbfb8aa3b, v128
	v_exp_f32_e32 v141, v141
	v_lshl_add_u64 v[146:147], v[142:143], 0, v[136:137]
	v_add_f32_e32 v141, 1.0, v141
	v_rcp_f32_e32 v141, v141
	s_nop 0
	v_mul_f32_e32 v128, v128, v141
	v_cvt_pk_bf16_f32 v128, v128, s0
	global_store_short v[146:147], v128, off
	v_mul_f32_e32 v128, v81, v129
	v_mul_f32_e32 v141, 0xbfb8aa3b, v128
	v_exp_f32_e32 v141, v141
	v_lshl_add_u64 v[146:147], v[142:143], 0, v[134:135]
	v_add_f32_e32 v141, 1.0, v141
	v_rcp_f32_e32 v141, v141
	s_nop 0
	v_mul_f32_e32 v128, v128, v141
	v_cvt_pk_bf16_f32 v128, v128, s0
	global_store_short v[146:147], v128, off
	v_mul_f32_e32 v128, v65, v129
	v_mul_f32_e32 v129, 0xbfb8aa3b, v128
	v_exp_f32_e32 v129, v129
	s_nop 0
	v_add_f32_e32 v129, 1.0, v129
	v_rcp_f32_e32 v129, v129
	s_nop 0
	v_mul_f32_e32 v128, v128, v129
	v_cvt_pk_bf16_f32 v141, v128, s0
	v_lshl_add_u64 v[128:129], v[142:143], 0, v[132:133]
	global_store_short v[128:129], v141, off
	v_mul_f32_e32 v141, v114, v130
	v_mul_f32_e32 v142, 0xbfb8aa3b, v141
	v_exp_f32_e32 v142, v142
	v_add_u32_e32 v128, 2, v140
	v_ashrrev_i32_e32 v129, 31, v128
	v_lshlrev_b64 v[128:129], 10, v[128:129]
	v_add_f32_e32 v142, 1.0, v142
	v_rcp_f32_e32 v142, v142
	v_lshl_add_u64 v[128:129], s[30:31], 0, v[128:129]
	v_mul_f32_e32 v141, v141, v142
	v_cvt_pk_bf16_f32 v141, v141, s0
	v_lshl_add_u64 v[142:143], v[128:129], 0, v[138:139]
	global_store_short v[142:143], v141, off
	v_mul_f32_e32 v141, v98, v130
	v_mul_f32_e32 v142, 0xbfb8aa3b, v141
	v_exp_f32_e32 v142, v142
	s_nop 0
	v_add_f32_e32 v142, 1.0, v142
	v_rcp_f32_e32 v142, v142
	s_nop 0
	v_mul_f32_e32 v141, v141, v142
	v_cvt_pk_bf16_f32 v141, v141, s0
	v_lshl_add_u64 v[142:143], v[128:129], 0, v[136:137]
	global_store_short v[142:143], v141, off
	v_mul_f32_e32 v141, v82, v130
	v_mul_f32_e32 v142, 0xbfb8aa3b, v141
	v_exp_f32_e32 v142, v142
	v_mul_f32_e32 v130, v66, v130
	v_add_f32_e32 v142, 1.0, v142
	v_rcp_f32_e32 v142, v142
	s_nop 0
	v_mul_f32_e32 v141, v141, v142
	v_cvt_pk_bf16_f32 v141, v141, s0
	v_lshl_add_u64 v[142:143], v[128:129], 0, v[134:135]
	global_store_short v[142:143], v141, off
	v_mul_f32_e32 v141, 0xbfb8aa3b, v130
	v_exp_f32_e32 v141, v141
	v_lshl_add_u64 v[128:129], v[128:129], 0, v[132:133]
	v_add_f32_e32 v141, 1.0, v141
	v_rcp_f32_e32 v141, v141
	s_nop 0
	v_mul_f32_e32 v130, v130, v141
	v_cvt_pk_bf16_f32 v130, v130, s0
	global_store_short v[128:129], v130, off
	v_mul_f32_e32 v130, v115, v131
	v_mul_f32_e32 v141, 0xbfb8aa3b, v130
	v_exp_f32_e32 v141, v141
	v_add_u32_e32 v128, 3, v140
	v_ashrrev_i32_e32 v129, 31, v128
	v_lshlrev_b64 v[128:129], 10, v[128:129]
	v_add_f32_e32 v141, 1.0, v141
	v_rcp_f32_e32 v141, v141
	v_lshl_add_u64 v[128:129], s[30:31], 0, v[128:129]
	v_lshl_add_u64 v[142:143], v[128:129], 0, v[138:139]
	v_mul_f32_e32 v130, v130, v141
	v_cvt_pk_bf16_f32 v130, v130, s0
	global_store_short v[142:143], v130, off
	v_mul_f32_e32 v130, v99, v131
	v_mul_f32_e32 v141, 0xbfb8aa3b, v130
	v_exp_f32_e32 v141, v141
	v_lshl_add_u64 v[142:143], v[128:129], 0, v[136:137]
	v_add_f32_e32 v141, 1.0, v141
	v_rcp_f32_e32 v141, v141
	s_nop 0
	v_mul_f32_e32 v130, v130, v141
	v_cvt_pk_bf16_f32 v130, v130, s0
	global_store_short v[142:143], v130, off
	v_mul_f32_e32 v130, v83, v131
	v_mul_f32_e32 v141, 0xbfb8aa3b, v130
	v_exp_f32_e32 v141, v141
	v_lshl_add_u64 v[142:143], v[128:129], 0, v[134:135]
	v_lshl_add_u64 v[128:129], v[128:129], 0, v[132:133]
	v_add_f32_e32 v141, 1.0, v141
	v_rcp_f32_e32 v141, v141
	s_nop 0
	v_mul_f32_e32 v130, v130, v141
	v_cvt_pk_bf16_f32 v130, v130, s0
	global_store_short v[142:143], v130, off
	v_mul_f32_e32 v130, v67, v131
	v_mul_f32_e32 v131, 0xbfb8aa3b, v130
	v_exp_f32_e32 v131, v131
	s_nop 0
	v_add_f32_e32 v131, 1.0, v131
	v_rcp_f32_e32 v131, v131
	s_nop 0
	v_mul_f32_e32 v130, v130, v131
	v_cvt_pk_bf16_f32 v130, v130, s0
	global_store_short v[128:129], v130, off
	v_or_b32_e32 v128, 8, v144
	v_add_u32_e32 v142, s76, v128
	v_lshl_add_u32 v128, v128, 2, s8
	ds_read_b128 v[128:131], v128
	v_ashrrev_i32_e32 v143, 31, v142
	v_lshlrev_b64 v[142:143], 10, v[142:143]
	v_lshl_add_u64 v[142:143], s[30:31], 0, v[142:143]
	s_waitcnt lgkmcnt(0)
; DI u16 f2bf(float a) { return (u16)(pack2(a, 0.f) & 0xffffu); }
; DI int crow(int reg, int g) { return (reg & 3) + 8 * (reg >> 2) + 4 * g; }
; DI float siluf(float x) { return x * __builtin_amdgcn_rcpf(1.f + __expf(-x)); }
; template <bool TR>
; DI void gemm_in_tile(const P& p, int l, int id, char* smem) {
;     ...
; #pragma unroll
;     for (int rb = 0; rb < 2; ++rb) {
; #pragma unroll
;       for (int reg = 0; reg < 16; ++reg) {
;         if ((reg & 7) == 0) asm volatile("" ::: "memory");
;         const int rl = 64 * wr + 32 * rb + crow(reg, g);
;         const int tok = m0 + rl;
;         const float rs = rs_s[rl];
; #pragma unroll
;         for (int cb = 0; cb < 4; ++cb) {
;           const int col = n0 - 3584 + 128 * wc + 32 * cb + li;
;           p.AG[(size_t)tok * 512 + col] = f2bf(siluf(acc[rb][cb][reg] * rs));
;         }
;       }
;     }
	v_mul_f32_e32 v141, v116, v128
	v_mul_f32_e32 v146, 0xbfb8aa3b, v141
	v_exp_f32_e32 v146, v146
	s_nop 0
	v_add_f32_e32 v146, 1.0, v146
	v_rcp_f32_e32 v146, v146
	s_nop 0
	v_mul_f32_e32 v141, v141, v146
	v_cvt_pk_bf16_f32 v141, v141, s0
	v_lshl_add_u64 v[146:147], v[142:143], 0, v[138:139]
	global_store_short v[146:147], v141, off
	v_mul_f32_e32 v141, v100, v128
	v_mul_f32_e32 v146, 0xbfb8aa3b, v141
	v_exp_f32_e32 v146, v146
	s_nop 0
	v_add_f32_e32 v146, 1.0, v146
	v_rcp_f32_e32 v146, v146
	s_nop 0
	v_mul_f32_e32 v141, v141, v146
	v_cvt_pk_bf16_f32 v141, v141, s0
	v_lshl_add_u64 v[146:147], v[142:143], 0, v[136:137]
	global_store_short v[146:147], v141, off
	v_mul_f32_e32 v141, v84, v128
	v_mul_f32_e32 v146, 0xbfb8aa3b, v141
	v_exp_f32_e32 v146, v146
	v_mul_f32_e32 v128, v68, v128
	v_add_f32_e32 v146, 1.0, v146
	v_rcp_f32_e32 v146, v146
	s_nop 0
	v_mul_f32_e32 v141, v141, v146
	v_cvt_pk_bf16_f32 v141, v141, s0
	v_lshl_add_u64 v[146:147], v[142:143], 0, v[134:135]
	global_store_short v[146:147], v141, off
	v_mul_f32_e32 v141, 0xbfb8aa3b, v128
	v_exp_f32_e32 v141, v141
	v_lshl_add_u64 v[142:143], v[142:143], 0, v[132:133]
	v_add_f32_e32 v141, 1.0, v141
	v_rcp_f32_e32 v141, v141
	s_nop 0
	v_mul_f32_e32 v128, v128, v141
	v_cvt_pk_bf16_f32 v128, v128, s0
	global_store_short v[142:143], v128, off
	v_mul_f32_e32 v128, v117, v129
	v_mul_f32_e32 v141, 0xbfb8aa3b, v128
	v_exp_f32_e32 v141, v141
	v_add_u32_e32 v142, 9, v140
	v_ashrrev_i32_e32 v143, 31, v142
	v_lshlrev_b64 v[142:143], 10, v[142:143]
	v_add_f32_e32 v141, 1.0, v141
	v_rcp_f32_e32 v141, v141
	v_lshl_add_u64 v[142:143], s[30:31], 0, v[142:143]
	v_lshl_add_u64 v[146:147], v[142:143], 0, v[138:139]
	v_mul_f32_e32 v128, v128, v141
	v_cvt_pk_bf16_f32 v128, v128, s0
	global_store_short v[146:147], v128, off
	v_mul_f32_e32 v128, v101, v129
	v_mul_f32_e32 v141, 0xbfb8aa3b, v128
	v_exp_f32_e32 v141, v141
	v_lshl_add_u64 v[146:147], v[142:143], 0, v[136:137]
	v_add_f32_e32 v141, 1.0, v141
	v_rcp_f32_e32 v141, v141
	s_nop 0
	v_mul_f32_e32 v128, v128, v141
	v_cvt_pk_bf16_f32 v128, v128, s0
	global_store_short v[146:147], v128, off
	v_mul_f32_e32 v128, v85, v129
	v_mul_f32_e32 v141, 0xbfb8aa3b, v128
	v_exp_f32_e32 v141, v141
	v_lshl_add_u64 v[146:147], v[142:143], 0, v[134:135]
	v_add_f32_e32 v141, 1.0, v141
	v_rcp_f32_e32 v141, v141
	s_nop 0
	v_mul_f32_e32 v128, v128, v141
	v_cvt_pk_bf16_f32 v128, v128, s0
	global_store_short v[146:147], v128, off
	v_mul_f32_e32 v128, v69, v129
	v_mul_f32_e32 v129, 0xbfb8aa3b, v128
	v_exp_f32_e32 v129, v129
	s_nop 0
	v_add_f32_e32 v129, 1.0, v129
	v_rcp_f32_e32 v129, v129
	s_nop 0
	v_mul_f32_e32 v128, v128, v129
	v_cvt_pk_bf16_f32 v141, v128, s0
	v_lshl_add_u64 v[128:129], v[142:143], 0, v[132:133]
	global_store_short v[128:129], v141, off
	v_mul_f32_e32 v141, v118, v130
	v_mul_f32_e32 v142, 0xbfb8aa3b, v141
	v_exp_f32_e32 v142, v142
	v_add_u32_e32 v128, 10, v140
	v_ashrrev_i32_e32 v129, 31, v128
	v_lshlrev_b64 v[128:129], 10, v[128:129]
	v_add_f32_e32 v142, 1.0, v142
	v_rcp_f32_e32 v142, v142
	v_lshl_add_u64 v[128:129], s[30:31], 0, v[128:129]
	v_mul_f32_e32 v141, v141, v142
	v_cvt_pk_bf16_f32 v141, v141, s0
	v_lshl_add_u64 v[142:143], v[128:129], 0, v[138:139]
	global_store_short v[142:143], v141, off
	v_mul_f32_e32 v141, v102, v130
	v_mul_f32_e32 v142, 0xbfb8aa3b, v141
	v_exp_f32_e32 v142, v142
	s_nop 0
	v_add_f32_e32 v142, 1.0, v142
	v_rcp_f32_e32 v142, v142
	s_nop 0
	v_mul_f32_e32 v141, v141, v142
	v_cvt_pk_bf16_f32 v141, v141, s0
	v_lshl_add_u64 v[142:143], v[128:129], 0, v[136:137]
	global_store_short v[142:143], v141, off
	v_mul_f32_e32 v141, v86, v130
	v_mul_f32_e32 v142, 0xbfb8aa3b, v141
	v_exp_f32_e32 v142, v142
	v_mul_f32_e32 v130, v70, v130
	v_add_f32_e32 v142, 1.0, v142
	v_rcp_f32_e32 v142, v142
	s_nop 0
	v_mul_f32_e32 v141, v141, v142
	v_cvt_pk_bf16_f32 v141, v141, s0
	v_lshl_add_u64 v[142:143], v[128:129], 0, v[134:135]
	global_store_short v[142:143], v141, off
	v_mul_f32_e32 v141, 0xbfb8aa3b, v130
	v_exp_f32_e32 v141, v141
	v_lshl_add_u64 v[128:129], v[128:129], 0, v[132:133]
	v_add_f32_e32 v141, 1.0, v141
	v_rcp_f32_e32 v141, v141
	s_nop 0
	v_mul_f32_e32 v130, v130, v141
	v_cvt_pk_bf16_f32 v130, v130, s0
	global_store_short v[128:129], v130, off
	v_mul_f32_e32 v130, v119, v131
	v_mul_f32_e32 v141, 0xbfb8aa3b, v130
	v_exp_f32_e32 v141, v141
	v_add_u32_e32 v128, 11, v140
	v_ashrrev_i32_e32 v129, 31, v128
	v_lshlrev_b64 v[128:129], 10, v[128:129]
	v_add_f32_e32 v141, 1.0, v141
	v_rcp_f32_e32 v141, v141
	v_lshl_add_u64 v[128:129], s[30:31], 0, v[128:129]
	v_lshl_add_u64 v[142:143], v[128:129], 0, v[138:139]
	v_mul_f32_e32 v130, v130, v141
	v_cvt_pk_bf16_f32 v130, v130, s0
	global_store_short v[142:143], v130, off
	v_mul_f32_e32 v130, v103, v131
	v_mul_f32_e32 v141, 0xbfb8aa3b, v130
	v_exp_f32_e32 v141, v141
	v_lshl_add_u64 v[142:143], v[128:129], 0, v[136:137]
	v_add_f32_e32 v141, 1.0, v141
	v_rcp_f32_e32 v141, v141
	s_nop 0
	v_mul_f32_e32 v130, v130, v141
	v_cvt_pk_bf16_f32 v130, v130, s0
	global_store_short v[142:143], v130, off
	v_mul_f32_e32 v130, v87, v131
	v_mul_f32_e32 v141, 0xbfb8aa3b, v130
	v_exp_f32_e32 v141, v141
	v_lshl_add_u64 v[142:143], v[128:129], 0, v[134:135]
	v_lshl_add_u64 v[128:129], v[128:129], 0, v[132:133]
	v_add_f32_e32 v141, 1.0, v141
	v_rcp_f32_e32 v141, v141
	s_nop 0
	v_mul_f32_e32 v130, v130, v141
	v_cvt_pk_bf16_f32 v130, v130, s0
	global_store_short v[142:143], v130, off
	v_mul_f32_e32 v130, v71, v131
	v_mul_f32_e32 v131, 0xbfb8aa3b, v130
	v_exp_f32_e32 v131, v131
	s_nop 0
	v_add_f32_e32 v131, 1.0, v131
	v_rcp_f32_e32 v131, v131
	s_nop 0
	v_mul_f32_e32 v130, v130, v131
	v_cvt_pk_bf16_f32 v130, v130, s0
	global_store_short v[128:129], v130, off
	v_or_b32_e32 v128, 16, v144
	v_add_u32_e32 v142, s76, v128
	v_lshl_add_u32 v128, v128, 2, s8
	ds_read_b128 v[128:131], v128
	v_ashrrev_i32_e32 v143, 31, v142
	v_lshlrev_b64 v[142:143], 10, v[142:143]
	v_lshl_add_u64 v[142:143], s[30:31], 0, v[142:143]
	s_waitcnt lgkmcnt(0)
; DI u16 f2bf(float a) { return (u16)(pack2(a, 0.f) & 0xffffu); }
; DI int crow(int reg, int g) { return (reg & 3) + 8 * (reg >> 2) + 4 * g; }
; DI float siluf(float x) { return x * __builtin_amdgcn_rcpf(1.f + __expf(-x)); }
; template <bool TR>
; DI void gemm_in_tile(const P& p, int l, int id, char* smem) {
;     ...
; #pragma unroll
;     for (int rb = 0; rb < 2; ++rb) {
; #pragma unroll
;       for (int reg = 0; reg < 16; ++reg) {
;         if ((reg & 7) == 0) asm volatile("" ::: "memory");
;         const int rl = 64 * wr + 32 * rb + crow(reg, g);
;         const int tok = m0 + rl;
;         const float rs = rs_s[rl];
; #pragma unroll
;         for (int cb = 0; cb < 4; ++cb) {
;           const int col = n0 - 3584 + 128 * wc + 32 * cb + li;
;           p.AG[(size_t)tok * 512 + col] = f2bf(siluf(acc[rb][cb][reg] * rs));
;         }
;       }
;     }
	v_mul_f32_e32 v141, v120, v128
	v_mul_f32_e32 v146, 0xbfb8aa3b, v141
	v_exp_f32_e32 v146, v146
	s_nop 0
	v_add_f32_e32 v146, 1.0, v146
	v_rcp_f32_e32 v146, v146
	s_nop 0
	v_mul_f32_e32 v141, v141, v146
	v_cvt_pk_bf16_f32 v141, v141, s0
	v_lshl_add_u64 v[146:147], v[142:143], 0, v[138:139]
	global_store_short v[146:147], v141, off
	v_mul_f32_e32 v141, v104, v128
	v_mul_f32_e32 v146, 0xbfb8aa3b, v141
	v_exp_f32_e32 v146, v146
	s_nop 0
	v_add_f32_e32 v146, 1.0, v146
	v_rcp_f32_e32 v146, v146
	s_nop 0
	v_mul_f32_e32 v141, v141, v146
	v_cvt_pk_bf16_f32 v141, v141, s0
	v_lshl_add_u64 v[146:147], v[142:143], 0, v[136:137]
	global_store_short v[146:147], v141, off
	v_mul_f32_e32 v141, v88, v128
	v_mul_f32_e32 v146, 0xbfb8aa3b, v141
	v_exp_f32_e32 v146, v146
	v_mul_f32_e32 v128, v72, v128
	v_add_f32_e32 v146, 1.0, v146
	v_rcp_f32_e32 v146, v146
	s_nop 0
	v_mul_f32_e32 v141, v141, v146
	v_cvt_pk_bf16_f32 v141, v141, s0
	v_lshl_add_u64 v[146:147], v[142:143], 0, v[134:135]
	global_store_short v[146:147], v141, off
	v_mul_f32_e32 v141, 0xbfb8aa3b, v128
	v_exp_f32_e32 v141, v141
	v_lshl_add_u64 v[142:143], v[142:143], 0, v[132:133]
	v_add_f32_e32 v141, 1.0, v141
	v_rcp_f32_e32 v141, v141
	s_nop 0
	v_mul_f32_e32 v128, v128, v141
	v_cvt_pk_bf16_f32 v128, v128, s0
	global_store_short v[142:143], v128, off
	v_mul_f32_e32 v128, v121, v129
	v_mul_f32_e32 v141, 0xbfb8aa3b, v128
	v_exp_f32_e32 v141, v141
	v_add_u32_e32 v142, 17, v140
	v_ashrrev_i32_e32 v143, 31, v142
	v_lshlrev_b64 v[142:143], 10, v[142:143]
	v_add_f32_e32 v141, 1.0, v141
	v_rcp_f32_e32 v141, v141
	v_lshl_add_u64 v[142:143], s[30:31], 0, v[142:143]
	v_lshl_add_u64 v[146:147], v[142:143], 0, v[138:139]
	v_mul_f32_e32 v128, v128, v141
	v_cvt_pk_bf16_f32 v128, v128, s0
	global_store_short v[146:147], v128, off
	v_mul_f32_e32 v128, v105, v129
	v_mul_f32_e32 v141, 0xbfb8aa3b, v128
	v_exp_f32_e32 v141, v141
	v_lshl_add_u64 v[146:147], v[142:143], 0, v[136:137]
	v_add_f32_e32 v141, 1.0, v141
	v_rcp_f32_e32 v141, v141
	s_nop 0
	v_mul_f32_e32 v128, v128, v141
	v_cvt_pk_bf16_f32 v128, v128, s0
	global_store_short v[146:147], v128, off
	v_mul_f32_e32 v128, v89, v129
	v_mul_f32_e32 v141, 0xbfb8aa3b, v128
	v_exp_f32_e32 v141, v141
	v_lshl_add_u64 v[146:147], v[142:143], 0, v[134:135]
	v_add_f32_e32 v141, 1.0, v141
	v_rcp_f32_e32 v141, v141
	s_nop 0
	v_mul_f32_e32 v128, v128, v141
	v_cvt_pk_bf16_f32 v128, v128, s0
	global_store_short v[146:147], v128, off
	v_mul_f32_e32 v128, v73, v129
	v_mul_f32_e32 v129, 0xbfb8aa3b, v128
	v_exp_f32_e32 v129, v129
	s_nop 0
	v_add_f32_e32 v129, 1.0, v129
	v_rcp_f32_e32 v129, v129
	s_nop 0
	v_mul_f32_e32 v128, v128, v129
	v_cvt_pk_bf16_f32 v141, v128, s0
	v_lshl_add_u64 v[128:129], v[142:143], 0, v[132:133]
	global_store_short v[128:129], v141, off
	v_mul_f32_e32 v141, v122, v130
	v_mul_f32_e32 v142, 0xbfb8aa3b, v141
	v_exp_f32_e32 v142, v142
	v_add_u32_e32 v128, 18, v140
	v_ashrrev_i32_e32 v129, 31, v128
	v_lshlrev_b64 v[128:129], 10, v[128:129]
	v_add_f32_e32 v142, 1.0, v142
	v_rcp_f32_e32 v142, v142
	v_lshl_add_u64 v[128:129], s[30:31], 0, v[128:129]
	v_mul_f32_e32 v141, v141, v142
	v_cvt_pk_bf16_f32 v141, v141, s0
	v_lshl_add_u64 v[142:143], v[128:129], 0, v[138:139]
	global_store_short v[142:143], v141, off
	v_mul_f32_e32 v141, v106, v130
	v_mul_f32_e32 v142, 0xbfb8aa3b, v141
	v_exp_f32_e32 v142, v142
	s_nop 0
	v_add_f32_e32 v142, 1.0, v142
	v_rcp_f32_e32 v142, v142
	s_nop 0
	v_mul_f32_e32 v141, v141, v142
	v_cvt_pk_bf16_f32 v141, v141, s0
	v_lshl_add_u64 v[142:143], v[128:129], 0, v[136:137]
	global_store_short v[142:143], v141, off
	v_mul_f32_e32 v141, v90, v130
	v_mul_f32_e32 v142, 0xbfb8aa3b, v141
	v_exp_f32_e32 v142, v142
	v_mul_f32_e32 v130, v74, v130
	v_add_f32_e32 v142, 1.0, v142
	v_rcp_f32_e32 v142, v142
	s_nop 0
	v_mul_f32_e32 v141, v141, v142
	v_cvt_pk_bf16_f32 v141, v141, s0
	v_lshl_add_u64 v[142:143], v[128:129], 0, v[134:135]
	global_store_short v[142:143], v141, off
	v_mul_f32_e32 v141, 0xbfb8aa3b, v130
	v_exp_f32_e32 v141, v141
	v_lshl_add_u64 v[128:129], v[128:129], 0, v[132:133]
	v_add_f32_e32 v141, 1.0, v141
	v_rcp_f32_e32 v141, v141
	s_nop 0
	v_mul_f32_e32 v130, v130, v141
	v_cvt_pk_bf16_f32 v130, v130, s0
	global_store_short v[128:129], v130, off
	v_mul_f32_e32 v130, v123, v131
	v_mul_f32_e32 v141, 0xbfb8aa3b, v130
	v_exp_f32_e32 v141, v141
	v_add_u32_e32 v128, 19, v140
	v_ashrrev_i32_e32 v129, 31, v128
	v_lshlrev_b64 v[128:129], 10, v[128:129]
	v_add_f32_e32 v141, 1.0, v141
	v_rcp_f32_e32 v141, v141
	v_lshl_add_u64 v[128:129], s[30:31], 0, v[128:129]
	v_lshl_add_u64 v[142:143], v[128:129], 0, v[138:139]
	v_mul_f32_e32 v130, v130, v141
	v_cvt_pk_bf16_f32 v130, v130, s0
	global_store_short v[142:143], v130, off
	v_mul_f32_e32 v130, v107, v131
	v_mul_f32_e32 v141, 0xbfb8aa3b, v130
	v_exp_f32_e32 v141, v141
	v_lshl_add_u64 v[142:143], v[128:129], 0, v[136:137]
	v_add_f32_e32 v141, 1.0, v141
	v_rcp_f32_e32 v141, v141
	s_nop 0
	v_mul_f32_e32 v130, v130, v141
	v_cvt_pk_bf16_f32 v130, v130, s0
	global_store_short v[142:143], v130, off
	v_mul_f32_e32 v130, v91, v131
	v_mul_f32_e32 v141, 0xbfb8aa3b, v130
	v_exp_f32_e32 v141, v141
	v_lshl_add_u64 v[142:143], v[128:129], 0, v[134:135]
	v_lshl_add_u64 v[128:129], v[128:129], 0, v[132:133]
	v_add_f32_e32 v141, 1.0, v141
	v_rcp_f32_e32 v141, v141
	s_nop 0
	v_mul_f32_e32 v130, v130, v141
	v_cvt_pk_bf16_f32 v130, v130, s0
	global_store_short v[142:143], v130, off
	v_mul_f32_e32 v130, v75, v131
	v_mul_f32_e32 v131, 0xbfb8aa3b, v130
	v_exp_f32_e32 v131, v131
	s_nop 0
	v_add_f32_e32 v131, 1.0, v131
	v_rcp_f32_e32 v131, v131
	s_nop 0
	v_mul_f32_e32 v130, v130, v131
	v_cvt_pk_bf16_f32 v130, v130, s0
	global_store_short v[128:129], v130, off
	v_or_b32_e32 v128, 24, v144
	v_add_u32_e32 v142, s76, v128
	v_lshl_add_u32 v128, v128, 2, s8
	ds_read_b128 v[128:131], v128
	v_ashrrev_i32_e32 v143, 31, v142
	v_lshlrev_b64 v[142:143], 10, v[142:143]
	v_lshl_add_u64 v[142:143], s[30:31], 0, v[142:143]
	s_waitcnt lgkmcnt(0)
; DI u16 f2bf(float a) { return (u16)(pack2(a, 0.f) & 0xffffu); }
; DI int crow(int reg, int g) { return (reg & 3) + 8 * (reg >> 2) + 4 * g; }
; DI float siluf(float x) { return x * __builtin_amdgcn_rcpf(1.f + __expf(-x)); }
; template <bool TR>
; DI void gemm_in_tile(const P& p, int l, int id, char* smem) {
;     ...
; #pragma unroll
;     for (int rb = 0; rb < 2; ++rb) {
; #pragma unroll
;       for (int reg = 0; reg < 16; ++reg) {
;         if ((reg & 7) == 0) asm volatile("" ::: "memory");
;         const int rl = 64 * wr + 32 * rb + crow(reg, g);
;         const int tok = m0 + rl;
;         const float rs = rs_s[rl];
; #pragma unroll
;         for (int cb = 0; cb < 4; ++cb) {
;           const int col = n0 - 3584 + 128 * wc + 32 * cb + li;
;           p.AG[(size_t)tok * 512 + col] = f2bf(siluf(acc[rb][cb][reg] * rs));
;         }
;       }
;     }
	v_mul_f32_e32 v141, v124, v128
	v_mul_f32_e32 v146, 0xbfb8aa3b, v141
	v_exp_f32_e32 v146, v146
	s_nop 0
	v_add_f32_e32 v146, 1.0, v146
	v_rcp_f32_e32 v146, v146
	s_nop 0
	v_mul_f32_e32 v141, v141, v146
	v_cvt_pk_bf16_f32 v141, v141, s0
	v_lshl_add_u64 v[146:147], v[142:143], 0, v[138:139]
	global_store_short v[146:147], v141, off
	v_mul_f32_e32 v141, v108, v128
	v_mul_f32_e32 v146, 0xbfb8aa3b, v141
	v_exp_f32_e32 v146, v146
	s_nop 0
	v_add_f32_e32 v146, 1.0, v146
	v_rcp_f32_e32 v146, v146
	s_nop 0
	v_mul_f32_e32 v141, v141, v146
	v_cvt_pk_bf16_f32 v141, v141, s0
	v_lshl_add_u64 v[146:147], v[142:143], 0, v[136:137]
	global_store_short v[146:147], v141, off
	v_mul_f32_e32 v141, v92, v128
	v_mul_f32_e32 v146, 0xbfb8aa3b, v141
	v_exp_f32_e32 v146, v146
	v_mul_f32_e32 v128, v76, v128
	v_add_f32_e32 v146, 1.0, v146
	v_rcp_f32_e32 v146, v146
	s_nop 0
	v_mul_f32_e32 v141, v141, v146
	v_cvt_pk_bf16_f32 v141, v141, s0
	v_lshl_add_u64 v[146:147], v[142:143], 0, v[134:135]
	global_store_short v[146:147], v141, off
	v_mul_f32_e32 v141, 0xbfb8aa3b, v128
	v_exp_f32_e32 v141, v141
	v_lshl_add_u64 v[142:143], v[142:143], 0, v[132:133]
	v_add_f32_e32 v141, 1.0, v141
	v_rcp_f32_e32 v141, v141
	s_nop 0
	v_mul_f32_e32 v128, v128, v141
	v_cvt_pk_bf16_f32 v128, v128, s0
	global_store_short v[142:143], v128, off
	v_mul_f32_e32 v128, v125, v129
	v_mul_f32_e32 v141, 0xbfb8aa3b, v128
	v_exp_f32_e32 v141, v141
	v_add_u32_e32 v142, 25, v140
	v_ashrrev_i32_e32 v143, 31, v142
	v_lshlrev_b64 v[142:143], 10, v[142:143]
	v_add_f32_e32 v141, 1.0, v141
	v_rcp_f32_e32 v141, v141
	v_lshl_add_u64 v[142:143], s[30:31], 0, v[142:143]
	v_lshl_add_u64 v[146:147], v[142:143], 0, v[138:139]
	v_mul_f32_e32 v128, v128, v141
	v_cvt_pk_bf16_f32 v128, v128, s0
	global_store_short v[146:147], v128, off
	v_mul_f32_e32 v128, v109, v129
	v_mul_f32_e32 v141, 0xbfb8aa3b, v128
	v_exp_f32_e32 v141, v141
	v_lshl_add_u64 v[146:147], v[142:143], 0, v[136:137]
	v_add_f32_e32 v141, 1.0, v141
	v_rcp_f32_e32 v141, v141
	s_nop 0
	v_mul_f32_e32 v128, v128, v141
	v_cvt_pk_bf16_f32 v128, v128, s0
	global_store_short v[146:147], v128, off
	v_mul_f32_e32 v128, v93, v129
	v_mul_f32_e32 v141, 0xbfb8aa3b, v128
	v_exp_f32_e32 v141, v141
	v_lshl_add_u64 v[146:147], v[142:143], 0, v[134:135]
	v_add_f32_e32 v141, 1.0, v141
	v_rcp_f32_e32 v141, v141
	s_nop 0
	v_mul_f32_e32 v128, v128, v141
	v_cvt_pk_bf16_f32 v128, v128, s0
	global_store_short v[146:147], v128, off
	v_mul_f32_e32 v128, v77, v129
	v_mul_f32_e32 v129, 0xbfb8aa3b, v128
	v_exp_f32_e32 v129, v129
	s_nop 0
	v_add_f32_e32 v129, 1.0, v129
	v_rcp_f32_e32 v129, v129
	s_nop 0
	v_mul_f32_e32 v128, v128, v129
	v_cvt_pk_bf16_f32 v141, v128, s0
	v_lshl_add_u64 v[128:129], v[142:143], 0, v[132:133]
	global_store_short v[128:129], v141, off
	v_mul_f32_e32 v141, v126, v130
	v_mul_f32_e32 v142, 0xbfb8aa3b, v141
	v_exp_f32_e32 v142, v142
	v_add_u32_e32 v128, 26, v140
	v_ashrrev_i32_e32 v129, 31, v128
	v_lshlrev_b64 v[128:129], 10, v[128:129]
	v_add_f32_e32 v142, 1.0, v142
	v_rcp_f32_e32 v142, v142
	v_lshl_add_u64 v[128:129], s[30:31], 0, v[128:129]
	v_mul_f32_e32 v141, v141, v142
	v_cvt_pk_bf16_f32 v141, v141, s0
	v_lshl_add_u64 v[142:143], v[128:129], 0, v[138:139]
	global_store_short v[142:143], v141, off
	v_mul_f32_e32 v141, v110, v130
	v_mul_f32_e32 v142, 0xbfb8aa3b, v141
	v_exp_f32_e32 v142, v142
	s_nop 0
	v_add_f32_e32 v142, 1.0, v142
	v_rcp_f32_e32 v142, v142
	s_nop 0
	v_mul_f32_e32 v141, v141, v142
	v_cvt_pk_bf16_f32 v141, v141, s0
	v_lshl_add_u64 v[142:143], v[128:129], 0, v[136:137]
	global_store_short v[142:143], v141, off
	v_mul_f32_e32 v141, v94, v130
	v_mul_f32_e32 v142, 0xbfb8aa3b, v141
	v_exp_f32_e32 v142, v142
	v_mul_f32_e32 v130, v78, v130
	v_add_f32_e32 v142, 1.0, v142
	v_rcp_f32_e32 v142, v142
	s_nop 0
	v_mul_f32_e32 v141, v141, v142
	v_cvt_pk_bf16_f32 v141, v141, s0
	v_lshl_add_u64 v[142:143], v[128:129], 0, v[134:135]
	global_store_short v[142:143], v141, off
	v_mul_f32_e32 v141, 0xbfb8aa3b, v130
	v_exp_f32_e32 v141, v141
	v_lshl_add_u64 v[128:129], v[128:129], 0, v[132:133]
	v_add_f32_e32 v141, 1.0, v141
	v_rcp_f32_e32 v141, v141
	s_nop 0
	v_mul_f32_e32 v130, v130, v141
	v_cvt_pk_bf16_f32 v130, v130, s0
	global_store_short v[128:129], v130, off
	v_mul_f32_e32 v130, v127, v131
	v_mul_f32_e32 v141, 0xbfb8aa3b, v130
	v_exp_f32_e32 v141, v141
	v_add_u32_e32 v128, 27, v140
	v_ashrrev_i32_e32 v129, 31, v128
	v_lshlrev_b64 v[128:129], 10, v[128:129]
	v_add_f32_e32 v141, 1.0, v141
	v_rcp_f32_e32 v141, v141
	v_lshl_add_u64 v[128:129], s[30:31], 0, v[128:129]
	v_lshl_add_u64 v[142:143], v[128:129], 0, v[138:139]
	v_mul_f32_e32 v130, v130, v141
	v_cvt_pk_bf16_f32 v130, v130, s0
	global_store_short v[142:143], v130, off
	v_mul_f32_e32 v130, v111, v131
	v_mul_f32_e32 v141, 0xbfb8aa3b, v130
	v_exp_f32_e32 v141, v141
	v_lshl_add_u64 v[142:143], v[128:129], 0, v[136:137]
	v_add_f32_e32 v141, 1.0, v141
	v_rcp_f32_e32 v141, v141
	s_nop 0
	v_mul_f32_e32 v130, v130, v141
	v_cvt_pk_bf16_f32 v130, v130, s0
	global_store_short v[142:143], v130, off
	v_mul_f32_e32 v130, v95, v131
	v_mul_f32_e32 v141, 0xbfb8aa3b, v130
	v_exp_f32_e32 v141, v141
	v_lshl_add_u64 v[142:143], v[128:129], 0, v[134:135]
	v_lshl_add_u64 v[128:129], v[128:129], 0, v[132:133]
	v_add_f32_e32 v141, 1.0, v141
	v_rcp_f32_e32 v141, v141
	s_nop 0
	v_mul_f32_e32 v130, v130, v141
	v_cvt_pk_bf16_f32 v130, v130, s0
	global_store_short v[142:143], v130, off
	v_mul_f32_e32 v130, v79, v131
	v_mul_f32_e32 v131, 0xbfb8aa3b, v130
	v_exp_f32_e32 v131, v131
	s_nop 0
	v_add_f32_e32 v131, 1.0, v131
	v_rcp_f32_e32 v131, v131
	s_nop 0
	v_mul_f32_e32 v130, v130, v131
	v_cvt_pk_bf16_f32 v130, v130, s0
	global_store_short v[128:129], v130, off
	v_or_b32_e32 v128, 32, v144
	v_add_u32_e32 v142, s76, v128
	v_lshl_add_u32 v128, v128, 2, s8
	ds_read_b128 v[128:131], v128
	v_ashrrev_i32_e32 v143, 31, v142
	v_lshlrev_b64 v[142:143], 10, v[142:143]
	v_lshl_add_u64 v[142:143], s[30:31], 0, v[142:143]
	s_waitcnt lgkmcnt(0)
; DI u16 f2bf(float a) { return (u16)(pack2(a, 0.f) & 0xffffu); }
; DI int crow(int reg, int g) { return (reg & 3) + 8 * (reg >> 2) + 4 * g; }
; DI float siluf(float x) { return x * __builtin_amdgcn_rcpf(1.f + __expf(-x)); }
; template <bool TR>
; DI void gemm_in_tile(const P& p, int l, int id, char* smem) {
;     ...
; #pragma unroll
;     for (int rb = 0; rb < 2; ++rb) {
; #pragma unroll
;       for (int reg = 0; reg < 16; ++reg) {
;         if ((reg & 7) == 0) asm volatile("" ::: "memory");
;         const int rl = 64 * wr + 32 * rb + crow(reg, g);
;         const int tok = m0 + rl;
;         const float rs = rs_s[rl];
; #pragma unroll
;         for (int cb = 0; cb < 4; ++cb) {
;           const int col = n0 - 3584 + 128 * wc + 32 * cb + li;
;           p.AG[(size_t)tok * 512 + col] = f2bf(siluf(acc[rb][cb][reg] * rs));
;         }
;       }
;     }
	v_mul_f32_e32 v141, v48, v128
	v_mul_f32_e32 v146, 0xbfb8aa3b, v141
	v_exp_f32_e32 v146, v146
	s_nop 0
	v_add_f32_e32 v146, 1.0, v146
	v_rcp_f32_e32 v146, v146
	s_nop 0
	v_mul_f32_e32 v141, v141, v146
	v_cvt_pk_bf16_f32 v141, v141, s0
	v_lshl_add_u64 v[146:147], v[142:143], 0, v[138:139]
	global_store_short v[146:147], v141, off
	v_mul_f32_e32 v141, v32, v128
	v_mul_f32_e32 v146, 0xbfb8aa3b, v141
	v_exp_f32_e32 v146, v146
	s_nop 0
	v_add_f32_e32 v146, 1.0, v146
	v_rcp_f32_e32 v146, v146
	s_nop 0
	v_mul_f32_e32 v141, v141, v146
	v_cvt_pk_bf16_f32 v141, v141, s0
	v_lshl_add_u64 v[146:147], v[142:143], 0, v[136:137]
	global_store_short v[146:147], v141, off
	v_mul_f32_e32 v141, v16, v128
	v_mul_f32_e32 v146, 0xbfb8aa3b, v141
	v_exp_f32_e32 v146, v146
	v_mul_f32_e32 v128, v0, v128
	v_add_f32_e32 v146, 1.0, v146
	v_rcp_f32_e32 v146, v146
	s_nop 0
	v_mul_f32_e32 v141, v141, v146
	v_cvt_pk_bf16_f32 v141, v141, s0
	v_lshl_add_u64 v[146:147], v[142:143], 0, v[134:135]
	global_store_short v[146:147], v141, off
	v_mul_f32_e32 v141, 0xbfb8aa3b, v128
	v_exp_f32_e32 v141, v141
	v_lshl_add_u64 v[142:143], v[142:143], 0, v[132:133]
	v_add_f32_e32 v141, 1.0, v141
	v_rcp_f32_e32 v141, v141
	s_nop 0
	v_mul_f32_e32 v128, v128, v141
	v_cvt_pk_bf16_f32 v128, v128, s0
	global_store_short v[142:143], v128, off
	v_mul_f32_e32 v128, v49, v129
	v_mul_f32_e32 v141, 0xbfb8aa3b, v128
	v_exp_f32_e32 v141, v141
	v_add_u32_e32 v142, 33, v140
	v_ashrrev_i32_e32 v143, 31, v142
	v_lshlrev_b64 v[142:143], 10, v[142:143]
	v_add_f32_e32 v141, 1.0, v141
	v_rcp_f32_e32 v141, v141
	v_lshl_add_u64 v[142:143], s[30:31], 0, v[142:143]
	v_lshl_add_u64 v[146:147], v[142:143], 0, v[138:139]
	v_mul_f32_e32 v128, v128, v141
	v_cvt_pk_bf16_f32 v128, v128, s0
	global_store_short v[146:147], v128, off
	v_mul_f32_e32 v128, v33, v129
	v_mul_f32_e32 v141, 0xbfb8aa3b, v128
	v_exp_f32_e32 v141, v141
	v_lshl_add_u64 v[146:147], v[142:143], 0, v[136:137]
	v_add_f32_e32 v141, 1.0, v141
	v_rcp_f32_e32 v141, v141
	s_nop 0
	v_mul_f32_e32 v128, v128, v141
	v_cvt_pk_bf16_f32 v128, v128, s0
	global_store_short v[146:147], v128, off
	v_mul_f32_e32 v128, v17, v129
	v_mul_f32_e32 v141, 0xbfb8aa3b, v128
	v_exp_f32_e32 v141, v141
	v_lshl_add_u64 v[146:147], v[142:143], 0, v[134:135]
	v_add_f32_e32 v141, 1.0, v141
	v_rcp_f32_e32 v141, v141
	s_nop 0
	v_mul_f32_e32 v128, v128, v141
	v_cvt_pk_bf16_f32 v128, v128, s0
	global_store_short v[146:147], v128, off
	v_mul_f32_e32 v128, v1, v129
	v_mul_f32_e32 v129, 0xbfb8aa3b, v128
	v_exp_f32_e32 v129, v129
	s_nop 0
	v_add_f32_e32 v129, 1.0, v129
	v_rcp_f32_e32 v129, v129
	s_nop 0
	v_mul_f32_e32 v128, v128, v129
	v_cvt_pk_bf16_f32 v141, v128, s0
	v_lshl_add_u64 v[128:129], v[142:143], 0, v[132:133]
	global_store_short v[128:129], v141, off
	v_mul_f32_e32 v141, v50, v130
	v_mul_f32_e32 v142, 0xbfb8aa3b, v141
	v_exp_f32_e32 v142, v142
	v_add_u32_e32 v128, 34, v140
	v_ashrrev_i32_e32 v129, 31, v128
	v_lshlrev_b64 v[128:129], 10, v[128:129]
	v_add_f32_e32 v142, 1.0, v142
	v_rcp_f32_e32 v142, v142
	v_lshl_add_u64 v[128:129], s[30:31], 0, v[128:129]
	v_mul_f32_e32 v141, v141, v142
	v_cvt_pk_bf16_f32 v141, v141, s0
	v_lshl_add_u64 v[142:143], v[128:129], 0, v[138:139]
	global_store_short v[142:143], v141, off
	v_mul_f32_e32 v141, v34, v130
	v_mul_f32_e32 v142, 0xbfb8aa3b, v141
	v_exp_f32_e32 v142, v142
	s_nop 0
	v_add_f32_e32 v142, 1.0, v142
	v_rcp_f32_e32 v142, v142
	s_nop 0
	v_mul_f32_e32 v141, v141, v142
	v_cvt_pk_bf16_f32 v141, v141, s0
	v_lshl_add_u64 v[142:143], v[128:129], 0, v[136:137]
	global_store_short v[142:143], v141, off
	v_mul_f32_e32 v141, v18, v130
	v_mul_f32_e32 v142, 0xbfb8aa3b, v141
	v_exp_f32_e32 v142, v142
	v_mul_f32_e32 v130, v2, v130
	v_add_f32_e32 v142, 1.0, v142
	v_rcp_f32_e32 v142, v142
	s_nop 0
	v_mul_f32_e32 v141, v141, v142
	v_cvt_pk_bf16_f32 v141, v141, s0
	v_lshl_add_u64 v[142:143], v[128:129], 0, v[134:135]
	global_store_short v[142:143], v141, off
	v_mul_f32_e32 v141, 0xbfb8aa3b, v130
	v_exp_f32_e32 v141, v141
	v_lshl_add_u64 v[128:129], v[128:129], 0, v[132:133]
	v_add_f32_e32 v141, 1.0, v141
	v_rcp_f32_e32 v141, v141
	s_nop 0
	v_mul_f32_e32 v130, v130, v141
	v_cvt_pk_bf16_f32 v130, v130, s0
	global_store_short v[128:129], v130, off
	v_mul_f32_e32 v130, v51, v131
	v_mul_f32_e32 v141, 0xbfb8aa3b, v130
	v_exp_f32_e32 v141, v141
	v_add_u32_e32 v128, 35, v140
	v_ashrrev_i32_e32 v129, 31, v128
	v_lshlrev_b64 v[128:129], 10, v[128:129]
	v_add_f32_e32 v141, 1.0, v141
	v_rcp_f32_e32 v141, v141
	v_lshl_add_u64 v[128:129], s[30:31], 0, v[128:129]
	v_lshl_add_u64 v[142:143], v[128:129], 0, v[138:139]
	v_mul_f32_e32 v130, v130, v141
	v_cvt_pk_bf16_f32 v130, v130, s0
	global_store_short v[142:143], v130, off
	v_mul_f32_e32 v130, v35, v131
	v_mul_f32_e32 v141, 0xbfb8aa3b, v130
	v_exp_f32_e32 v141, v141
	v_lshl_add_u64 v[142:143], v[128:129], 0, v[136:137]
	v_add_f32_e32 v141, 1.0, v141
	v_rcp_f32_e32 v141, v141
	s_nop 0
	v_mul_f32_e32 v130, v130, v141
	v_cvt_pk_bf16_f32 v130, v130, s0
	global_store_short v[142:143], v130, off
	v_mul_f32_e32 v130, v19, v131
	v_mul_f32_e32 v141, 0xbfb8aa3b, v130
	v_exp_f32_e32 v141, v141
	v_lshl_add_u64 v[142:143], v[128:129], 0, v[134:135]
	v_lshl_add_u64 v[128:129], v[128:129], 0, v[132:133]
	v_add_f32_e32 v141, 1.0, v141
	v_rcp_f32_e32 v141, v141
	s_nop 0
	v_mul_f32_e32 v130, v130, v141
	v_cvt_pk_bf16_f32 v130, v130, s0
	global_store_short v[142:143], v130, off
	v_mul_f32_e32 v130, v3, v131
	v_mul_f32_e32 v131, 0xbfb8aa3b, v130
	v_exp_f32_e32 v131, v131
	s_nop 0
	v_add_f32_e32 v131, 1.0, v131
	v_rcp_f32_e32 v131, v131
	s_nop 0
	v_mul_f32_e32 v130, v130, v131
	v_cvt_pk_bf16_f32 v130, v130, s0
	global_store_short v[128:129], v130, off
	v_or_b32_e32 v128, 40, v144
	v_add_u32_e32 v142, s76, v128
	v_lshl_add_u32 v128, v128, 2, s8
	ds_read_b128 v[128:131], v128
	v_ashrrev_i32_e32 v143, 31, v142
	v_lshlrev_b64 v[142:143], 10, v[142:143]
	v_lshl_add_u64 v[142:143], s[30:31], 0, v[142:143]
	s_waitcnt lgkmcnt(0)
; DI u16 f2bf(float a) { return (u16)(pack2(a, 0.f) & 0xffffu); }
; DI int crow(int reg, int g) { return (reg & 3) + 8 * (reg >> 2) + 4 * g; }
; DI float siluf(float x) { return x * __builtin_amdgcn_rcpf(1.f + __expf(-x)); }
; template <bool TR>
; DI void gemm_in_tile(const P& p, int l, int id, char* smem) {
;     ...
; #pragma unroll
;     for (int rb = 0; rb < 2; ++rb) {
; #pragma unroll
;       for (int reg = 0; reg < 16; ++reg) {
;         if ((reg & 7) == 0) asm volatile("" ::: "memory");
;         const int rl = 64 * wr + 32 * rb + crow(reg, g);
;         const int tok = m0 + rl;
;         const float rs = rs_s[rl];
; #pragma unroll
;         for (int cb = 0; cb < 4; ++cb) {
;           const int col = n0 - 3584 + 128 * wc + 32 * cb + li;
;           p.AG[(size_t)tok * 512 + col] = f2bf(siluf(acc[rb][cb][reg] * rs));
;         }
;       }
;     }
	v_mul_f32_e32 v141, v52, v128
	v_mul_f32_e32 v146, 0xbfb8aa3b, v141
	v_exp_f32_e32 v146, v146
	s_nop 0
	v_add_f32_e32 v146, 1.0, v146
	v_rcp_f32_e32 v146, v146
	s_nop 0
	v_mul_f32_e32 v141, v141, v146
	v_cvt_pk_bf16_f32 v141, v141, s0
	v_lshl_add_u64 v[146:147], v[142:143], 0, v[138:139]
	global_store_short v[146:147], v141, off
	v_mul_f32_e32 v141, v36, v128
	v_mul_f32_e32 v146, 0xbfb8aa3b, v141
	v_exp_f32_e32 v146, v146
	s_nop 0
	v_add_f32_e32 v146, 1.0, v146
	v_rcp_f32_e32 v146, v146
	s_nop 0
	v_mul_f32_e32 v141, v141, v146
	v_cvt_pk_bf16_f32 v141, v141, s0
	v_lshl_add_u64 v[146:147], v[142:143], 0, v[136:137]
	global_store_short v[146:147], v141, off
	v_mul_f32_e32 v141, v20, v128
	v_mul_f32_e32 v146, 0xbfb8aa3b, v141
	v_exp_f32_e32 v146, v146
	v_mul_f32_e32 v128, v4, v128
	v_add_f32_e32 v146, 1.0, v146
	v_rcp_f32_e32 v146, v146
	s_nop 0
	v_mul_f32_e32 v141, v141, v146
	v_cvt_pk_bf16_f32 v141, v141, s0
	v_lshl_add_u64 v[146:147], v[142:143], 0, v[134:135]
	global_store_short v[146:147], v141, off
	v_mul_f32_e32 v141, 0xbfb8aa3b, v128
	v_exp_f32_e32 v141, v141
	v_lshl_add_u64 v[142:143], v[142:143], 0, v[132:133]
	v_add_f32_e32 v141, 1.0, v141
	v_rcp_f32_e32 v141, v141
	s_nop 0
	v_mul_f32_e32 v128, v128, v141
	v_cvt_pk_bf16_f32 v128, v128, s0
	global_store_short v[142:143], v128, off
	v_mul_f32_e32 v128, v53, v129
	v_mul_f32_e32 v141, 0xbfb8aa3b, v128
	v_exp_f32_e32 v141, v141
	v_add_u32_e32 v142, 41, v140
	v_ashrrev_i32_e32 v143, 31, v142
	v_lshlrev_b64 v[142:143], 10, v[142:143]
	v_add_f32_e32 v141, 1.0, v141
	v_rcp_f32_e32 v141, v141
	v_lshl_add_u64 v[142:143], s[30:31], 0, v[142:143]
	v_lshl_add_u64 v[146:147], v[142:143], 0, v[138:139]
	v_mul_f32_e32 v128, v128, v141
	v_cvt_pk_bf16_f32 v128, v128, s0
	global_store_short v[146:147], v128, off
	v_mul_f32_e32 v128, v37, v129
	v_mul_f32_e32 v141, 0xbfb8aa3b, v128
	v_exp_f32_e32 v141, v141
	v_lshl_add_u64 v[146:147], v[142:143], 0, v[136:137]
	v_add_f32_e32 v141, 1.0, v141
	v_rcp_f32_e32 v141, v141
	s_nop 0
	v_mul_f32_e32 v128, v128, v141
	v_cvt_pk_bf16_f32 v128, v128, s0
	global_store_short v[146:147], v128, off
	v_mul_f32_e32 v128, v21, v129
	v_mul_f32_e32 v141, 0xbfb8aa3b, v128
	v_exp_f32_e32 v141, v141
	v_lshl_add_u64 v[146:147], v[142:143], 0, v[134:135]
	v_add_f32_e32 v141, 1.0, v141
	v_rcp_f32_e32 v141, v141
	s_nop 0
	v_mul_f32_e32 v128, v128, v141
	v_cvt_pk_bf16_f32 v128, v128, s0
	global_store_short v[146:147], v128, off
	v_mul_f32_e32 v128, v5, v129
	v_mul_f32_e32 v129, 0xbfb8aa3b, v128
	v_exp_f32_e32 v129, v129
	s_nop 0
	v_add_f32_e32 v129, 1.0, v129
	v_rcp_f32_e32 v129, v129
	s_nop 0
	v_mul_f32_e32 v128, v128, v129
	v_cvt_pk_bf16_f32 v141, v128, s0
	v_lshl_add_u64 v[128:129], v[142:143], 0, v[132:133]
	global_store_short v[128:129], v141, off
	v_mul_f32_e32 v141, v54, v130
	v_mul_f32_e32 v142, 0xbfb8aa3b, v141
	v_exp_f32_e32 v142, v142
	v_add_u32_e32 v128, 42, v140
	v_ashrrev_i32_e32 v129, 31, v128
	v_lshlrev_b64 v[128:129], 10, v[128:129]
	v_add_f32_e32 v142, 1.0, v142
	v_rcp_f32_e32 v142, v142
	v_lshl_add_u64 v[128:129], s[30:31], 0, v[128:129]
	v_mul_f32_e32 v141, v141, v142
	v_cvt_pk_bf16_f32 v141, v141, s0
	v_lshl_add_u64 v[142:143], v[128:129], 0, v[138:139]
	global_store_short v[142:143], v141, off
	v_mul_f32_e32 v141, v38, v130
	v_mul_f32_e32 v142, 0xbfb8aa3b, v141
	v_exp_f32_e32 v142, v142
	s_nop 0
	v_add_f32_e32 v142, 1.0, v142
	v_rcp_f32_e32 v142, v142
	s_nop 0
	v_mul_f32_e32 v141, v141, v142
	v_cvt_pk_bf16_f32 v141, v141, s0
	v_lshl_add_u64 v[142:143], v[128:129], 0, v[136:137]
	global_store_short v[142:143], v141, off
	v_mul_f32_e32 v141, v22, v130
	v_mul_f32_e32 v142, 0xbfb8aa3b, v141
	v_exp_f32_e32 v142, v142
	v_mul_f32_e32 v130, v6, v130
	v_add_f32_e32 v142, 1.0, v142
	v_rcp_f32_e32 v142, v142
	s_nop 0
	v_mul_f32_e32 v141, v141, v142
	v_cvt_pk_bf16_f32 v141, v141, s0
	v_lshl_add_u64 v[142:143], v[128:129], 0, v[134:135]
	global_store_short v[142:143], v141, off
	v_mul_f32_e32 v141, 0xbfb8aa3b, v130
	v_exp_f32_e32 v141, v141
	v_lshl_add_u64 v[128:129], v[128:129], 0, v[132:133]
	v_add_f32_e32 v141, 1.0, v141
	v_rcp_f32_e32 v141, v141
	s_nop 0
	v_mul_f32_e32 v130, v130, v141
	v_cvt_pk_bf16_f32 v130, v130, s0
	global_store_short v[128:129], v130, off
	v_mul_f32_e32 v130, v55, v131
	v_mul_f32_e32 v141, 0xbfb8aa3b, v130
	v_exp_f32_e32 v141, v141
	v_add_u32_e32 v128, 43, v140
	v_ashrrev_i32_e32 v129, 31, v128
	v_lshlrev_b64 v[128:129], 10, v[128:129]
	v_add_f32_e32 v141, 1.0, v141
	v_rcp_f32_e32 v141, v141
	v_lshl_add_u64 v[128:129], s[30:31], 0, v[128:129]
	v_lshl_add_u64 v[142:143], v[128:129], 0, v[138:139]
	v_mul_f32_e32 v130, v130, v141
	v_cvt_pk_bf16_f32 v130, v130, s0
	global_store_short v[142:143], v130, off
	v_mul_f32_e32 v130, v39, v131
	v_mul_f32_e32 v141, 0xbfb8aa3b, v130
	v_exp_f32_e32 v141, v141
	v_lshl_add_u64 v[142:143], v[128:129], 0, v[136:137]
	v_add_f32_e32 v141, 1.0, v141
	v_rcp_f32_e32 v141, v141
	s_nop 0
	v_mul_f32_e32 v130, v130, v141
	v_cvt_pk_bf16_f32 v130, v130, s0
	global_store_short v[142:143], v130, off
	v_mul_f32_e32 v130, v23, v131
	v_mul_f32_e32 v141, 0xbfb8aa3b, v130
	v_exp_f32_e32 v141, v141
	v_lshl_add_u64 v[142:143], v[128:129], 0, v[134:135]
	v_lshl_add_u64 v[128:129], v[128:129], 0, v[132:133]
	v_add_f32_e32 v141, 1.0, v141
	v_rcp_f32_e32 v141, v141
	s_nop 0
	v_mul_f32_e32 v130, v130, v141
	v_cvt_pk_bf16_f32 v130, v130, s0
	global_store_short v[142:143], v130, off
	v_mul_f32_e32 v130, v7, v131
	v_mul_f32_e32 v131, 0xbfb8aa3b, v130
	v_exp_f32_e32 v131, v131
	s_nop 0
	v_add_f32_e32 v131, 1.0, v131
	v_rcp_f32_e32 v131, v131
	s_nop 0
	v_mul_f32_e32 v130, v130, v131
	v_cvt_pk_bf16_f32 v130, v130, s0
	global_store_short v[128:129], v130, off
	v_or_b32_e32 v128, 48, v144
	v_add_u32_e32 v142, s76, v128
	v_lshl_add_u32 v128, v128, 2, s8
	ds_read_b128 v[128:131], v128
	v_ashrrev_i32_e32 v143, 31, v142
	v_lshlrev_b64 v[142:143], 10, v[142:143]
	v_lshl_add_u64 v[142:143], s[30:31], 0, v[142:143]
	s_waitcnt lgkmcnt(0)
; DI u16 f2bf(float a) { return (u16)(pack2(a, 0.f) & 0xffffu); }
; DI int crow(int reg, int g) { return (reg & 3) + 8 * (reg >> 2) + 4 * g; }
; DI float siluf(float x) { return x * __builtin_amdgcn_rcpf(1.f + __expf(-x)); }
; template <bool TR>
; DI void gemm_in_tile(const P& p, int l, int id, char* smem) {
;     ...
; #pragma unroll
;     for (int rb = 0; rb < 2; ++rb) {
; #pragma unroll
;       for (int reg = 0; reg < 16; ++reg) {
;         if ((reg & 7) == 0) asm volatile("" ::: "memory");
;         const int rl = 64 * wr + 32 * rb + crow(reg, g);
;         const int tok = m0 + rl;
;         const float rs = rs_s[rl];
; #pragma unroll
;         for (int cb = 0; cb < 4; ++cb) {
;           const int col = n0 - 3584 + 128 * wc + 32 * cb + li;
;           p.AG[(size_t)tok * 512 + col] = f2bf(siluf(acc[rb][cb][reg] * rs));
;         }
;       }
;     }
	v_mul_f32_e32 v141, v56, v128
	v_mul_f32_e32 v146, 0xbfb8aa3b, v141
	v_exp_f32_e32 v146, v146
	s_nop 0
	v_add_f32_e32 v146, 1.0, v146
	v_rcp_f32_e32 v146, v146
	s_nop 0
	v_mul_f32_e32 v141, v141, v146
	v_cvt_pk_bf16_f32 v141, v141, s0
	v_lshl_add_u64 v[146:147], v[142:143], 0, v[138:139]
	global_store_short v[146:147], v141, off
	v_mul_f32_e32 v141, v40, v128
	v_mul_f32_e32 v146, 0xbfb8aa3b, v141
	v_exp_f32_e32 v146, v146
	s_nop 0
	v_add_f32_e32 v146, 1.0, v146
	v_rcp_f32_e32 v146, v146
	s_nop 0
	v_mul_f32_e32 v141, v141, v146
	v_cvt_pk_bf16_f32 v141, v141, s0
	v_lshl_add_u64 v[146:147], v[142:143], 0, v[136:137]
	global_store_short v[146:147], v141, off
	v_mul_f32_e32 v141, v24, v128
	v_mul_f32_e32 v146, 0xbfb8aa3b, v141
	v_exp_f32_e32 v146, v146
	v_mul_f32_e32 v128, v8, v128
	v_add_f32_e32 v146, 1.0, v146
	v_rcp_f32_e32 v146, v146
	s_nop 0
	v_mul_f32_e32 v141, v141, v146
	v_cvt_pk_bf16_f32 v141, v141, s0
	v_lshl_add_u64 v[146:147], v[142:143], 0, v[134:135]
	global_store_short v[146:147], v141, off
	v_mul_f32_e32 v141, 0xbfb8aa3b, v128
	v_exp_f32_e32 v141, v141
	v_lshl_add_u64 v[142:143], v[142:143], 0, v[132:133]
	v_add_f32_e32 v141, 1.0, v141
	v_rcp_f32_e32 v141, v141
	s_nop 0
	v_mul_f32_e32 v128, v128, v141
	v_cvt_pk_bf16_f32 v128, v128, s0
	global_store_short v[142:143], v128, off
	v_mul_f32_e32 v128, v57, v129
	v_mul_f32_e32 v141, 0xbfb8aa3b, v128
	v_exp_f32_e32 v141, v141
	v_add_u32_e32 v142, 49, v140
	v_ashrrev_i32_e32 v143, 31, v142
	v_lshlrev_b64 v[142:143], 10, v[142:143]
	v_add_f32_e32 v141, 1.0, v141
	v_rcp_f32_e32 v141, v141
	v_lshl_add_u64 v[142:143], s[30:31], 0, v[142:143]
	v_lshl_add_u64 v[146:147], v[142:143], 0, v[138:139]
	v_mul_f32_e32 v128, v128, v141
	v_cvt_pk_bf16_f32 v128, v128, s0
	global_store_short v[146:147], v128, off
	v_mul_f32_e32 v128, v41, v129
	v_mul_f32_e32 v141, 0xbfb8aa3b, v128
	v_exp_f32_e32 v141, v141
	v_lshl_add_u64 v[146:147], v[142:143], 0, v[136:137]
	v_add_f32_e32 v141, 1.0, v141
	v_rcp_f32_e32 v141, v141
	s_nop 0
	v_mul_f32_e32 v128, v128, v141
	v_cvt_pk_bf16_f32 v128, v128, s0
	global_store_short v[146:147], v128, off
	v_mul_f32_e32 v128, v25, v129
	v_mul_f32_e32 v141, 0xbfb8aa3b, v128
	v_exp_f32_e32 v141, v141
	v_lshl_add_u64 v[146:147], v[142:143], 0, v[134:135]
	v_add_f32_e32 v141, 1.0, v141
	v_rcp_f32_e32 v141, v141
	s_nop 0
	v_mul_f32_e32 v128, v128, v141
	v_cvt_pk_bf16_f32 v128, v128, s0
	global_store_short v[146:147], v128, off
	v_mul_f32_e32 v128, v9, v129
	v_mul_f32_e32 v129, 0xbfb8aa3b, v128
	v_exp_f32_e32 v129, v129
	s_nop 0
	v_add_f32_e32 v129, 1.0, v129
	v_rcp_f32_e32 v129, v129
	s_nop 0
	v_mul_f32_e32 v128, v128, v129
	v_cvt_pk_bf16_f32 v141, v128, s0
	v_lshl_add_u64 v[128:129], v[142:143], 0, v[132:133]
	global_store_short v[128:129], v141, off
	v_mul_f32_e32 v141, v58, v130
	v_mul_f32_e32 v142, 0xbfb8aa3b, v141
	v_exp_f32_e32 v142, v142
	v_add_u32_e32 v128, 50, v140
	v_ashrrev_i32_e32 v129, 31, v128
	v_lshlrev_b64 v[128:129], 10, v[128:129]
	v_add_f32_e32 v142, 1.0, v142
	v_rcp_f32_e32 v142, v142
	v_lshl_add_u64 v[128:129], s[30:31], 0, v[128:129]
	v_mul_f32_e32 v141, v141, v142
	v_cvt_pk_bf16_f32 v141, v141, s0
	v_lshl_add_u64 v[142:143], v[128:129], 0, v[138:139]
	global_store_short v[142:143], v141, off
	v_mul_f32_e32 v141, v42, v130
	v_mul_f32_e32 v142, 0xbfb8aa3b, v141
	v_exp_f32_e32 v142, v142
	s_nop 0
	v_add_f32_e32 v142, 1.0, v142
	v_rcp_f32_e32 v142, v142
	s_nop 0
	v_mul_f32_e32 v141, v141, v142
	v_cvt_pk_bf16_f32 v141, v141, s0
	v_lshl_add_u64 v[142:143], v[128:129], 0, v[136:137]
	global_store_short v[142:143], v141, off
	v_mul_f32_e32 v141, v26, v130
	v_mul_f32_e32 v142, 0xbfb8aa3b, v141
	v_exp_f32_e32 v142, v142
	v_mul_f32_e32 v130, v10, v130
	v_add_f32_e32 v142, 1.0, v142
	v_rcp_f32_e32 v142, v142
	s_nop 0
	v_mul_f32_e32 v141, v141, v142
	v_cvt_pk_bf16_f32 v141, v141, s0
	v_lshl_add_u64 v[142:143], v[128:129], 0, v[134:135]
	global_store_short v[142:143], v141, off
	v_mul_f32_e32 v141, 0xbfb8aa3b, v130
	v_exp_f32_e32 v141, v141
	v_lshl_add_u64 v[128:129], v[128:129], 0, v[132:133]
	v_add_f32_e32 v141, 1.0, v141
	v_rcp_f32_e32 v141, v141
	s_nop 0
	v_mul_f32_e32 v130, v130, v141
	v_cvt_pk_bf16_f32 v130, v130, s0
	global_store_short v[128:129], v130, off
	v_mul_f32_e32 v130, v59, v131
	v_mul_f32_e32 v141, 0xbfb8aa3b, v130
	v_exp_f32_e32 v141, v141
	v_add_u32_e32 v128, 51, v140
	v_ashrrev_i32_e32 v129, 31, v128
	v_lshlrev_b64 v[128:129], 10, v[128:129]
	v_add_f32_e32 v141, 1.0, v141
	v_rcp_f32_e32 v141, v141
	v_lshl_add_u64 v[128:129], s[30:31], 0, v[128:129]
	v_lshl_add_u64 v[142:143], v[128:129], 0, v[138:139]
	v_mul_f32_e32 v130, v130, v141
	v_cvt_pk_bf16_f32 v130, v130, s0
	global_store_short v[142:143], v130, off
	v_mul_f32_e32 v130, v43, v131
	v_mul_f32_e32 v141, 0xbfb8aa3b, v130
	v_exp_f32_e32 v141, v141
	v_lshl_add_u64 v[142:143], v[128:129], 0, v[136:137]
	v_add_f32_e32 v141, 1.0, v141
	v_rcp_f32_e32 v141, v141
	s_nop 0
	v_mul_f32_e32 v130, v130, v141
	v_cvt_pk_bf16_f32 v130, v130, s0
	global_store_short v[142:143], v130, off
	v_mul_f32_e32 v130, v27, v131
	v_mul_f32_e32 v141, 0xbfb8aa3b, v130
	v_exp_f32_e32 v141, v141
	v_lshl_add_u64 v[142:143], v[128:129], 0, v[134:135]
	v_lshl_add_u64 v[128:129], v[128:129], 0, v[132:133]
	v_add_f32_e32 v141, 1.0, v141
	v_rcp_f32_e32 v141, v141
	s_nop 0
	v_mul_f32_e32 v130, v130, v141
	v_cvt_pk_bf16_f32 v130, v130, s0
	global_store_short v[142:143], v130, off
	v_mul_f32_e32 v130, v11, v131
	v_mul_f32_e32 v131, 0xbfb8aa3b, v130
	v_exp_f32_e32 v131, v131
	s_nop 0
	v_add_f32_e32 v131, 1.0, v131
	v_rcp_f32_e32 v131, v131
	s_nop 0
	v_mul_f32_e32 v130, v130, v131
	v_cvt_pk_bf16_f32 v130, v130, s0
	global_store_short v[128:129], v130, off
	v_or_b32_e32 v128, 56, v144
	v_add_u32_e32 v142, s76, v128
	v_lshl_add_u32 v128, v128, 2, s8
	ds_read_b128 v[128:131], v128
	v_ashrrev_i32_e32 v143, 31, v142
	v_lshlrev_b64 v[142:143], 10, v[142:143]
	v_lshl_add_u64 v[142:143], s[30:31], 0, v[142:143]
	s_mov_b64 s[8:9], 0
	s_waitcnt lgkmcnt(0)
; DI u16 f2bf(float a) { return (u16)(pack2(a, 0.f) & 0xffffu); }
; DI int crow(int reg, int g) { return (reg & 3) + 8 * (reg >> 2) + 4 * g; }
; DI float siluf(float x) { return x * __builtin_amdgcn_rcpf(1.f + __expf(-x)); }
; template <bool TR>
; DI void gemm_in_tile(const P& p, int l, int id, char* smem) {
;     ...
; #pragma unroll
;     for (int rb = 0; rb < 2; ++rb) {
; #pragma unroll
;       for (int reg = 0; reg < 16; ++reg) {
;         if ((reg & 7) == 0) asm volatile("" ::: "memory");
;         const int rl = 64 * wr + 32 * rb + crow(reg, g);
;         const int tok = m0 + rl;
;         const float rs = rs_s[rl];
; #pragma unroll
;         for (int cb = 0; cb < 4; ++cb) {
;           const int col = n0 - 3584 + 128 * wc + 32 * cb + li;
;           p.AG[(size_t)tok * 512 + col] = f2bf(siluf(acc[rb][cb][reg] * rs));
;         }
;       }
;     }
	v_mul_f32_e32 v141, v60, v128
	v_mul_f32_e32 v146, 0xbfb8aa3b, v141
	v_exp_f32_e32 v146, v146
	s_nop 0
	v_add_f32_e32 v146, 1.0, v146
	v_rcp_f32_e32 v146, v146
	s_nop 0
	v_mul_f32_e32 v141, v141, v146
	v_cvt_pk_bf16_f32 v141, v141, s0
	v_lshl_add_u64 v[146:147], v[142:143], 0, v[138:139]
	global_store_short v[146:147], v141, off
	v_mul_f32_e32 v141, v44, v128
	v_mul_f32_e32 v146, 0xbfb8aa3b, v141
	v_exp_f32_e32 v146, v146
	s_nop 0
	v_add_f32_e32 v146, 1.0, v146
	v_rcp_f32_e32 v146, v146
	s_nop 0
	v_mul_f32_e32 v141, v141, v146
	v_cvt_pk_bf16_f32 v141, v141, s0
	v_lshl_add_u64 v[146:147], v[142:143], 0, v[136:137]
	global_store_short v[146:147], v141, off
	v_mul_f32_e32 v141, v28, v128
	v_mul_f32_e32 v146, 0xbfb8aa3b, v141
	v_exp_f32_e32 v146, v146
	v_mul_f32_e32 v128, v12, v128
	v_add_f32_e32 v146, 1.0, v146
	v_rcp_f32_e32 v146, v146
	s_nop 0
	v_mul_f32_e32 v141, v141, v146
	v_cvt_pk_bf16_f32 v141, v141, s0
	v_lshl_add_u64 v[146:147], v[142:143], 0, v[134:135]
	global_store_short v[146:147], v141, off
	v_mul_f32_e32 v141, 0xbfb8aa3b, v128
	v_exp_f32_e32 v141, v141
	v_lshl_add_u64 v[142:143], v[142:143], 0, v[132:133]
	v_add_f32_e32 v141, 1.0, v141
	v_rcp_f32_e32 v141, v141
	s_nop 0
	v_mul_f32_e32 v128, v128, v141
	v_cvt_pk_bf16_f32 v128, v128, s0
	global_store_short v[142:143], v128, off
	v_mul_f32_e32 v128, v61, v129
	v_mul_f32_e32 v141, 0xbfb8aa3b, v128
	v_exp_f32_e32 v141, v141
	v_add_u32_e32 v142, 57, v140
	v_ashrrev_i32_e32 v143, 31, v142
	v_lshlrev_b64 v[142:143], 10, v[142:143]
	v_add_f32_e32 v141, 1.0, v141
	v_rcp_f32_e32 v141, v141
	v_lshl_add_u64 v[142:143], s[30:31], 0, v[142:143]
	v_lshl_add_u64 v[146:147], v[142:143], 0, v[138:139]
	v_mul_f32_e32 v128, v128, v141
	v_cvt_pk_bf16_f32 v128, v128, s0
	global_store_short v[146:147], v128, off
	v_mul_f32_e32 v128, v45, v129
	v_mul_f32_e32 v141, 0xbfb8aa3b, v128
	v_exp_f32_e32 v141, v141
	v_lshl_add_u64 v[146:147], v[142:143], 0, v[136:137]
	v_add_f32_e32 v141, 1.0, v141
	v_rcp_f32_e32 v141, v141
	s_nop 0
	v_mul_f32_e32 v128, v128, v141
	v_cvt_pk_bf16_f32 v128, v128, s0
	global_store_short v[146:147], v128, off
	v_mul_f32_e32 v128, v29, v129
	v_mul_f32_e32 v141, 0xbfb8aa3b, v128
	v_exp_f32_e32 v141, v141
	v_lshl_add_u64 v[146:147], v[142:143], 0, v[134:135]
	v_add_f32_e32 v141, 1.0, v141
	v_rcp_f32_e32 v141, v141
	s_nop 0
	v_mul_f32_e32 v128, v128, v141
	v_cvt_pk_bf16_f32 v128, v128, s0
	global_store_short v[146:147], v128, off
	v_mul_f32_e32 v128, v13, v129
	v_mul_f32_e32 v129, 0xbfb8aa3b, v128
	v_exp_f32_e32 v129, v129
	s_nop 0
	v_add_f32_e32 v129, 1.0, v129
	v_rcp_f32_e32 v129, v129
	s_nop 0
	v_mul_f32_e32 v128, v128, v129
	v_cvt_pk_bf16_f32 v141, v128, s0
	v_lshl_add_u64 v[128:129], v[142:143], 0, v[132:133]
	global_store_short v[128:129], v141, off
	v_mul_f32_e32 v141, v62, v130
	v_mul_f32_e32 v142, 0xbfb8aa3b, v141
	v_exp_f32_e32 v142, v142
	v_add_u32_e32 v128, 58, v140
	v_ashrrev_i32_e32 v129, 31, v128
	v_lshlrev_b64 v[128:129], 10, v[128:129]
	v_add_f32_e32 v142, 1.0, v142
	v_rcp_f32_e32 v142, v142
	v_lshl_add_u64 v[128:129], s[30:31], 0, v[128:129]
	v_mul_f32_e32 v141, v141, v142
	v_cvt_pk_bf16_f32 v141, v141, s0
	v_lshl_add_u64 v[142:143], v[128:129], 0, v[138:139]
	global_store_short v[142:143], v141, off
	v_mul_f32_e32 v141, v46, v130
	v_mul_f32_e32 v142, 0xbfb8aa3b, v141
	v_exp_f32_e32 v142, v142
	s_nop 0
	v_add_f32_e32 v142, 1.0, v142
	v_rcp_f32_e32 v142, v142
	s_nop 0
	v_mul_f32_e32 v141, v141, v142
	v_cvt_pk_bf16_f32 v141, v141, s0
	v_lshl_add_u64 v[142:143], v[128:129], 0, v[136:137]
	global_store_short v[142:143], v141, off
	v_mul_f32_e32 v141, v30, v130
	v_mul_f32_e32 v142, 0xbfb8aa3b, v141
	v_exp_f32_e32 v142, v142
	v_mul_f32_e32 v130, v14, v130
	v_add_f32_e32 v142, 1.0, v142
	v_rcp_f32_e32 v142, v142
	s_nop 0
	v_mul_f32_e32 v141, v141, v142
	v_cvt_pk_bf16_f32 v141, v141, s0
	v_lshl_add_u64 v[142:143], v[128:129], 0, v[134:135]
	global_store_short v[142:143], v141, off
	v_mul_f32_e32 v141, 0xbfb8aa3b, v130
	v_exp_f32_e32 v141, v141
	v_lshl_add_u64 v[128:129], v[128:129], 0, v[132:133]
	v_add_f32_e32 v141, 1.0, v141
	v_rcp_f32_e32 v141, v141
	s_nop 0
	v_mul_f32_e32 v130, v130, v141
	v_cvt_pk_bf16_f32 v130, v130, s0
	global_store_short v[128:129], v130, off
	v_mul_f32_e32 v130, v63, v131
	v_add_u32_e32 v128, 59, v140
	v_mul_f32_e32 v140, 0xbfb8aa3b, v130
	v_exp_f32_e32 v140, v140
	v_ashrrev_i32_e32 v129, 31, v128
	v_lshlrev_b64 v[128:129], 10, v[128:129]
	v_lshl_add_u64 v[128:129], s[30:31], 0, v[128:129]
	v_add_f32_e32 v140, 1.0, v140
	v_rcp_f32_e32 v140, v140
	v_lshl_add_u64 v[138:139], v[128:129], 0, v[138:139]
	v_lshl_add_u64 v[136:137], v[128:129], 0, v[136:137]
	v_lshl_add_u64 v[134:135], v[128:129], 0, v[134:135]
	v_mul_f32_e32 v130, v130, v140
	v_cvt_pk_bf16_f32 v130, v130, s0
	global_store_short v[138:139], v130, off
	v_mul_f32_e32 v130, v47, v131
	v_mul_f32_e32 v138, 0xbfb8aa3b, v130
	v_exp_f32_e32 v138, v138
	v_lshl_add_u64 v[128:129], v[128:129], 0, v[132:133]
	v_add_f32_e32 v138, 1.0, v138
	v_rcp_f32_e32 v138, v138
	s_nop 0
	v_mul_f32_e32 v130, v130, v138
	v_cvt_pk_bf16_f32 v130, v130, s0
	global_store_short v[136:137], v130, off
	v_mul_f32_e32 v130, v31, v131
	v_mul_f32_e32 v136, 0xbfb8aa3b, v130
	v_exp_f32_e32 v136, v136
	s_nop 0
	v_add_f32_e32 v136, 1.0, v136
	v_rcp_f32_e32 v136, v136
	s_nop 0
	v_mul_f32_e32 v130, v130, v136
	v_cvt_pk_bf16_f32 v130, v130, s0
	global_store_short v[134:135], v130, off
	v_mul_f32_e32 v130, v15, v131
	v_mul_f32_e32 v131, 0xbfb8aa3b, v130
	v_exp_f32_e32 v131, v131
	s_nop 0
	v_add_f32_e32 v131, 1.0, v131
	v_rcp_f32_e32 v131, v131
	s_nop 0
	v_mul_f32_e32 v130, v130, v131
	v_cvt_pk_bf16_f32 v130, v130, s0
	global_store_short v[128:129], v130, off

; DI f32x16 zero16() { f32x16 z; for (int i = 0; i < 16; ++i) z[i] = 0.f; return z; }
; template <bool AT>
; DI void gemm_main(f32x16 (&acc)[2][4], const u16* __restrict__ R, int ldr, const u16* __restrict__ Cm, int ldc,
;                   const u16* __restrict__ RT, int ldrt, int K, char* smem, int tid) {
;     ...
; #pragma unroll
;   for (int a = 0; a < 2; ++a)
; #pragma unroll
;     for (int b = 0; b < 4; ++b) acc[a][b] = zero16();
;   const int nk = K / 64;
; #pragma unroll
;   for (int i = 0; i < 4; ++i) {
;     const int cid = tid + NT * i;
;     const int row = cid >> 3, kc = cid & 7;
;     if (AT) {
;       const int kr = cid >> 5, tc = cid & 31;
;       rr[i] = *(const u32x4*)(RT + (size_t)kr * ldrt + tc * 8);
;     } else {
;       rr[i] = *(const u32x4*)(R + (size_t)row * ldr + kc * 8);
;     }
;     cr[i] = *(const u32x4*)(Cm + (size_t)row * ldc + kc * 8);
;   }
;   for (int kt = -1; kt < nk; ++kt) {
;     if (kt + 1 < nk) {
;       const int ks1 = kt + 1;
;       u16* Rs = S0 + (ks1 & 1) * STG;
;       u16* Cs = Rs + 256 * 72;
; #pragma unroll
;       for (int i = 0; i < 4; ++i) {
;         const int cid = tid + NT * i;
;         const int row = cid >> 3, kc = cid & 7;
;         if (AT && ks1 < 8) {
;           const int kr = cid >> 5, tc = cid & 31;
;           *(u32x4*)(Rs + kr * 264 + tc * 8) = rr[i];
;         } else {
;           *(u32x4*)(Rs + row * 72 + kc * 8) = rr[i];
;         }
;         *(u32x4*)(Cs + row * 72 + kc * 8) = cr[i];
;       }
; template <bool TR>
; DI void gemm_in_tile(const P& p, int l, int id, char* smem) {
;     ...
;   const u16* A = p.hb + (size_t)m0 * 1024;
;   const u16* B = p.WinT + (size_t)l * 4096 * 1024 + (size_t)n0 * 1024;
;   f32x16 acc[2][4];
;   if (TR) gemm_main<false>(acc, B, 1024, A, 1024, nullptr, 0, 1024, smem, tid);
;   else gemm_main<false>(acc, A, 1024, B, 1024, nullptr, 0, 1024, smem, tid);
.LBB0_341:
	s_or_b64 exec, exec, s[8:9]
	s_lshl_b32 s8, s74, 8
	s_lshl_b32 s9, s76, 19
	v_lshlrev_b32_e32 v0, 3, v177
	s_add_u32 s76, s36, s9
	v_and_b32_e32 v0, 56, v0
	s_addc_u32 s77, s37, 0
	v_lshlrev_b32_e32 v188, 1, v0
	s_ashr_i32 s9, s8, 31
	v_lshl_add_u64 v[20:21], s[76:77], 0, v[188:189]
	s_lshl_b64 s[76:77], s[8:9], 11
	v_readlane_b32 s9, v248, 29
	v_add_u32_e32 v8, 0x200, v177
	v_add_u32_e32 v9, 0x400, v177
	v_add_u32_e32 v10, 0x600, v177
	v_ashrrev_i32_e32 v32, 3, v177
	s_add_u32 s76, s9, s76
	v_readlane_b32 s9, v248, 30
	v_ashrrev_i32_e32 v40, 3, v8
	v_ashrrev_i32_e32 v42, 3, v9
	v_ashrrev_i32_e32 v44, 3, v10
	v_ashrrev_i32_e32 v33, 31, v32
	s_addc_u32 s77, s9, s77
	v_ashrrev_i32_e32 v41, 31, v40
	v_ashrrev_i32_e32 v43, 31, v42
	v_ashrrev_i32_e32 v45, 31, v44
	v_lshlrev_b64 v[34:35], 11, v[32:33]
	v_lshl_add_u64 v[24:25], s[76:77], 0, v[188:189]
	v_lshlrev_b64 v[46:47], 11, v[40:41]
	v_lshlrev_b64 v[52:53], 11, v[42:43]
	v_lshlrev_b64 v[56:57], 11, v[44:45]
	v_lshl_add_u64 v[36:37], v[20:21], 0, v[34:35]
	v_lshl_add_u64 v[38:39], v[24:25], 0, v[34:35]
	v_lshl_add_u64 v[48:49], v[24:25], 0, v[46:47]
	v_lshl_add_u64 v[50:51], v[20:21], 0, v[46:47]
	v_lshl_add_u64 v[54:55], v[24:25], 0, v[52:53]
	v_lshl_add_u64 v[60:61], v[20:21], 0, v[52:53]
	v_lshl_add_u64 v[62:63], v[24:25], 0, v[56:57]
	s_waitcnt lgkmcnt(0)
	global_load_dwordx4 v[0:3], v[36:37], off
	global_load_dwordx4 v[4:7], v[38:39], off
	global_load_dwordx4 v[8:11], v[48:49], off
	global_load_dwordx4 v[12:15], v[50:51], off
	global_load_dwordx4 v[16:19], v[54:55], off
	v_lshl_add_u64 v[58:59], v[20:21], 0, v[56:57]
	global_load_dwordx4 v[20:23], v[60:61], off
	global_load_dwordx4 v[24:27], v[62:63], off
	global_load_dwordx4 v[28:31], v[58:59], off
	global_load_dwordx4 v[136:139], v[36:37], off offset:128
	global_load_dwordx4 v[132:135], v[50:51], off offset:128
	global_load_dwordx4 v[128:131], v[60:61], off offset:128
	global_load_dwordx4 v[156:159], v[58:59], off offset:128
	global_load_dwordx4 v[152:155], v[38:39], off offset:128
	global_load_dwordx4 v[148:151], v[48:49], off offset:128
	global_load_dwordx4 v[144:147], v[54:55], off offset:128
	global_load_dwordx4 v[140:143], v[62:63], off offset:128
	s_movk_i32 s9, 0x48
	v_mul_lo_u32 v184, v32, s9
	v_mul_lo_u32 v185, v40, s9
	v_mul_lo_u32 v183, v42, s9
	v_mul_lo_u32 v182, v44, s9
	v_readlane_b32 s9, v248, 36
	s_add_u32 s76, s9, s64
	v_readlane_b32 s9, v248, 38
	s_addc_u32 s77, s9, 0
	s_lshl_b32 s9, s11, 8
	s_and_b32 s9, s9, 0xfffffc00
	v_ashrrev_i32_e32 v41, 1, v177
	s_or_b32 s10, s9, s10
	v_and_b32_e32 v33, 31, v177
	v_lshlrev_b32_e32 v45, 1, v177
	v_and_b32_e32 v178, 0xffffffc0, v41
	s_ashr_i32 s11, s10, 31
	v_lshlrev_b32_e32 v64, 4, v177
	v_and_or_b32 v176, v45, s95, v33
	v_or_b32_e32 v33, v178, v33
	v_add_u32_e32 v186, 0, v188
	s_lshl_b64 s[10:11], s[10:11], 11
	v_lshrrev_b32_e32 v43, 1, v177
	v_and_b32_e32 v32, 0x70, v64
	v_mul_lo_u32 v180, v33, s94
	v_lshl_add_u32 v33, v184, 1, v186
	s_add_u32 s10, s72, s10
	v_and_b32_e32 v179, 16, v43
	v_lshl_add_u32 v40, v185, 1, v186
	v_lshl_add_u32 v41, v183, 1, v186
	v_lshl_add_u32 v42, v182, 1, v186
	v_or_b32_e32 v56, v56, v32
	v_or_b32_e32 v52, v52, v32
	v_or_b32_e32 v46, v46, v32
	v_or_b32_e32 v34, v34, v32
	s_addc_u32 s11, s73, s11
	v_lshl_add_u64 v[160:161], s[76:77], 0, v[56:57]
	v_lshl_add_u64 v[162:163], s[76:77], 0, v[52:53]
	v_lshl_add_u64 v[164:165], s[76:77], 0, v[46:47]
	v_lshl_add_u64 v[166:167], s[76:77], 0, v[34:35]
	v_lshl_add_u64 v[168:169], s[10:11], 0, v[56:57]
	s_waitcnt vmcnt(15)
	ds_write_b128 v33, v[0:3] offset:36864
	s_waitcnt vmcnt(14)
	ds_write_b128 v33, v[4:7]
	s_waitcnt vmcnt(13)
	ds_write_b128 v40, v[8:11]
	s_waitcnt vmcnt(12)
	ds_write_b128 v40, v[12:15] offset:36864
	s_waitcnt vmcnt(11)
	ds_write_b128 v41, v[16:19]
	s_waitcnt vmcnt(10)
	ds_write_b128 v41, v[20:23] offset:36864
	s_waitcnt vmcnt(9)
	ds_write_b128 v42, v[24:27]
	s_waitcnt vmcnt(8)
	ds_write_b128 v42, v[28:31] offset:36864
	v_mov_b32_e32 v0, 0
	v_lshl_add_u64 v[170:171], s[10:11], 0, v[52:53]
	v_lshl_add_u64 v[172:173], s[10:11], 0, v[46:47]
	v_lshl_add_u64 v[174:175], s[10:11], 0, v[34:35]
	s_mov_b32 s9, 0
	s_mov_b64 s[10:11], 0
	v_mov_b32_e32 v1, v0
	v_mov_b32_e32 v2, v0
	v_mov_b32_e32 v3, v0
	v_mov_b32_e32 v4, v0
	v_mov_b32_e32 v5, v0
	v_mov_b32_e32 v6, v0
	v_mov_b32_e32 v7, v0
	v_mov_b32_e32 v8, v0
	v_mov_b32_e32 v9, v0
	v_mov_b32_e32 v10, v0
	v_mov_b32_e32 v11, v0
	v_mov_b32_e32 v12, v0
	v_mov_b32_e32 v13, v0
	v_mov_b32_e32 v14, v0
	v_mov_b32_e32 v15, v0
	v_mov_b32_e32 v32, v0
	v_mov_b32_e32 v33, v0
	v_mov_b32_e32 v34, v0
	v_mov_b32_e32 v35, v0
	v_mov_b32_e32 v36, v0
	v_mov_b32_e32 v37, v0
	v_mov_b32_e32 v38, v0
	v_mov_b32_e32 v39, v0
	v_mov_b32_e32 v40, v0
	v_mov_b32_e32 v41, v0
	v_mov_b32_e32 v42, v0
	v_mov_b32_e32 v43, v0
	v_mov_b32_e32 v44, v0
	v_mov_b32_e32 v45, v0
	v_mov_b32_e32 v46, v0
	v_mov_b32_e32 v47, v0
	v_mov_b32_e32 v64, v0
	v_mov_b32_e32 v65, v0
	v_mov_b32_e32 v66, v0
	v_mov_b32_e32 v67, v0
	v_mov_b32_e32 v68, v0
	v_mov_b32_e32 v69, v0
	v_mov_b32_e32 v70, v0
	v_mov_b32_e32 v71, v0
	v_mov_b32_e32 v72, v0
	v_mov_b32_e32 v73, v0
	v_mov_b32_e32 v74, v0
	v_mov_b32_e32 v75, v0
	v_mov_b32_e32 v76, v0
	v_mov_b32_e32 v77, v0
	v_mov_b32_e32 v78, v0
	v_mov_b32_e32 v79, v0
	v_mov_b32_e32 v96, v0
	v_mov_b32_e32 v97, v0
	v_mov_b32_e32 v98, v0
	v_mov_b32_e32 v99, v0
	v_mov_b32_e32 v100, v0
	v_mov_b32_e32 v101, v0
	v_mov_b32_e32 v102, v0
	v_mov_b32_e32 v103, v0
	v_mov_b32_e32 v104, v0
	v_mov_b32_e32 v105, v0
	v_mov_b32_e32 v106, v0
	v_mov_b32_e32 v107, v0
	v_mov_b32_e32 v108, v0
	v_mov_b32_e32 v109, v0
	v_mov_b32_e32 v110, v0
	v_mov_b32_e32 v111, v0
	v_mov_b32_e32 v16, v0
; template <bool AT>
; DI void gemm_main(f32x16 (&acc)[2][4], const u16* __restrict__ R, int ldr, const u16* __restrict__ Cm, int ldc,
;                   const u16* __restrict__ RT, int ldrt, int K, char* smem, int tid) {
;     ...
;   for (int kt = -1; kt < nk; ++kt) {
;     if (kt + 1 < nk) {
;       const int ks1 = kt + 1;
;       u16* Rs = S0 + (ks1 & 1) * STG;
;       u16* Cs = Rs + 256 * 72;
; #pragma unroll
;       for (int i = 0; i < 4; ++i) {
;         const int cid = tid + NT * i;
;         const int row = cid >> 3, kc = cid & 7;
;         if (AT && ks1 < 8) {
;           const int kr = cid >> 5, tc = cid & 31;
;           *(u32x4*)(Rs + kr * 264 + tc * 8) = rr[i];
;         } else {
;           *(u32x4*)(Rs + row * 72 + kc * 8) = rr[i];
;         }
;         *(u32x4*)(Cs + row * 72 + kc * 8) = cr[i];
;       }
;     }
;     if (kt + 2 < nk) {
;       const int kn = kt + 2;
; #pragma unroll
;       for (int i = 0; i < 4; ++i) {
;         const int cid = tid + NT * i;
;         const int row = cid >> 3, kc = cid & 7;
;         if (AT && kn < 8) {
;           const int kr = cid >> 5, tc = cid & 31;
;           rr[i] = *(const u32x4*)(RT + (size_t)(kn * 64 + kr) * ldrt + tc * 8);
;         } else {
;           rr[i] = *(const u32x4*)(R + (size_t)row * ldr + kn * 64 + kc * 8);
;         }
;         cr[i] = *(const u32x4*)(Cm + (size_t)row * ldc + kn * 64 + kc * 8);
;       }
;     }
;     __builtin_amdgcn_sched_barrier(0x38F);
;     if (kt >= 0) {
;       const u16* Rs = S0 + (kt & 1) * STG;
;       const u16* Cs = Rs + 256 * 72;
;       const u16* RTs = Rs;
; #pragma unroll
;       for (int ks = 0; ks < 4; ++ks) {
;         bf16x8 rf[2];
; #pragma unroll
;         for (int rb = 0; rb < 2; ++rb) {
;           if (AT && kt < 8) {
;             const u16* src = RTs + (16 * ks + 8 * g) * 264 + 64 * wr + 32 * rb + li;
;             bf16x8 t;
; #pragma unroll
;             for (int j = 0; j < 8; ++j) t[j] = (short)src[j * 264];
;             rf[rb] = t;
;           } else {
;             rf[rb] = *(const bf16x8*)(Rs + (64 * wr + 32 * rb + li) * 72 + 16 * ks + 8 * g);
;           }
;         }
; #pragma unroll
;         for (int cb = 0; cb < 4; ++cb) {
;           const bf16x8 cfv = *(const bf16x8*)(Cs + (128 * wc + 32 * cb + li) * 72 + 16 * ks + 8 * g);
; #pragma unroll
;           for (int rb = 0; rb < 2; ++rb) acc[rb][cb] = MFMA(rf[rb], cfv, acc[rb][cb]);
	v_mov_b32_e32 v17, v0
	v_mov_b32_e32 v18, v0
	v_mov_b32_e32 v19, v0
	v_mov_b32_e32 v20, v0
	v_mov_b32_e32 v21, v0
	v_mov_b32_e32 v22, v0
	v_mov_b32_e32 v23, v0
	v_mov_b32_e32 v24, v0
	v_mov_b32_e32 v25, v0
	v_mov_b32_e32 v26, v0
	v_mov_b32_e32 v27, v0
	v_mov_b32_e32 v28, v0
	v_mov_b32_e32 v29, v0
	v_mov_b32_e32 v30, v0
	v_mov_b32_e32 v31, v0
	v_mov_b32_e32 v48, v0
	v_mov_b32_e32 v49, v0
	v_mov_b32_e32 v50, v0
	v_mov_b32_e32 v51, v0
	v_mov_b32_e32 v52, v0
	v_mov_b32_e32 v53, v0
	v_mov_b32_e32 v54, v0
	v_mov_b32_e32 v55, v0
	v_mov_b32_e32 v56, v0
	v_mov_b32_e32 v57, v0
	v_mov_b32_e32 v58, v0
	v_mov_b32_e32 v59, v0
	v_mov_b32_e32 v60, v0
	v_mov_b32_e32 v61, v0
	v_mov_b32_e32 v62, v0
	v_mov_b32_e32 v63, v0
	v_mov_b32_e32 v80, v0
	v_mov_b32_e32 v81, v0
	v_mov_b32_e32 v82, v0
	v_mov_b32_e32 v83, v0
	v_mov_b32_e32 v84, v0
	v_mov_b32_e32 v85, v0
	v_mov_b32_e32 v86, v0
	v_mov_b32_e32 v87, v0
	v_mov_b32_e32 v88, v0
	v_mov_b32_e32 v89, v0
	v_mov_b32_e32 v90, v0
	v_mov_b32_e32 v91, v0
	v_mov_b32_e32 v92, v0
	v_mov_b32_e32 v93, v0
	v_mov_b32_e32 v94, v0
	v_mov_b32_e32 v95, v0
	v_mov_b32_e32 v112, v0
	v_mov_b32_e32 v113, v0
	v_mov_b32_e32 v114, v0
	v_mov_b32_e32 v115, v0
	v_mov_b32_e32 v116, v0
	v_mov_b32_e32 v117, v0
	v_mov_b32_e32 v118, v0
	v_mov_b32_e32 v119, v0
	v_mov_b32_e32 v120, v0
	v_mov_b32_e32 v121, v0
	v_mov_b32_e32 v122, v0
	v_mov_b32_e32 v123, v0
	v_mov_b32_e32 v124, v0
	v_mov_b32_e32 v125, v0
	v_mov_b32_e32 v126, v0
	v_mov_b32_e32 v127, v0
	v_mul_u32_u24_e32 v181, 0x90, v176
	v_add_u32_e32 v187, 0, v179
	s_waitcnt lgkmcnt(0)
	s_barrier
	v_add_u32_e32 v190, v187, v180
	v_add_u32_e32 v191, v187, v181
	v_lshl_add_u32 v196, v184, 1, v186
	v_lshl_add_u32 v197, v185, 1, v186
	v_lshl_add_u32 v249, v183, 1, v186
	v_lshl_add_u32 v250, v182, 1, v186
	v_add_u32_e32 v196, 0x12000, v196
	v_add_u32_e32 v197, 0x12000, v197
	v_add_u32_e32 v249, 0x12000, v249
	v_add_u32_e32 v250, 0x12000, v250
	s_movk_i32 s64, 7
.Lgn_loop:
	ds_read_b128 v[192:195], v190 offset:0
	ds_read_b128 v[220:223], v190 offset:4608
	ds_read_b128 v[232:235], v191 offset:36864
	ds_read_b128 v[236:239], v191 offset:41472
	ds_read_b128 v[240:243], v191 offset:46080
	ds_read_b128 v[244:247], v191 offset:50688
	ds_read_b128 v[224:227], v190 offset:32
	ds_read_b128 v[228:231], v190 offset:4640
	s_waitcnt lgkmcnt(5)
	v_mfma_f32_32x32x16_bf16 v[112:127], v[192:195], v[232:235], v[112:127]
	v_mfma_f32_32x32x16_bf16 v[96:111], v[220:223], v[232:235], v[96:111]
	ds_read_b128 v[232:235], v191 offset:36896
	s_waitcnt vmcnt(0)
	ds_write_b128 v196, v[152:155]
	s_waitcnt lgkmcnt(6)
	v_mfma_f32_32x32x16_bf16 v[80:95], v[192:195], v[236:239], v[80:95]
	v_mfma_f32_32x32x16_bf16 v[64:79], v[220:223], v[236:239], v[64:79]
	ds_read_b128 v[236:239], v191 offset:41504
	ds_write_b128 v196, v[136:139] offset:36864
	s_waitcnt lgkmcnt(7)
	v_mfma_f32_32x32x16_bf16 v[48:63], v[192:195], v[240:243], v[48:63]
	v_mfma_f32_32x32x16_bf16 v[32:47], v[220:223], v[240:243], v[32:47]
	ds_read_b128 v[240:243], v191 offset:46112
	ds_write_b128 v197, v[148:151]
	s_waitcnt lgkmcnt(8)
	v_mfma_f32_32x32x16_bf16 v[16:31], v[192:195], v[244:247], v[16:31]
	v_mfma_f32_32x32x16_bf16 v[0:15], v[220:223], v[244:247], v[0:15]
	ds_read_b128 v[244:247], v191 offset:50720
	ds_write_b128 v197, v[132:135] offset:36864
	ds_read_b128 v[192:195], v190 offset:64
	ds_read_b128 v[220:223], v190 offset:4672
	s_waitcnt lgkmcnt(9)
	v_mfma_f32_32x32x16_bf16 v[112:127], v[224:227], v[232:235], v[112:127]
	v_mfma_f32_32x32x16_bf16 v[96:111], v[228:231], v[232:235], v[96:111]
	ds_read_b128 v[232:235], v191 offset:36928
	ds_write_b128 v249, v[144:147]
	s_waitcnt lgkmcnt(9)
	v_mfma_f32_32x32x16_bf16 v[80:95], v[224:227], v[236:239], v[80:95]
	v_mfma_f32_32x32x16_bf16 v[64:79], v[228:231], v[236:239], v[64:79]
	ds_read_b128 v[236:239], v191 offset:41536
	ds_write_b128 v249, v[128:131] offset:36864
	s_waitcnt lgkmcnt(9)
	v_mfma_f32_32x32x16_bf16 v[48:63], v[224:227], v[240:243], v[48:63]
	v_mfma_f32_32x32x16_bf16 v[32:47], v[228:231], v[240:243], v[32:47]
	ds_read_b128 v[240:243], v191 offset:46144
	ds_write_b128 v250, v[140:143]
	s_waitcnt lgkmcnt(9)
	v_mfma_f32_32x32x16_bf16 v[16:31], v[224:227], v[244:247], v[16:31]
	v_mfma_f32_32x32x16_bf16 v[0:15], v[228:231], v[244:247], v[0:15]
	ds_read_b128 v[244:247], v191 offset:50752
	ds_write_b128 v250, v[156:159] offset:36864
	ds_read_b128 v[224:227], v190 offset:96
	ds_read_b128 v[228:231], v190 offset:4704
	s_waitcnt lgkmcnt(9)
	v_mfma_f32_32x32x16_bf16 v[112:127], v[192:195], v[232:235], v[112:127]
	v_mfma_f32_32x32x16_bf16 v[96:111], v[220:223], v[232:235], v[96:111]
	ds_read_b128 v[232:235], v191 offset:36960
	v_subrev_u32_e32 v196, 0x12000, v196
	global_load_dwordx4 v[152:155], v[174:175], off
	v_lshl_add_u64 v[174:175], v[174:175], 0, s[58:59]
	s_waitcnt lgkmcnt(8)
	v_mfma_f32_32x32x16_bf16 v[80:95], v[192:195], v[236:239], v[80:95]
	v_mfma_f32_32x32x16_bf16 v[64:79], v[220:223], v[236:239], v[64:79]
	ds_read_b128 v[236:239], v191 offset:41568
	v_subrev_u32_e32 v197, 0x12000, v197
	global_load_dwordx4 v[136:139], v[166:167], off
	v_lshl_add_u64 v[166:167], v[166:167], 0, s[58:59]
	s_waitcnt lgkmcnt(7)
	v_mfma_f32_32x32x16_bf16 v[48:63], v[192:195], v[240:243], v[48:63]
	v_mfma_f32_32x32x16_bf16 v[32:47], v[220:223], v[240:243], v[32:47]
	ds_read_b128 v[240:243], v191 offset:46176
	v_subrev_u32_e32 v249, 0x12000, v249
	global_load_dwordx4 v[148:151], v[172:173], off
	v_lshl_add_u64 v[172:173], v[172:173], 0, s[58:59]
	s_waitcnt lgkmcnt(6)
	v_mfma_f32_32x32x16_bf16 v[16:31], v[192:195], v[244:247], v[16:31]
	v_mfma_f32_32x32x16_bf16 v[0:15], v[220:223], v[244:247], v[0:15]
	ds_read_b128 v[244:247], v191 offset:50784
	v_subrev_u32_e32 v250, 0x12000, v250
	global_load_dwordx4 v[132:135], v[164:165], off
	v_lshl_add_u64 v[164:165], v[164:165], 0, s[58:59]
	v_add_u32_e32 v190, 0x12000, v190
	v_add_u32_e32 v191, 0x12000, v191
	s_waitcnt lgkmcnt(3)
	v_mfma_f32_32x32x16_bf16 v[112:127], v[224:227], v[232:235], v[112:127]
	v_mfma_f32_32x32x16_bf16 v[96:111], v[228:231], v[232:235], v[96:111]
	global_load_dwordx4 v[144:147], v[170:171], off
	v_lshl_add_u64 v[170:171], v[170:171], 0, s[58:59]
	s_waitcnt lgkmcnt(2)
	v_mfma_f32_32x32x16_bf16 v[80:95], v[224:227], v[236:239], v[80:95]
	v_mfma_f32_32x32x16_bf16 v[64:79], v[228:231], v[236:239], v[64:79]
	global_load_dwordx4 v[128:131], v[162:163], off
	v_lshl_add_u64 v[162:163], v[162:163], 0, s[58:59]
	s_waitcnt lgkmcnt(1)
	v_mfma_f32_32x32x16_bf16 v[48:63], v[224:227], v[240:243], v[48:63]
	v_mfma_f32_32x32x16_bf16 v[32:47], v[228:231], v[240:243], v[32:47]
	global_load_dwordx4 v[140:143], v[168:169], off
	v_lshl_add_u64 v[168:169], v[168:169], 0, s[58:59]
	s_waitcnt lgkmcnt(0)
	v_mfma_f32_32x32x16_bf16 v[16:31], v[224:227], v[244:247], v[16:31]
	v_mfma_f32_32x32x16_bf16 v[0:15], v[228:231], v[244:247], v[0:15]
	global_load_dwordx4 v[156:159], v[160:161], off
	v_lshl_add_u64 v[160:161], v[160:161], 0, s[58:59]
	s_waitcnt lgkmcnt(0)
	s_barrier
; template <bool AT>
; DI void gemm_main(f32x16 (&acc)[2][4], const u16* __restrict__ R, int ldr, const u16* __restrict__ Cm, int ldc,
;                   const u16* __restrict__ RT, int ldrt, int K, char* smem, int tid) {
;     ...
;   for (int kt = -1; kt < nk; ++kt) {
;     if (kt + 1 < nk) {
;       const int ks1 = kt + 1;
;       u16* Rs = S0 + (ks1 & 1) * STG;
;       u16* Cs = Rs + 256 * 72;
; #pragma unroll
;       for (int i = 0; i < 4; ++i) {
;         const int cid = tid + NT * i;
;         const int row = cid >> 3, kc = cid & 7;
;         if (AT && ks1 < 8) {
;           const int kr = cid >> 5, tc = cid & 31;
;           *(u32x4*)(Rs + kr * 264 + tc * 8) = rr[i];
;         } else {
;           *(u32x4*)(Rs + row * 72 + kc * 8) = rr[i];
;         }
;         *(u32x4*)(Cs + row * 72 + kc * 8) = cr[i];
;       }
;     }
;     if (kt + 2 < nk) {
;       const int kn = kt + 2;
; #pragma unroll
;       for (int i = 0; i < 4; ++i) {
;         const int cid = tid + NT * i;
;         const int row = cid >> 3, kc = cid & 7;
;         if (AT && kn < 8) {
;           const int kr = cid >> 5, tc = cid & 31;
;           rr[i] = *(const u32x4*)(RT + (size_t)(kn * 64 + kr) * ldrt + tc * 8);
;         } else {
;           rr[i] = *(const u32x4*)(R + (size_t)row * ldr + kn * 64 + kc * 8);
;         }
;         cr[i] = *(const u32x4*)(Cm + (size_t)row * ldc + kn * 64 + kc * 8);
;       }
;     }
;     __builtin_amdgcn_sched_barrier(0x38F);
;     if (kt >= 0) {
;       const u16* Rs = S0 + (kt & 1) * STG;
;       const u16* Cs = Rs + 256 * 72;
;       const u16* RTs = Rs;
; #pragma unroll
;       for (int ks = 0; ks < 4; ++ks) {
;         bf16x8 rf[2];
; #pragma unroll
;         for (int rb = 0; rb < 2; ++rb) {
;           if (AT && kt < 8) {
;             const u16* src = RTs + (16 * ks + 8 * g) * 264 + 64 * wr + 32 * rb + li;
;             bf16x8 t;
; #pragma unroll
;             for (int j = 0; j < 8; ++j) t[j] = (short)src[j * 264];
;             rf[rb] = t;
;           } else {
;             rf[rb] = *(const bf16x8*)(Rs + (64 * wr + 32 * rb + li) * 72 + 16 * ks + 8 * g);
;           }
;         }
; #pragma unroll
;         for (int cb = 0; cb < 4; ++cb) {
;           const bf16x8 cfv = *(const bf16x8*)(Cs + (128 * wc + 32 * cb + li) * 72 + 16 * ks + 8 * g);
; #pragma unroll
;           for (int rb = 0; rb < 2; ++rb) acc[rb][cb] = MFMA(rf[rb], cfv, acc[rb][cb]);
	ds_read_b128 v[192:195], v190 offset:0
	ds_read_b128 v[220:223], v190 offset:4608
	ds_read_b128 v[232:235], v191 offset:36864
	ds_read_b128 v[236:239], v191 offset:41472
	ds_read_b128 v[240:243], v191 offset:46080
	ds_read_b128 v[244:247], v191 offset:50688
	ds_read_b128 v[224:227], v190 offset:32
	ds_read_b128 v[228:231], v190 offset:4640
	s_waitcnt lgkmcnt(5)
	v_mfma_f32_32x32x16_bf16 v[112:127], v[192:195], v[232:235], v[112:127]
	v_mfma_f32_32x32x16_bf16 v[96:111], v[220:223], v[232:235], v[96:111]
	ds_read_b128 v[232:235], v191 offset:36896
	s_waitcnt vmcnt(0)
	ds_write_b128 v196, v[152:155]
	s_waitcnt lgkmcnt(6)
	v_mfma_f32_32x32x16_bf16 v[80:95], v[192:195], v[236:239], v[80:95]
	v_mfma_f32_32x32x16_bf16 v[64:79], v[220:223], v[236:239], v[64:79]
	ds_read_b128 v[236:239], v191 offset:41504
	ds_write_b128 v196, v[136:139] offset:36864
	s_waitcnt lgkmcnt(7)
	v_mfma_f32_32x32x16_bf16 v[48:63], v[192:195], v[240:243], v[48:63]
	v_mfma_f32_32x32x16_bf16 v[32:47], v[220:223], v[240:243], v[32:47]
	ds_read_b128 v[240:243], v191 offset:46112
	ds_write_b128 v197, v[148:151]
	s_waitcnt lgkmcnt(8)
	v_mfma_f32_32x32x16_bf16 v[16:31], v[192:195], v[244:247], v[16:31]
	v_mfma_f32_32x32x16_bf16 v[0:15], v[220:223], v[244:247], v[0:15]
	ds_read_b128 v[244:247], v191 offset:50720
	ds_write_b128 v197, v[132:135] offset:36864
	ds_read_b128 v[192:195], v190 offset:64
	ds_read_b128 v[220:223], v190 offset:4672
	s_waitcnt lgkmcnt(9)
	v_mfma_f32_32x32x16_bf16 v[112:127], v[224:227], v[232:235], v[112:127]
	v_mfma_f32_32x32x16_bf16 v[96:111], v[228:231], v[232:235], v[96:111]
	ds_read_b128 v[232:235], v191 offset:36928
	ds_write_b128 v249, v[144:147]
	s_waitcnt lgkmcnt(9)
	v_mfma_f32_32x32x16_bf16 v[80:95], v[224:227], v[236:239], v[80:95]
	v_mfma_f32_32x32x16_bf16 v[64:79], v[228:231], v[236:239], v[64:79]
	ds_read_b128 v[236:239], v191 offset:41536
	ds_write_b128 v249, v[128:131] offset:36864
	s_waitcnt lgkmcnt(9)
	v_mfma_f32_32x32x16_bf16 v[48:63], v[224:227], v[240:243], v[48:63]
	v_mfma_f32_32x32x16_bf16 v[32:47], v[228:231], v[240:243], v[32:47]
	ds_read_b128 v[240:243], v191 offset:46144
	ds_write_b128 v250, v[140:143]
	s_waitcnt lgkmcnt(9)
	v_mfma_f32_32x32x16_bf16 v[16:31], v[224:227], v[244:247], v[16:31]
	v_mfma_f32_32x32x16_bf16 v[0:15], v[228:231], v[244:247], v[0:15]
	ds_read_b128 v[244:247], v191 offset:50752
	ds_write_b128 v250, v[156:159] offset:36864
	ds_read_b128 v[224:227], v190 offset:96
	ds_read_b128 v[228:231], v190 offset:4704
	s_waitcnt lgkmcnt(9)
	v_mfma_f32_32x32x16_bf16 v[112:127], v[192:195], v[232:235], v[112:127]
	v_mfma_f32_32x32x16_bf16 v[96:111], v[220:223], v[232:235], v[96:111]
	ds_read_b128 v[232:235], v191 offset:36960
	v_add_u32_e32 v196, 0x12000, v196
	global_load_dwordx4 v[152:155], v[174:175], off
	v_lshl_add_u64 v[174:175], v[174:175], 0, s[58:59]
	s_waitcnt lgkmcnt(8)
	v_mfma_f32_32x32x16_bf16 v[80:95], v[192:195], v[236:239], v[80:95]
	v_mfma_f32_32x32x16_bf16 v[64:79], v[220:223], v[236:239], v[64:79]
	ds_read_b128 v[236:239], v191 offset:41568
	v_add_u32_e32 v197, 0x12000, v197
	global_load_dwordx4 v[136:139], v[166:167], off
	v_lshl_add_u64 v[166:167], v[166:167], 0, s[58:59]
	s_waitcnt lgkmcnt(7)
	v_mfma_f32_32x32x16_bf16 v[48:63], v[192:195], v[240:243], v[48:63]
	v_mfma_f32_32x32x16_bf16 v[32:47], v[220:223], v[240:243], v[32:47]
	ds_read_b128 v[240:243], v191 offset:46176
	v_add_u32_e32 v249, 0x12000, v249
	global_load_dwordx4 v[148:151], v[172:173], off
	v_lshl_add_u64 v[172:173], v[172:173], 0, s[58:59]
	s_waitcnt lgkmcnt(6)
	v_mfma_f32_32x32x16_bf16 v[16:31], v[192:195], v[244:247], v[16:31]
	v_mfma_f32_32x32x16_bf16 v[0:15], v[220:223], v[244:247], v[0:15]
	ds_read_b128 v[244:247], v191 offset:50784
	v_add_u32_e32 v250, 0x12000, v250
	global_load_dwordx4 v[132:135], v[164:165], off
	v_lshl_add_u64 v[164:165], v[164:165], 0, s[58:59]
	v_subrev_u32_e32 v190, 0x12000, v190
	v_subrev_u32_e32 v191, 0x12000, v191
	s_waitcnt lgkmcnt(3)
	v_mfma_f32_32x32x16_bf16 v[112:127], v[224:227], v[232:235], v[112:127]
	v_mfma_f32_32x32x16_bf16 v[96:111], v[228:231], v[232:235], v[96:111]
	global_load_dwordx4 v[144:147], v[170:171], off
	v_lshl_add_u64 v[170:171], v[170:171], 0, s[58:59]
	s_waitcnt lgkmcnt(2)
	v_mfma_f32_32x32x16_bf16 v[80:95], v[224:227], v[236:239], v[80:95]
	v_mfma_f32_32x32x16_bf16 v[64:79], v[228:231], v[236:239], v[64:79]
	global_load_dwordx4 v[128:131], v[162:163], off
	v_lshl_add_u64 v[162:163], v[162:163], 0, s[58:59]
	s_waitcnt lgkmcnt(1)
	v_mfma_f32_32x32x16_bf16 v[48:63], v[224:227], v[240:243], v[48:63]
	v_mfma_f32_32x32x16_bf16 v[32:47], v[228:231], v[240:243], v[32:47]
	global_load_dwordx4 v[140:143], v[168:169], off
	v_lshl_add_u64 v[168:169], v[168:169], 0, s[58:59]
	s_waitcnt lgkmcnt(0)
	v_mfma_f32_32x32x16_bf16 v[16:31], v[224:227], v[244:247], v[16:31]
	v_mfma_f32_32x32x16_bf16 v[0:15], v[228:231], v[244:247], v[0:15]
	global_load_dwordx4 v[156:159], v[160:161], off
	v_lshl_add_u64 v[160:161], v[160:161], 0, s[58:59]
	s_waitcnt lgkmcnt(0)
	s_barrier
	s_add_i32 s64, s64, -1
	s_cmp_lg_u32 s64, 0
	s_cbranch_scc1 .Lgn_loop
; template <bool AT>
; DI void gemm_main(f32x16 (&acc)[2][4], const u16* __restrict__ R, int ldr, const u16* __restrict__ Cm, int ldc,
;                   const u16* __restrict__ RT, int ldrt, int K, char* smem, int tid) {
;     ...
;   for (int kt = -1; kt < nk; ++kt) {
;     if (kt + 1 < nk) {
;       const int ks1 = kt + 1;
;       u16* Rs = S0 + (ks1 & 1) * STG;
;       u16* Cs = Rs + 256 * 72;
; #pragma unroll
;       for (int i = 0; i < 4; ++i) {
;         const int cid = tid + NT * i;
;         const int row = cid >> 3, kc = cid & 7;
;         if (AT && ks1 < 8) {
;           const int kr = cid >> 5, tc = cid & 31;
;           *(u32x4*)(Rs + kr * 264 + tc * 8) = rr[i];
;         } else {
;           *(u32x4*)(Rs + row * 72 + kc * 8) = rr[i];
;         }
;         *(u32x4*)(Cs + row * 72 + kc * 8) = cr[i];
;       }
;     }
;     if (kt + 2 < nk) {
;       const int kn = kt + 2;
; #pragma unroll
;       for (int i = 0; i < 4; ++i) {
;         const int cid = tid + NT * i;
;         const int row = cid >> 3, kc = cid & 7;
;         if (AT && kn < 8) {
;           const int kr = cid >> 5, tc = cid & 31;
;           rr[i] = *(const u32x4*)(RT + (size_t)(kn * 64 + kr) * ldrt + tc * 8);
;         } else {
;           rr[i] = *(const u32x4*)(R + (size_t)row * ldr + kn * 64 + kc * 8);
;         }
;         cr[i] = *(const u32x4*)(Cm + (size_t)row * ldc + kn * 64 + kc * 8);
;       }
;     }
;     __builtin_amdgcn_sched_barrier(0x38F);
;     if (kt >= 0) {
;       const u16* Rs = S0 + (kt & 1) * STG;
;       const u16* Cs = Rs + 256 * 72;
;       const u16* RTs = Rs;
; #pragma unroll
;       for (int ks = 0; ks < 4; ++ks) {
;         bf16x8 rf[2];
; #pragma unroll
;         for (int rb = 0; rb < 2; ++rb) {
;           if (AT && kt < 8) {
;             const u16* src = RTs + (16 * ks + 8 * g) * 264 + 64 * wr + 32 * rb + li;
;             bf16x8 t;
; #pragma unroll
;             for (int j = 0; j < 8; ++j) t[j] = (short)src[j * 264];
;             rf[rb] = t;
;           } else {
;             rf[rb] = *(const bf16x8*)(Rs + (64 * wr + 32 * rb + li) * 72 + 16 * ks + 8 * g);
;           }
;         }
; #pragma unroll
;         for (int cb = 0; cb < 4; ++cb) {
;           const bf16x8 cfv = *(const bf16x8*)(Cs + (128 * wc + 32 * cb + li) * 72 + 16 * ks + 8 * g);
; #pragma unroll
;           for (int rb = 0; rb < 2; ++rb) acc[rb][cb] = MFMA(rf[rb], cfv, acc[rb][cb]);
	s_add_i32 s9, 0, 0x12000
	v_add_u32_e32 v160, s9, v188
	v_lshlrev_b32_e32 v162, 1, v184
	v_add_u32_e32 v161, s90, v188
	v_add_u32_e32 v163, v160, v162
	s_waitcnt vmcnt(7)
	ds_write_b128 v163, v[152:155]
	v_add_u32_e32 v152, v161, v162
	s_waitcnt vmcnt(6)
	ds_write_b128 v152, v[136:139]
	v_lshlrev_b32_e32 v136, 1, v185
	v_add_u32_e32 v137, v160, v136
	v_add_u32_e32 v136, v161, v136
	s_waitcnt vmcnt(4)
	ds_write_b128 v136, v[132:135]
	v_lshlrev_b32_e32 v132, 1, v183
	v_add_u32_e32 v133, v160, v132
	v_add_u32_e32 v132, v161, v132
	ds_write_b128 v137, v[148:151]
	s_waitcnt vmcnt(2)
	ds_write_b128 v132, v[128:131]
	v_lshlrev_b32_e32 v128, 1, v182
	v_add_u32_e32 v129, v160, v128
	v_add_u32_e32 v128, v161, v128
	ds_write_b128 v133, v[144:147]
	s_waitcnt vmcnt(1)
	ds_write_b128 v129, v[140:143]
	s_waitcnt vmcnt(0)
	ds_write_b128 v128, v[156:159]
	v_add_u32_e32 v148, v187, v180
	ds_read_b128 v[128:131], v148 offset:4608
	v_add_u32_e32 v149, v187, v181
	ds_read_b128 v[132:135], v148
	ds_read_b128 v[136:139], v148 offset:32
	ds_read_b128 v[140:143], v149 offset:36864
	ds_read_b128 v[144:147], v149 offset:36896
	s_waitcnt lgkmcnt(1)
	v_mfma_f32_32x32x16_bf16 v[112:127], v[132:135], v[140:143], v[112:127]
	v_mov_b32_e32 v162, s56
	v_mfma_f32_32x32x16_bf16 v[96:111], v[128:131], v[140:143], v[96:111]
	ds_read_b128 v[140:143], v149 offset:41472
	s_waitcnt lgkmcnt(0)
	v_mfma_f32_32x32x16_bf16 v[80:95], v[132:135], v[140:143], v[80:95]
	v_mfma_f32_32x32x16_bf16 v[64:79], v[128:131], v[140:143], v[64:79]
	ds_read_b128 v[140:143], v149 offset:46080
	s_waitcnt lgkmcnt(0)
	v_mfma_f32_32x32x16_bf16 v[48:63], v[132:135], v[140:143], v[48:63]
	v_mfma_f32_32x32x16_bf16 v[32:47], v[128:131], v[140:143], v[32:47]
	ds_read_b128 v[140:143], v149 offset:50688
	s_waitcnt lgkmcnt(0)
	v_mfma_f32_32x32x16_bf16 v[0:15], v[128:131], v[140:143], v[0:15]
	ds_read_b128 v[128:131], v148 offset:4640
	v_mfma_f32_32x32x16_bf16 v[16:31], v[132:135], v[140:143], v[16:31]
	ds_read_b128 v[132:135], v149 offset:41504
	s_waitcnt lgkmcnt(0)
	v_mfma_f32_32x32x16_bf16 v[80:95], v[136:139], v[132:135], v[80:95]
	v_mfma_f32_32x32x16_bf16 v[64:79], v[128:131], v[132:135], v[64:79]
	ds_read_b128 v[132:135], v149 offset:46112
	s_waitcnt lgkmcnt(0)
	v_mfma_f32_32x32x16_bf16 v[48:63], v[136:139], v[132:135], v[48:63]
	v_mfma_f32_32x32x16_bf16 v[32:47], v[128:131], v[132:135], v[32:47]
	ds_read_b128 v[132:135], v149 offset:50720
	v_mfma_f32_32x32x16_bf16 v[112:127], v[136:139], v[144:147], v[112:127]
	v_mfma_f32_32x32x16_bf16 v[96:111], v[128:131], v[144:147], v[96:111]
	s_waitcnt lgkmcnt(0)
	v_mfma_f32_32x32x16_bf16 v[16:31], v[136:139], v[132:135], v[16:31]
	v_mfma_f32_32x32x16_bf16 v[0:15], v[128:131], v[132:135], v[0:15]
	ds_read_b128 v[128:131], v148 offset:64
	ds_read_b128 v[132:135], v148 offset:4672
	ds_read_b128 v[136:139], v149 offset:36928
	s_waitcnt lgkmcnt(0)
	v_mfma_f32_32x32x16_bf16 v[112:127], v[128:131], v[136:139], v[112:127]
	v_mfma_f32_32x32x16_bf16 v[96:111], v[132:135], v[136:139], v[96:111]
	ds_read_b128 v[136:139], v149 offset:41536
	s_waitcnt lgkmcnt(0)
	v_mfma_f32_32x32x16_bf16 v[80:95], v[128:131], v[136:139], v[80:95]
	v_mfma_f32_32x32x16_bf16 v[64:79], v[132:135], v[136:139], v[64:79]
	ds_read_b128 v[136:139], v149 offset:46144
	s_waitcnt lgkmcnt(0)
	v_mfma_f32_32x32x16_bf16 v[48:63], v[128:131], v[136:139], v[48:63]
	v_mfma_f32_32x32x16_bf16 v[32:47], v[132:135], v[136:139], v[32:47]
	ds_read_b128 v[136:139], v149 offset:50752
	s_waitcnt lgkmcnt(0)
	v_mfma_f32_32x32x16_bf16 v[16:31], v[128:131], v[136:139], v[16:31]
	v_mfma_f32_32x32x16_bf16 v[0:15], v[132:135], v[136:139], v[0:15]
	ds_read_b128 v[128:131], v148 offset:96
	ds_read_b128 v[132:135], v148 offset:4704
	ds_read_b128 v[136:139], v149 offset:36960
	v_add3_u32 v148, s9, v179, v180
	s_lshl_b32 s9, s75, 4
	s_and_b32 s9, s9, 0x200
	s_add_i32 s9, s8, s9
	s_addk_i32 s9, 0xf400
	s_waitcnt lgkmcnt(0)
	v_mfma_f32_32x32x16_bf16 v[112:127], v[128:131], v[136:139], v[112:127]
	v_mfma_f32_32x32x16_bf16 v[96:111], v[132:135], v[136:139], v[96:111]
	ds_read_b128 v[136:139], v149 offset:41568
	s_waitcnt lgkmcnt(0)
	v_mfma_f32_32x32x16_bf16 v[80:95], v[128:131], v[136:139], v[80:95]
	v_mfma_f32_32x32x16_bf16 v[64:79], v[132:135], v[136:139], v[64:79]
	ds_read_b128 v[136:139], v149 offset:46176
	s_waitcnt lgkmcnt(0)
	v_mfma_f32_32x32x16_bf16 v[48:63], v[128:131], v[136:139], v[48:63]
	v_mfma_f32_32x32x16_bf16 v[32:47], v[132:135], v[136:139], v[32:47]
	ds_read_b128 v[136:139], v149 offset:50784
	s_waitcnt lgkmcnt(0)
	s_barrier
; #define MFMA(a, b, c) __builtin_amdgcn_mfma_f32_32x32x16_bf16((a), (b), (c), 0, 0, 0)
; DI u16 f2bf(float a) { return (u16)(pack2(a, 0.f) & 0xffffu); }
; DI int crow(int reg, int g) { return (reg & 3) + 8 * (reg >> 2) + 4 * g; }
; template <bool AT>
; DI void gemm_main(f32x16 (&acc)[2][4], const u16* __restrict__ R, int ldr, const u16* __restrict__ Cm, int ldc,
;                   const u16* __restrict__ RT, int ldrt, int K, char* smem, int tid) {
;     ...
;     if (kt >= 0) {
;       const u16* Rs = S0 + (kt & 1) * STG;
;       const u16* Cs = Rs + 256 * 72;
;       const u16* RTs = Rs;
; #pragma unroll
;       for (int ks = 0; ks < 4; ++ks) {
;         bf16x8 rf[2];
; #pragma unroll
;         for (int rb = 0; rb < 2; ++rb) {
;           if (AT && kt < 8) {
;             const u16* src = RTs + (16 * ks + 8 * g) * 264 + 64 * wr + 32 * rb + li;
;             bf16x8 t;
; #pragma unroll
;             for (int j = 0; j < 8; ++j) t[j] = (short)src[j * 264];
;             rf[rb] = t;
;           } else {
;             rf[rb] = *(const bf16x8*)(Rs + (64 * wr + 32 * rb + li) * 72 + 16 * ks + 8 * g);
;           }
;         }
; #pragma unroll
;         for (int cb = 0; cb < 4; ++cb) {
;           const bf16x8 cfv = *(const bf16x8*)(Cs + (128 * wc + 32 * cb + li) * 72 + 16 * ks + 8 * g);
; #pragma unroll
;           for (int rb = 0; rb < 2; ++rb) acc[rb][cb] = MFMA(rf[rb], cfv, acc[rb][cb]);
;         }
;       }
;     }
;     __syncthreads();
; template <bool TR>
; DI void gemm_in_tile(const P& p, int l, int id, char* smem) {
;     ...
;   if (tr) {
;     const bool hy = nt < 8;
; #pragma unroll
;     for (int cb = 0; cb < 4; ++cb) {
;       asm volatile("" ::: "memory");
;       const int tl = 128 * wc + 32 * cb + li;
;       const int tok = m0 + tl;
;       const float rs = rs_s[tl];
;       u16* dst = hy ? (p.hyT + (size_t)(n0 + 64 * wr) * HYP + tok)
;                     : (p.VT + (size_t)((tok >> 13) * 512 + (n0 - 3072) + 64 * wr) * VTP + (tok & 8191));
;       const size_t cstride = hy ? (size_t)HYP : (size_t)VTP;
; #pragma unroll
;       for (int rb = 0; rb < 2; ++rb) {
; #pragma unroll
;         for (int reg = 0; reg < 16; ++reg) {
;           const int cl = 32 * rb + crow(reg, g);
;           dst[(size_t)cl * cstride] = f2bf(acc[rb][cb][reg] * rs);
	v_add3_u32 v149, s90, v179, v181
	v_mfma_f32_32x32x16_bf16 v[16:31], v[128:131], v[136:139], v[16:31]
	ds_read_b128 v[128:131], v148 offset:4608
	v_mfma_f32_32x32x16_bf16 v[0:15], v[132:135], v[136:139], v[0:15]
	ds_read_b128 v[132:135], v148
	ds_read_b128 v[136:139], v148 offset:32
	ds_read_b128 v[140:143], v149
	ds_read_b128 v[144:147], v149 offset:32
	s_waitcnt lgkmcnt(1)
	v_mfma_f32_32x32x16_bf16 v[112:127], v[132:135], v[140:143], v[112:127]
	v_mfma_f32_32x32x16_bf16 v[96:111], v[128:131], v[140:143], v[96:111]
	ds_read_b128 v[140:143], v149 offset:4608
	s_waitcnt lgkmcnt(0)
	v_mfma_f32_32x32x16_bf16 v[80:95], v[132:135], v[140:143], v[80:95]
	v_mfma_f32_32x32x16_bf16 v[64:79], v[128:131], v[140:143], v[64:79]
	ds_read_b128 v[140:143], v149 offset:9216
	s_waitcnt lgkmcnt(0)
	v_mfma_f32_32x32x16_bf16 v[48:63], v[132:135], v[140:143], v[48:63]
	v_mfma_f32_32x32x16_bf16 v[32:47], v[128:131], v[140:143], v[32:47]
	ds_read_b128 v[140:143], v149 offset:13824
	s_waitcnt lgkmcnt(0)
	v_mfma_f32_32x32x16_bf16 v[0:15], v[128:131], v[140:143], v[0:15]
	ds_read_b128 v[128:131], v148 offset:4640
	v_mfma_f32_32x32x16_bf16 v[16:31], v[132:135], v[140:143], v[16:31]
	ds_read_b128 v[132:135], v149 offset:4640
	s_waitcnt lgkmcnt(0)
	v_mfma_f32_32x32x16_bf16 v[80:95], v[136:139], v[132:135], v[80:95]
	v_mfma_f32_32x32x16_bf16 v[64:79], v[128:131], v[132:135], v[64:79]
	ds_read_b128 v[132:135], v149 offset:9248
	s_waitcnt lgkmcnt(0)
	v_mfma_f32_32x32x16_bf16 v[48:63], v[136:139], v[132:135], v[48:63]
	v_mfma_f32_32x32x16_bf16 v[32:47], v[128:131], v[132:135], v[32:47]
	ds_read_b128 v[132:135], v149 offset:13856
	v_mfma_f32_32x32x16_bf16 v[112:127], v[136:139], v[144:147], v[112:127]
	v_mfma_f32_32x32x16_bf16 v[96:111], v[128:131], v[144:147], v[96:111]
	s_waitcnt lgkmcnt(0)
	v_mfma_f32_32x32x16_bf16 v[16:31], v[136:139], v[132:135], v[16:31]
	v_mfma_f32_32x32x16_bf16 v[0:15], v[128:131], v[132:135], v[0:15]
	ds_read_b128 v[128:131], v148 offset:64
	ds_read_b128 v[132:135], v148 offset:4672
	ds_read_b128 v[136:139], v149 offset:64
	s_waitcnt lgkmcnt(0)
	v_mfma_f32_32x32x16_bf16 v[112:127], v[128:131], v[136:139], v[112:127]
	v_mfma_f32_32x32x16_bf16 v[96:111], v[132:135], v[136:139], v[96:111]
	ds_read_b128 v[136:139], v149 offset:4672
	s_waitcnt lgkmcnt(0)
	v_mfma_f32_32x32x16_bf16 v[80:95], v[128:131], v[136:139], v[80:95]
	v_mfma_f32_32x32x16_bf16 v[64:79], v[132:135], v[136:139], v[64:79]
	ds_read_b128 v[136:139], v149 offset:9280
	s_waitcnt lgkmcnt(0)
	v_mfma_f32_32x32x16_bf16 v[48:63], v[128:131], v[136:139], v[48:63]
	v_mfma_f32_32x32x16_bf16 v[32:47], v[132:135], v[136:139], v[32:47]
	ds_read_b128 v[136:139], v149 offset:13888
	s_waitcnt lgkmcnt(0)
	v_mfma_f32_32x32x16_bf16 v[16:31], v[128:131], v[136:139], v[16:31]
	v_mfma_f32_32x32x16_bf16 v[0:15], v[132:135], v[136:139], v[0:15]
	ds_read_b128 v[128:131], v148 offset:96
	ds_read_b128 v[132:135], v148 offset:4704
	ds_read_b128 v[136:139], v149 offset:96
	s_waitcnt lgkmcnt(0)
	v_mfma_f32_32x32x16_bf16 v[112:127], v[128:131], v[136:139], v[112:127]
	v_mfma_f32_32x32x16_bf16 v[96:111], v[132:135], v[136:139], v[96:111]
	ds_read_b128 v[136:139], v149 offset:4704
	s_waitcnt lgkmcnt(0)
	v_mfma_f32_32x32x16_bf16 v[80:95], v[128:131], v[136:139], v[80:95]
	v_mfma_f32_32x32x16_bf16 v[64:79], v[132:135], v[136:139], v[64:79]
	ds_read_b128 v[136:139], v149 offset:9312
	s_waitcnt lgkmcnt(0)
	v_mfma_f32_32x32x16_bf16 v[48:63], v[128:131], v[136:139], v[48:63]
	v_mfma_f32_32x32x16_bf16 v[32:47], v[132:135], v[136:139], v[32:47]
	ds_read_b128 v[136:139], v149 offset:13920
	s_waitcnt lgkmcnt(0)
	s_barrier
	v_mfma_f32_32x32x16_bf16 v[16:31], v[128:131], v[136:139], v[16:31]
	v_lshrrev_b32_e32 v128, 3, v177
	v_and_b32_e32 v163, 4, v128
	v_add_u32_e32 v130, s9, v178
	s_movk_i32 s9, 0x4080
	v_mfma_f32_32x32x16_bf16 v[0:15], v[132:135], v[136:139], v[0:15]
	v_add_u32_e32 v132, s8, v178
	s_add_i32 s8, 0, 0x24000
	v_lshl_add_u32 v128, v176, 2, s8
	ds_read_b32 v164, v128
	v_mov_b64_e32 v[128:129], s[28:29]
	v_mad_i64_i32 v[128:129], s[10:11], v130, s9, v[128:129]
	s_movk_i32 s9, 0x1f9f
	v_or_b32_e32 v133, s56, v176
	v_bitop3_b32 v134, v176, s9, v162 bitop3:0xc8
	v_mov_b64_e32 v[130:131], s[38:39]
	s_and_b64 s[10:11], s[6:7], exec
	s_movk_i32 s9, 0x4040
	v_mad_i64_i32 v[130:131], s[10:11], v132, s67, v[130:131]
	v_cndmask_b32_e64 v132, v134, v133, s[6:7]
	s_cselect_b32 s9, s9, 0x2040
	v_cndmask_b32_e64 v129, v129, v131, s[6:7]
	v_cndmask_b32_e64 v128, v128, v130, s[6:7]
	v_lshlrev_b32_e32 v188, 1, v132
	v_mul_u32_u24_e32 v130, s9, v163
	v_lshl_add_u64 v[138:139], v[128:129], 0, v[188:189]
	s_waitcnt lgkmcnt(0)
; DI u16 f2bf(float a) { return (u16)(pack2(a, 0.f) & 0xffffu); }
; DI int crow(int reg, int g) { return (reg & 3) + 8 * (reg >> 2) + 4 * g; }
; template <bool TR>
; DI void gemm_in_tile(const P& p, int l, int id, char* smem) {
;     ...
;   if (tr) {
;     const bool hy = nt < 8;
; #pragma unroll
;     for (int cb = 0; cb < 4; ++cb) {
;       asm volatile("" ::: "memory");
;       const int tl = 128 * wc + 32 * cb + li;
;       const int tok = m0 + tl;
;       const float rs = rs_s[tl];
;       u16* dst = hy ? (p.hyT + (size_t)(n0 + 64 * wr) * HYP + tok)
;                     : (p.VT + (size_t)((tok >> 13) * 512 + (n0 - 3072) + 64 * wr) * VTP + (tok & 8191));
;       const size_t cstride = hy ? (size_t)HYP : (size_t)VTP;
; #pragma unroll
;       for (int rb = 0; rb < 2; ++rb) {
; #pragma unroll
;         for (int reg = 0; reg < 16; ++reg) {
;           const int cl = 32 * rb + crow(reg, g);
;           dst[(size_t)cl * cstride] = f2bf(acc[rb][cb][reg] * rs);
;         }
;       }
	v_mul_f32_e32 v112, v112, v164
	v_lshlrev_b32_e32 v188, 1, v130
	v_cvt_pk_bf16_f32 v112, v112, s0
	v_lshl_add_u64 v[130:131], v[138:139], 0, v[188:189]
	global_store_short v[130:131], v112, off
	v_or_b32_e32 v112, 1, v163
	v_mul_f32_e32 v113, v113, v164
	v_mul_u32_u24_e32 v112, s9, v112
	v_cvt_pk_bf16_f32 v132, v113, s0
	v_lshlrev_b32_e32 v112, 1, v112
	v_mov_b32_e32 v113, v189
	v_lshl_add_u64 v[130:131], v[138:139], 0, v[112:113]
	global_store_short v[130:131], v132, off
	v_or_b32_e32 v130, 2, v163
	v_mul_u32_u24_e32 v130, s9, v130
	v_mul_f32_e32 v114, v114, v164
	v_lshlrev_b32_e32 v130, 1, v130
	v_mov_b32_e32 v131, v189
	v_cvt_pk_bf16_f32 v114, v114, s0
	v_lshl_add_u64 v[132:133], v[138:139], 0, v[130:131]
	global_store_short v[132:133], v114, off
	v_or_b32_e32 v114, 3, v163
	v_mul_f32_e32 v115, v115, v164
	v_mul_u32_u24_e32 v114, s9, v114
	v_cvt_pk_bf16_f32 v134, v115, s0
	v_lshlrev_b32_e32 v114, 1, v114
	v_mov_b32_e32 v115, v189
	v_lshl_add_u64 v[132:133], v[138:139], 0, v[114:115]
	global_store_short v[132:133], v134, off
	v_or_b32_e32 v132, 8, v163
	v_mul_u32_u24_e32 v132, s9, v132
	v_mul_f32_e32 v116, v116, v164
	v_lshlrev_b32_e32 v132, 1, v132
	v_mov_b32_e32 v133, v189
	v_cvt_pk_bf16_f32 v116, v116, s0
	v_lshl_add_u64 v[134:135], v[138:139], 0, v[132:133]
	global_store_short v[134:135], v116, off
	v_or_b32_e32 v116, 9, v163
	v_mul_f32_e32 v117, v117, v164
	v_mul_u32_u24_e32 v116, s9, v116
	v_cvt_pk_bf16_f32 v136, v117, s0
	v_lshlrev_b32_e32 v116, 1, v116
	v_mov_b32_e32 v117, v189
	v_lshl_add_u64 v[134:135], v[138:139], 0, v[116:117]
	global_store_short v[134:135], v136, off
	v_or_b32_e32 v134, 10, v163
	v_mul_u32_u24_e32 v134, s9, v134
	v_mul_f32_e32 v118, v118, v164
	v_lshlrev_b32_e32 v134, 1, v134
	v_mov_b32_e32 v135, v189
	v_cvt_pk_bf16_f32 v118, v118, s0
	v_lshl_add_u64 v[136:137], v[138:139], 0, v[134:135]
	global_store_short v[136:137], v118, off
	v_or_b32_e32 v118, 11, v163
	v_mul_f32_e32 v119, v119, v164
	v_mul_u32_u24_e32 v118, s9, v118
	v_cvt_pk_bf16_f32 v140, v119, s0
	v_lshlrev_b32_e32 v118, 1, v118
	v_mov_b32_e32 v119, v189
	v_lshl_add_u64 v[136:137], v[138:139], 0, v[118:119]
	global_store_short v[136:137], v140, off
	v_or_b32_e32 v136, 16, v163
	v_mul_u32_u24_e32 v136, s9, v136
	v_mul_f32_e32 v120, v120, v164
	v_lshlrev_b32_e32 v136, 1, v136
	v_mov_b32_e32 v137, v189
	v_cvt_pk_bf16_f32 v120, v120, s0
	v_lshl_add_u64 v[140:141], v[138:139], 0, v[136:137]
	global_store_short v[140:141], v120, off
	v_or_b32_e32 v120, 17, v163
	v_mul_f32_e32 v121, v121, v164
	v_mul_u32_u24_e32 v120, s9, v120
	v_cvt_pk_bf16_f32 v142, v121, s0
	v_lshlrev_b32_e32 v120, 1, v120
	v_mov_b32_e32 v121, v189
	v_lshl_add_u64 v[140:141], v[138:139], 0, v[120:121]
	global_store_short v[140:141], v142, off
	v_or_b32_e32 v140, 18, v163
	v_mul_u32_u24_e32 v140, s9, v140
	v_mul_f32_e32 v122, v122, v164
	v_lshlrev_b32_e32 v140, 1, v140
	v_mov_b32_e32 v141, v189
	v_cvt_pk_bf16_f32 v122, v122, s0
	v_lshl_add_u64 v[142:143], v[138:139], 0, v[140:141]
	global_store_short v[142:143], v122, off
	v_or_b32_e32 v122, 19, v163
	v_mul_f32_e32 v123, v123, v164
	v_mul_u32_u24_e32 v122, s9, v122
	v_cvt_pk_bf16_f32 v144, v123, s0
	v_lshlrev_b32_e32 v122, 1, v122
	v_mov_b32_e32 v123, v189
	v_lshl_add_u64 v[142:143], v[138:139], 0, v[122:123]
	global_store_short v[142:143], v144, off
	v_or_b32_e32 v142, 24, v163
	v_mul_u32_u24_e32 v142, s9, v142
	v_mul_f32_e32 v124, v124, v164
	v_lshlrev_b32_e32 v142, 1, v142
	v_mov_b32_e32 v143, v189
	v_cvt_pk_bf16_f32 v124, v124, s0
	v_lshl_add_u64 v[144:145], v[138:139], 0, v[142:143]
	global_store_short v[144:145], v124, off
	v_or_b32_e32 v124, 25, v163
	v_mul_f32_e32 v125, v125, v164
	v_mul_u32_u24_e32 v124, s9, v124
	v_cvt_pk_bf16_f32 v146, v125, s0
	v_lshlrev_b32_e32 v124, 1, v124
	v_mov_b32_e32 v125, v189
	v_lshl_add_u64 v[144:145], v[138:139], 0, v[124:125]
	global_store_short v[144:145], v146, off
	v_or_b32_e32 v144, 26, v163
	v_mul_u32_u24_e32 v144, s9, v144
	v_mul_f32_e32 v126, v126, v164
	v_lshlrev_b32_e32 v144, 1, v144
	v_mov_b32_e32 v145, v189
	v_cvt_pk_bf16_f32 v126, v126, s0
	v_lshl_add_u64 v[146:147], v[138:139], 0, v[144:145]
	global_store_short v[146:147], v126, off
	v_or_b32_e32 v126, 27, v163
	v_mul_f32_e32 v127, v127, v164
	v_mul_u32_u24_e32 v126, s9, v126
	v_cvt_pk_bf16_f32 v148, v127, s0
	v_lshlrev_b32_e32 v126, 1, v126
	v_mov_b32_e32 v127, v189
	v_lshl_add_u64 v[146:147], v[138:139], 0, v[126:127]
	global_store_short v[146:147], v148, off
	v_or_b32_e32 v146, 32, v163
	v_mul_u32_u24_e32 v146, s9, v146
	v_mul_f32_e32 v96, v96, v164
	v_lshlrev_b32_e32 v146, 1, v146
	v_mov_b32_e32 v147, v189
	v_cvt_pk_bf16_f32 v96, v96, s0
	v_lshl_add_u64 v[148:149], v[138:139], 0, v[146:147]
	global_store_short v[148:149], v96, off
	v_or_b32_e32 v96, 33, v163
	v_mul_f32_e32 v97, v97, v164
	v_mul_u32_u24_e32 v96, s9, v96
	v_cvt_pk_bf16_f32 v150, v97, s0
	v_lshlrev_b32_e32 v96, 1, v96
	v_mov_b32_e32 v97, v189
	v_lshl_add_u64 v[148:149], v[138:139], 0, v[96:97]
	global_store_short v[148:149], v150, off
	v_or_b32_e32 v148, 34, v163
	v_mul_u32_u24_e32 v148, s9, v148
	v_mul_f32_e32 v98, v98, v164
	v_lshlrev_b32_e32 v148, 1, v148
	v_mov_b32_e32 v149, v189
	v_cvt_pk_bf16_f32 v98, v98, s0
	v_lshl_add_u64 v[150:151], v[138:139], 0, v[148:149]
	global_store_short v[150:151], v98, off
	v_or_b32_e32 v98, 35, v163
	v_mul_f32_e32 v99, v99, v164
	v_mul_u32_u24_e32 v98, s9, v98
	v_cvt_pk_bf16_f32 v152, v99, s0
	v_lshlrev_b32_e32 v98, 1, v98
	v_mov_b32_e32 v99, v189
	v_lshl_add_u64 v[150:151], v[138:139], 0, v[98:99]
	global_store_short v[150:151], v152, off
	v_or_b32_e32 v150, 40, v163
	v_mul_u32_u24_e32 v150, s9, v150
	v_mul_f32_e32 v100, v100, v164
; DI u16 f2bf(float a) { return (u16)(pack2(a, 0.f) & 0xffffu); }
; DI int crow(int reg, int g) { return (reg & 3) + 8 * (reg >> 2) + 4 * g; }
; template <bool TR>
; DI void gemm_in_tile(const P& p, int l, int id, char* smem) {
;     ...
;   if (tr) {
;     const bool hy = nt < 8;
; #pragma unroll
;     for (int cb = 0; cb < 4; ++cb) {
;       asm volatile("" ::: "memory");
;       const int tl = 128 * wc + 32 * cb + li;
;       const int tok = m0 + tl;
;       const float rs = rs_s[tl];
;       u16* dst = hy ? (p.hyT + (size_t)(n0 + 64 * wr) * HYP + tok)
;                     : (p.VT + (size_t)((tok >> 13) * 512 + (n0 - 3072) + 64 * wr) * VTP + (tok & 8191));
;       const size_t cstride = hy ? (size_t)HYP : (size_t)VTP;
; #pragma unroll
;       for (int rb = 0; rb < 2; ++rb) {
; #pragma unroll
;         for (int reg = 0; reg < 16; ++reg) {
;           const int cl = 32 * rb + crow(reg, g);
;           dst[(size_t)cl * cstride] = f2bf(acc[rb][cb][reg] * rs);
;         }
;       }
	v_lshlrev_b32_e32 v150, 1, v150
	v_mov_b32_e32 v151, v189
	v_cvt_pk_bf16_f32 v100, v100, s0
	v_lshl_add_u64 v[152:153], v[138:139], 0, v[150:151]
	global_store_short v[152:153], v100, off
	v_or_b32_e32 v100, 41, v163
	v_mul_f32_e32 v101, v101, v164
	v_mul_u32_u24_e32 v100, s9, v100
	v_cvt_pk_bf16_f32 v154, v101, s0
	v_lshlrev_b32_e32 v100, 1, v100
	v_mov_b32_e32 v101, v189
	v_lshl_add_u64 v[152:153], v[138:139], 0, v[100:101]
	global_store_short v[152:153], v154, off
	v_or_b32_e32 v152, 42, v163
	v_mul_u32_u24_e32 v152, s9, v152
	v_mul_f32_e32 v102, v102, v164
	v_lshlrev_b32_e32 v152, 1, v152
	v_mov_b32_e32 v153, v189
	v_cvt_pk_bf16_f32 v102, v102, s0
	v_lshl_add_u64 v[154:155], v[138:139], 0, v[152:153]
	global_store_short v[154:155], v102, off
	v_or_b32_e32 v102, 43, v163
	v_mul_f32_e32 v103, v103, v164
	v_mul_u32_u24_e32 v102, s9, v102
	v_cvt_pk_bf16_f32 v156, v103, s0
	v_lshlrev_b32_e32 v102, 1, v102
	v_mov_b32_e32 v103, v189
	v_lshl_add_u64 v[154:155], v[138:139], 0, v[102:103]
	global_store_short v[154:155], v156, off
	v_or_b32_e32 v154, 48, v163
	v_mul_u32_u24_e32 v154, s9, v154
	v_mul_f32_e32 v104, v104, v164
	v_lshlrev_b32_e32 v154, 1, v154
	v_mov_b32_e32 v155, v189
	v_cvt_pk_bf16_f32 v104, v104, s0
	v_lshl_add_u64 v[156:157], v[138:139], 0, v[154:155]
	global_store_short v[156:157], v104, off
	v_or_b32_e32 v104, 49, v163
	v_mul_f32_e32 v105, v105, v164
	v_mul_u32_u24_e32 v104, s9, v104
	v_cvt_pk_bf16_f32 v158, v105, s0
	v_lshlrev_b32_e32 v104, 1, v104
	v_mov_b32_e32 v105, v189
	v_lshl_add_u64 v[156:157], v[138:139], 0, v[104:105]
	global_store_short v[156:157], v158, off
	v_or_b32_e32 v156, 50, v163
	v_mul_u32_u24_e32 v156, s9, v156
	v_mul_f32_e32 v106, v106, v164
	v_lshlrev_b32_e32 v156, 1, v156
	v_mov_b32_e32 v157, v189
	v_cvt_pk_bf16_f32 v106, v106, s0
	v_lshl_add_u64 v[158:159], v[138:139], 0, v[156:157]
	global_store_short v[158:159], v106, off
	v_or_b32_e32 v106, 51, v163
	v_mul_f32_e32 v107, v107, v164
	v_mul_u32_u24_e32 v106, s9, v106
	v_cvt_pk_bf16_f32 v160, v107, s0
	v_lshlrev_b32_e32 v106, 1, v106
	v_mov_b32_e32 v107, v189
	v_lshl_add_u64 v[158:159], v[138:139], 0, v[106:107]
	global_store_short v[158:159], v160, off
	v_or_b32_e32 v158, 56, v163
	v_mul_u32_u24_e32 v158, s9, v158
	v_mul_f32_e32 v108, v108, v164
	v_lshlrev_b32_e32 v158, 1, v158
	v_mov_b32_e32 v159, v189
	v_cvt_pk_bf16_f32 v108, v108, s0
	v_lshl_add_u64 v[160:161], v[138:139], 0, v[158:159]
	global_store_short v[160:161], v108, off
	v_or_b32_e32 v108, 57, v163
	v_mul_f32_e32 v109, v109, v164
	v_mul_u32_u24_e32 v108, s9, v108
	v_cvt_pk_bf16_f32 v165, v109, s0
	v_lshlrev_b32_e32 v108, 1, v108
	v_mov_b32_e32 v109, v189
	v_lshl_add_u64 v[160:161], v[138:139], 0, v[108:109]
	global_store_short v[160:161], v165, off
	v_or_b32_e32 v160, 58, v163
	v_mul_u32_u24_e32 v160, s9, v160
	v_mul_f32_e32 v110, v110, v164
	v_lshlrev_b32_e32 v160, 1, v160
	v_mov_b32_e32 v161, v189
	v_cvt_pk_bf16_f32 v110, v110, s0
	v_lshl_add_u64 v[166:167], v[138:139], 0, v[160:161]
	global_store_short v[166:167], v110, off
	v_or_b32_e32 v110, 59, v163
	v_mul_f32_e32 v111, v111, v164
	v_mul_u32_u24_e32 v110, s9, v110
	v_cvt_pk_bf16_f32 v163, v111, s0
	v_lshlrev_b32_e32 v110, 1, v110
	v_mov_b32_e32 v111, v189
	v_lshl_add_u64 v[138:139], v[138:139], 0, v[110:111]
	global_store_short v[138:139], v163, off
	v_or_b32_e32 v138, 32, v176
	v_lshl_add_u32 v163, v138, 2, s8
	ds_read_b32 v163, v163
	s_movk_i32 s9, 0x1fbf
	v_or_b32_e32 v139, s56, v138
	v_bitop3_b32 v138, v138, s9, v162 bitop3:0xc8
	v_cndmask_b32_e64 v138, v138, v139, s[6:7]
	v_lshlrev_b32_e32 v138, 1, v138
	v_mov_b32_e32 v139, v189
	v_lshl_add_u64 v[138:139], v[128:129], 0, v[138:139]
	s_waitcnt lgkmcnt(0)
	v_mul_f32_e32 v80, v80, v163
	v_cvt_pk_bf16_f32 v80, v80, s0
	v_lshl_add_u64 v[164:165], v[138:139], 0, v[188:189]
	global_store_short v[164:165], v80, off
	v_mul_f32_e32 v80, v81, v163
	v_cvt_pk_bf16_f32 v164, v80, s0
	v_lshl_add_u64 v[80:81], v[138:139], 0, v[112:113]
	global_store_short v[80:81], v164, off
	v_mul_f32_e32 v80, v82, v163
	v_cvt_pk_bf16_f32 v82, v80, s0
	v_lshl_add_u64 v[80:81], v[138:139], 0, v[130:131]
	global_store_short v[80:81], v82, off
	v_mul_f32_e32 v80, v83, v163
	v_cvt_pk_bf16_f32 v82, v80, s0
	v_lshl_add_u64 v[80:81], v[138:139], 0, v[114:115]
	global_store_short v[80:81], v82, off
	v_mul_f32_e32 v80, v84, v163
	v_cvt_pk_bf16_f32 v82, v80, s0
	v_lshl_add_u64 v[80:81], v[138:139], 0, v[132:133]
	global_store_short v[80:81], v82, off
	v_mul_f32_e32 v80, v85, v163
	v_cvt_pk_bf16_f32 v82, v80, s0
	v_lshl_add_u64 v[80:81], v[138:139], 0, v[116:117]
	global_store_short v[80:81], v82, off
	v_mul_f32_e32 v80, v86, v163
	v_cvt_pk_bf16_f32 v82, v80, s0
	v_lshl_add_u64 v[80:81], v[138:139], 0, v[134:135]
	global_store_short v[80:81], v82, off
	v_mul_f32_e32 v80, v87, v163
	v_cvt_pk_bf16_f32 v82, v80, s0
	v_lshl_add_u64 v[80:81], v[138:139], 0, v[118:119]
	global_store_short v[80:81], v82, off
	v_mul_f32_e32 v80, v88, v163
	v_cvt_pk_bf16_f32 v82, v80, s0
	v_lshl_add_u64 v[80:81], v[138:139], 0, v[136:137]
	global_store_short v[80:81], v82, off
	v_mul_f32_e32 v80, v89, v163
	v_cvt_pk_bf16_f32 v82, v80, s0
	v_lshl_add_u64 v[80:81], v[138:139], 0, v[120:121]
	global_store_short v[80:81], v82, off
	v_mul_f32_e32 v80, v90, v163
	v_cvt_pk_bf16_f32 v82, v80, s0
	v_lshl_add_u64 v[80:81], v[138:139], 0, v[140:141]
	global_store_short v[80:81], v82, off
	v_mul_f32_e32 v80, v91, v163
	v_cvt_pk_bf16_f32 v82, v80, s0
	v_lshl_add_u64 v[80:81], v[138:139], 0, v[122:123]
	global_store_short v[80:81], v82, off
	v_mul_f32_e32 v80, v92, v163
	v_cvt_pk_bf16_f32 v82, v80, s0
	v_lshl_add_u64 v[80:81], v[138:139], 0, v[142:143]
; DI u16 f2bf(float a) { return (u16)(pack2(a, 0.f) & 0xffffu); }
; DI int crow(int reg, int g) { return (reg & 3) + 8 * (reg >> 2) + 4 * g; }
; template <bool TR>
; DI void gemm_in_tile(const P& p, int l, int id, char* smem) {
;     ...
; #pragma unroll
;       for (int rb = 0; rb < 2; ++rb) {
; #pragma unroll
;         for (int reg = 0; reg < 16; ++reg) {
;           const int cl = 32 * rb + crow(reg, g);
;           dst[(size_t)cl * cstride] = f2bf(acc[rb][cb][reg] * rs);
;         }
;       }
	global_store_short v[80:81], v82, off
	v_mul_f32_e32 v80, v93, v163
	v_cvt_pk_bf16_f32 v82, v80, s0
	v_lshl_add_u64 v[80:81], v[138:139], 0, v[124:125]
	global_store_short v[80:81], v82, off
	v_mul_f32_e32 v80, v94, v163
	v_cvt_pk_bf16_f32 v82, v80, s0
	v_lshl_add_u64 v[80:81], v[138:139], 0, v[144:145]
	global_store_short v[80:81], v82, off
	v_mul_f32_e32 v80, v95, v163
	v_cvt_pk_bf16_f32 v82, v80, s0
	v_lshl_add_u64 v[80:81], v[138:139], 0, v[126:127]
	v_mul_f32_e32 v64, v64, v163
	global_store_short v[80:81], v82, off
	v_cvt_pk_bf16_f32 v64, v64, s0
	v_lshl_add_u64 v[80:81], v[138:139], 0, v[146:147]
	global_store_short v[80:81], v64, off
	v_mul_f32_e32 v64, v65, v163
	v_cvt_pk_bf16_f32 v80, v64, s0
	v_lshl_add_u64 v[64:65], v[138:139], 0, v[96:97]
	global_store_short v[64:65], v80, off
	v_mul_f32_e32 v64, v66, v163
	v_cvt_pk_bf16_f32 v66, v64, s0
	v_lshl_add_u64 v[64:65], v[138:139], 0, v[148:149]
	global_store_short v[64:65], v66, off
	v_mul_f32_e32 v64, v67, v163
	v_cvt_pk_bf16_f32 v66, v64, s0
	v_lshl_add_u64 v[64:65], v[138:139], 0, v[98:99]
	global_store_short v[64:65], v66, off
	v_mul_f32_e32 v64, v68, v163
	v_cvt_pk_bf16_f32 v66, v64, s0
	v_lshl_add_u64 v[64:65], v[138:139], 0, v[150:151]
	global_store_short v[64:65], v66, off
	v_mul_f32_e32 v64, v69, v163
	v_cvt_pk_bf16_f32 v66, v64, s0
	v_lshl_add_u64 v[64:65], v[138:139], 0, v[100:101]
	global_store_short v[64:65], v66, off
	v_mul_f32_e32 v64, v70, v163
	v_cvt_pk_bf16_f32 v66, v64, s0
	v_lshl_add_u64 v[64:65], v[138:139], 0, v[152:153]
	global_store_short v[64:65], v66, off
	v_mul_f32_e32 v64, v71, v163
	v_cvt_pk_bf16_f32 v66, v64, s0
	v_lshl_add_u64 v[64:65], v[138:139], 0, v[102:103]
	global_store_short v[64:65], v66, off
	v_mul_f32_e32 v64, v72, v163
	v_cvt_pk_bf16_f32 v66, v64, s0
	v_lshl_add_u64 v[64:65], v[138:139], 0, v[154:155]
	global_store_short v[64:65], v66, off
	v_mul_f32_e32 v64, v73, v163
	v_cvt_pk_bf16_f32 v66, v64, s0
	v_lshl_add_u64 v[64:65], v[138:139], 0, v[104:105]
	global_store_short v[64:65], v66, off
	v_mul_f32_e32 v64, v74, v163
	v_cvt_pk_bf16_f32 v66, v64, s0
	v_lshl_add_u64 v[64:65], v[138:139], 0, v[156:157]
	global_store_short v[64:65], v66, off
	v_mul_f32_e32 v64, v75, v163
	v_cvt_pk_bf16_f32 v66, v64, s0
	v_lshl_add_u64 v[64:65], v[138:139], 0, v[106:107]
	global_store_short v[64:65], v66, off
	v_mul_f32_e32 v64, v76, v163
	v_cvt_pk_bf16_f32 v66, v64, s0
	v_lshl_add_u64 v[64:65], v[138:139], 0, v[158:159]
	global_store_short v[64:65], v66, off
	v_mul_f32_e32 v64, v77, v163
	v_cvt_pk_bf16_f32 v66, v64, s0
	v_lshl_add_u64 v[64:65], v[138:139], 0, v[108:109]
	global_store_short v[64:65], v66, off
	v_mul_f32_e32 v64, v78, v163
	v_cvt_pk_bf16_f32 v66, v64, s0
	v_lshl_add_u64 v[64:65], v[138:139], 0, v[160:161]
	global_store_short v[64:65], v66, off
	v_mul_f32_e32 v64, v79, v163
	v_cvt_pk_bf16_f32 v66, v64, s0
	v_lshl_add_u64 v[64:65], v[138:139], 0, v[110:111]
	global_store_short v[64:65], v66, off
	v_or_b32_e32 v64, 64, v176
	v_lshl_add_u32 v66, v64, 2, s8
	ds_read_b32 v68, v66
	s_movk_i32 s9, 0x1fdf
	v_or_b32_e32 v65, s56, v64
	v_bitop3_b32 v64, v64, s9, v162 bitop3:0xc8
	v_cndmask_b32_e64 v64, v64, v65, s[6:7]
	v_lshlrev_b32_e32 v64, 1, v64
	v_mov_b32_e32 v65, v189
	v_lshl_add_u64 v[64:65], v[128:129], 0, v[64:65]
	s_waitcnt lgkmcnt(0)
	v_mul_f32_e32 v48, v48, v68
	v_cvt_pk_bf16_f32 v48, v48, s0
	v_lshl_add_u64 v[66:67], v[64:65], 0, v[188:189]
	global_store_short v[66:67], v48, off
	v_mul_f32_e32 v48, v49, v68
	v_cvt_pk_bf16_f32 v66, v48, s0
	v_lshl_add_u64 v[48:49], v[64:65], 0, v[112:113]
	global_store_short v[48:49], v66, off
	v_mul_f32_e32 v48, v50, v68
	v_cvt_pk_bf16_f32 v50, v48, s0
	v_lshl_add_u64 v[48:49], v[64:65], 0, v[130:131]
	global_store_short v[48:49], v50, off
	v_mul_f32_e32 v48, v51, v68
	v_cvt_pk_bf16_f32 v50, v48, s0
	v_lshl_add_u64 v[48:49], v[64:65], 0, v[114:115]
	global_store_short v[48:49], v50, off
	v_mul_f32_e32 v48, v52, v68
	v_cvt_pk_bf16_f32 v50, v48, s0
	v_lshl_add_u64 v[48:49], v[64:65], 0, v[132:133]
	global_store_short v[48:49], v50, off
	v_mul_f32_e32 v48, v53, v68
	v_cvt_pk_bf16_f32 v50, v48, s0
	v_lshl_add_u64 v[48:49], v[64:65], 0, v[116:117]
	global_store_short v[48:49], v50, off
	v_mul_f32_e32 v48, v54, v68
	v_cvt_pk_bf16_f32 v50, v48, s0
	v_lshl_add_u64 v[48:49], v[64:65], 0, v[134:135]
	global_store_short v[48:49], v50, off
	v_mul_f32_e32 v48, v55, v68
	v_cvt_pk_bf16_f32 v50, v48, s0
	v_lshl_add_u64 v[48:49], v[64:65], 0, v[118:119]
	global_store_short v[48:49], v50, off
	v_mul_f32_e32 v48, v56, v68
	v_cvt_pk_bf16_f32 v50, v48, s0
	v_lshl_add_u64 v[48:49], v[64:65], 0, v[136:137]
	global_store_short v[48:49], v50, off
	v_mul_f32_e32 v48, v57, v68
	v_cvt_pk_bf16_f32 v50, v48, s0
	v_lshl_add_u64 v[48:49], v[64:65], 0, v[120:121]
	global_store_short v[48:49], v50, off
	v_mul_f32_e32 v48, v58, v68
	v_cvt_pk_bf16_f32 v50, v48, s0
	v_lshl_add_u64 v[48:49], v[64:65], 0, v[140:141]
	global_store_short v[48:49], v50, off
	v_mul_f32_e32 v48, v59, v68
	v_cvt_pk_bf16_f32 v50, v48, s0
	v_lshl_add_u64 v[48:49], v[64:65], 0, v[122:123]
	global_store_short v[48:49], v50, off
	v_mul_f32_e32 v48, v60, v68
	v_cvt_pk_bf16_f32 v50, v48, s0
	v_lshl_add_u64 v[48:49], v[64:65], 0, v[142:143]
	global_store_short v[48:49], v50, off
	v_mul_f32_e32 v48, v61, v68
	v_cvt_pk_bf16_f32 v50, v48, s0
	v_lshl_add_u64 v[48:49], v[64:65], 0, v[124:125]
	global_store_short v[48:49], v50, off
	v_mul_f32_e32 v48, v62, v68
	v_cvt_pk_bf16_f32 v50, v48, s0
	v_lshl_add_u64 v[48:49], v[64:65], 0, v[144:145]
	global_store_short v[48:49], v50, off
	v_mul_f32_e32 v48, v63, v68
	v_cvt_pk_bf16_f32 v50, v48, s0
	v_lshl_add_u64 v[48:49], v[64:65], 0, v[126:127]
; DI u16 f2bf(float a) { return (u16)(pack2(a, 0.f) & 0xffffu); }
; DI int crow(int reg, int g) { return (reg & 3) + 8 * (reg >> 2) + 4 * g; }
; template <bool TR>
; DI void gemm_in_tile(const P& p, int l, int id, char* smem) {
;     ...
; #pragma unroll
;       for (int rb = 0; rb < 2; ++rb) {
; #pragma unroll
;         for (int reg = 0; reg < 16; ++reg) {
;           const int cl = 32 * rb + crow(reg, g);
;           dst[(size_t)cl * cstride] = f2bf(acc[rb][cb][reg] * rs);
;         }
;       }
	v_mul_f32_e32 v32, v32, v68
	global_store_short v[48:49], v50, off
	v_cvt_pk_bf16_f32 v32, v32, s0
	v_lshl_add_u64 v[48:49], v[64:65], 0, v[146:147]
	global_store_short v[48:49], v32, off
	v_mul_f32_e32 v32, v33, v68
	v_cvt_pk_bf16_f32 v48, v32, s0
	v_lshl_add_u64 v[32:33], v[64:65], 0, v[96:97]
	global_store_short v[32:33], v48, off
	v_mul_f32_e32 v32, v34, v68
	v_cvt_pk_bf16_f32 v34, v32, s0
	v_lshl_add_u64 v[32:33], v[64:65], 0, v[148:149]
	global_store_short v[32:33], v34, off
	v_mul_f32_e32 v32, v35, v68
	v_cvt_pk_bf16_f32 v34, v32, s0
	v_lshl_add_u64 v[32:33], v[64:65], 0, v[98:99]
	global_store_short v[32:33], v34, off
	v_mul_f32_e32 v32, v36, v68
	v_cvt_pk_bf16_f32 v34, v32, s0
	v_lshl_add_u64 v[32:33], v[64:65], 0, v[150:151]
	global_store_short v[32:33], v34, off
	v_mul_f32_e32 v32, v37, v68
	v_cvt_pk_bf16_f32 v34, v32, s0
	v_lshl_add_u64 v[32:33], v[64:65], 0, v[100:101]
	global_store_short v[32:33], v34, off
	v_mul_f32_e32 v32, v38, v68
	v_cvt_pk_bf16_f32 v34, v32, s0
	v_lshl_add_u64 v[32:33], v[64:65], 0, v[152:153]
	global_store_short v[32:33], v34, off
	v_mul_f32_e32 v32, v39, v68
	v_cvt_pk_bf16_f32 v34, v32, s0
	v_lshl_add_u64 v[32:33], v[64:65], 0, v[102:103]
	global_store_short v[32:33], v34, off
	v_mul_f32_e32 v32, v40, v68
	v_cvt_pk_bf16_f32 v34, v32, s0
	v_lshl_add_u64 v[32:33], v[64:65], 0, v[154:155]
	global_store_short v[32:33], v34, off
	v_mul_f32_e32 v32, v41, v68
	v_cvt_pk_bf16_f32 v34, v32, s0
	v_lshl_add_u64 v[32:33], v[64:65], 0, v[104:105]
	global_store_short v[32:33], v34, off
	v_mul_f32_e32 v32, v42, v68
	v_cvt_pk_bf16_f32 v34, v32, s0
	v_lshl_add_u64 v[32:33], v[64:65], 0, v[156:157]
	global_store_short v[32:33], v34, off
	v_mul_f32_e32 v32, v43, v68
	v_cvt_pk_bf16_f32 v34, v32, s0
	v_lshl_add_u64 v[32:33], v[64:65], 0, v[106:107]
	global_store_short v[32:33], v34, off
	v_mul_f32_e32 v32, v44, v68
	v_cvt_pk_bf16_f32 v34, v32, s0
	v_lshl_add_u64 v[32:33], v[64:65], 0, v[158:159]
	global_store_short v[32:33], v34, off
	v_mul_f32_e32 v32, v45, v68
	v_cvt_pk_bf16_f32 v34, v32, s0
	v_lshl_add_u64 v[32:33], v[64:65], 0, v[108:109]
	global_store_short v[32:33], v34, off
	v_mul_f32_e32 v32, v46, v68
	v_cvt_pk_bf16_f32 v34, v32, s0
	v_lshl_add_u64 v[32:33], v[64:65], 0, v[160:161]
	global_store_short v[32:33], v34, off
	v_mul_f32_e32 v32, v47, v68
	v_cvt_pk_bf16_f32 v34, v32, s0
	v_lshl_add_u64 v[32:33], v[64:65], 0, v[110:111]
	global_store_short v[32:33], v34, off
	v_or_b32_e32 v32, 0x60, v176
	v_lshl_add_u32 v34, v32, 2, s8
	ds_read_b32 v36, v34
	s_movk_i32 s8, 0x1fff
	v_or_b32_e32 v33, s56, v32
	v_bitop3_b32 v32, v32, s8, v162 bitop3:0xc8
	v_cndmask_b32_e64 v32, v32, v33, s[6:7]
	v_lshlrev_b32_e32 v32, 1, v32
	v_mov_b32_e32 v33, v189
	v_lshl_add_u64 v[32:33], v[128:129], 0, v[32:33]
	s_waitcnt lgkmcnt(0)
; DI u16 f2bf(float a) { return (u16)(pack2(a, 0.f) & 0xffffu); }
; DI int crow(int reg, int g) { return (reg & 3) + 8 * (reg >> 2) + 4 * g; }
; template <bool TR>
; DI void gemm_in_tile(const P& p, int l, int id, char* smem) {
;     ...
; #pragma unroll
;       for (int rb = 0; rb < 2; ++rb) {
; #pragma unroll
;         for (int reg = 0; reg < 16; ++reg) {
;           const int cl = 32 * rb + crow(reg, g);
;           dst[(size_t)cl * cstride] = f2bf(acc[rb][cb][reg] * rs);
;         }
;       }
	v_mul_f32_e32 v16, v16, v36
	v_cvt_pk_bf16_f32 v16, v16, s0
	v_lshl_add_u64 v[34:35], v[32:33], 0, v[188:189]
	global_store_short v[34:35], v16, off
	v_mul_f32_e32 v16, v17, v36
	v_cvt_pk_bf16_f32 v34, v16, s0
	v_lshl_add_u64 v[16:17], v[32:33], 0, v[112:113]
	global_store_short v[16:17], v34, off
	v_mul_f32_e32 v16, v18, v36
	v_cvt_pk_bf16_f32 v18, v16, s0
	v_lshl_add_u64 v[16:17], v[32:33], 0, v[130:131]
	global_store_short v[16:17], v18, off
	v_mul_f32_e32 v16, v19, v36
	v_cvt_pk_bf16_f32 v18, v16, s0
	v_lshl_add_u64 v[16:17], v[32:33], 0, v[114:115]
	global_store_short v[16:17], v18, off
	v_mul_f32_e32 v16, v20, v36
	v_cvt_pk_bf16_f32 v18, v16, s0
	v_lshl_add_u64 v[16:17], v[32:33], 0, v[132:133]
	global_store_short v[16:17], v18, off
	v_mul_f32_e32 v16, v21, v36
	v_cvt_pk_bf16_f32 v18, v16, s0
	v_lshl_add_u64 v[16:17], v[32:33], 0, v[116:117]
	global_store_short v[16:17], v18, off
	v_mul_f32_e32 v16, v22, v36
	v_cvt_pk_bf16_f32 v18, v16, s0
	v_lshl_add_u64 v[16:17], v[32:33], 0, v[134:135]
	global_store_short v[16:17], v18, off
	v_mul_f32_e32 v16, v23, v36
	v_cvt_pk_bf16_f32 v18, v16, s0
	v_lshl_add_u64 v[16:17], v[32:33], 0, v[118:119]
	global_store_short v[16:17], v18, off
	v_mul_f32_e32 v16, v24, v36
	v_cvt_pk_bf16_f32 v18, v16, s0
	v_lshl_add_u64 v[16:17], v[32:33], 0, v[136:137]
	global_store_short v[16:17], v18, off
	v_mul_f32_e32 v16, v25, v36
	v_cvt_pk_bf16_f32 v18, v16, s0
	v_lshl_add_u64 v[16:17], v[32:33], 0, v[120:121]
	global_store_short v[16:17], v18, off
	v_mul_f32_e32 v16, v26, v36
	v_cvt_pk_bf16_f32 v18, v16, s0
	v_lshl_add_u64 v[16:17], v[32:33], 0, v[140:141]
	global_store_short v[16:17], v18, off
	v_mul_f32_e32 v16, v27, v36
	v_cvt_pk_bf16_f32 v18, v16, s0
	v_lshl_add_u64 v[16:17], v[32:33], 0, v[122:123]
	global_store_short v[16:17], v18, off
	v_mul_f32_e32 v16, v28, v36
	v_cvt_pk_bf16_f32 v18, v16, s0
	v_lshl_add_u64 v[16:17], v[32:33], 0, v[142:143]
	global_store_short v[16:17], v18, off
	v_mul_f32_e32 v16, v29, v36
	v_cvt_pk_bf16_f32 v18, v16, s0
	v_lshl_add_u64 v[16:17], v[32:33], 0, v[124:125]
	global_store_short v[16:17], v18, off
	v_mul_f32_e32 v16, v30, v36
	v_cvt_pk_bf16_f32 v18, v16, s0
	v_lshl_add_u64 v[16:17], v[32:33], 0, v[144:145]
	global_store_short v[16:17], v18, off
	v_mul_f32_e32 v16, v31, v36
	v_cvt_pk_bf16_f32 v18, v16, s0
	v_lshl_add_u64 v[16:17], v[32:33], 0, v[126:127]
	v_mul_f32_e32 v0, v0, v36
	global_store_short v[16:17], v18, off
	v_cvt_pk_bf16_f32 v0, v0, s0
	v_lshl_add_u64 v[16:17], v[32:33], 0, v[146:147]
	global_store_short v[16:17], v0, off
	v_mul_f32_e32 v0, v1, v36
	v_cvt_pk_bf16_f32 v16, v0, s0
	v_lshl_add_u64 v[0:1], v[32:33], 0, v[96:97]
	global_store_short v[0:1], v16, off
	v_mul_f32_e32 v0, v2, v36
	v_cvt_pk_bf16_f32 v2, v0, s0
	v_lshl_add_u64 v[0:1], v[32:33], 0, v[148:149]
	global_store_short v[0:1], v2, off
	v_mul_f32_e32 v0, v3, v36
	v_cvt_pk_bf16_f32 v2, v0, s0
	v_lshl_add_u64 v[0:1], v[32:33], 0, v[98:99]
	global_store_short v[0:1], v2, off
	v_mul_f32_e32 v0, v4, v36
	v_cvt_pk_bf16_f32 v2, v0, s0
	v_lshl_add_u64 v[0:1], v[32:33], 0, v[150:151]
	global_store_short v[0:1], v2, off
	v_mul_f32_e32 v0, v5, v36
	v_cvt_pk_bf16_f32 v2, v0, s0
	v_lshl_add_u64 v[0:1], v[32:33], 0, v[100:101]
	global_store_short v[0:1], v2, off
	v_mul_f32_e32 v0, v6, v36
	v_cvt_pk_bf16_f32 v2, v0, s0
	v_lshl_add_u64 v[0:1], v[32:33], 0, v[152:153]
	global_store_short v[0:1], v2, off
	v_mul_f32_e32 v0, v7, v36
	v_cvt_pk_bf16_f32 v2, v0, s0
	v_lshl_add_u64 v[0:1], v[32:33], 0, v[102:103]
	global_store_short v[0:1], v2, off
	v_mul_f32_e32 v0, v8, v36
	v_cvt_pk_bf16_f32 v2, v0, s0
	v_lshl_add_u64 v[0:1], v[32:33], 0, v[154:155]
	global_store_short v[0:1], v2, off
	v_mul_f32_e32 v0, v9, v36
	v_cvt_pk_bf16_f32 v2, v0, s0
	v_lshl_add_u64 v[0:1], v[32:33], 0, v[104:105]
	global_store_short v[0:1], v2, off
	v_mul_f32_e32 v0, v10, v36
	v_cvt_pk_bf16_f32 v2, v0, s0
	v_lshl_add_u64 v[0:1], v[32:33], 0, v[156:157]
	global_store_short v[0:1], v2, off
	v_mul_f32_e32 v0, v11, v36
	v_cvt_pk_bf16_f32 v2, v0, s0
	v_lshl_add_u64 v[0:1], v[32:33], 0, v[106:107]
	global_store_short v[0:1], v2, off
	v_mul_f32_e32 v0, v12, v36
	v_cvt_pk_bf16_f32 v2, v0, s0
	v_lshl_add_u64 v[0:1], v[32:33], 0, v[158:159]
	global_store_short v[0:1], v2, off
	v_mul_f32_e32 v0, v13, v36
	v_cvt_pk_bf16_f32 v2, v0, s0
	v_lshl_add_u64 v[0:1], v[32:33], 0, v[108:109]
	global_store_short v[0:1], v2, off
	v_mul_f32_e32 v0, v14, v36
	v_cvt_pk_bf16_f32 v2, v0, s0
	v_lshl_add_u64 v[0:1], v[32:33], 0, v[160:161]
	global_store_short v[0:1], v2, off
	v_mul_f32_e32 v0, v15, v36
	v_cvt_pk_bf16_f32 v2, v0, s0
	v_lshl_add_u64 v[0:1], v[32:33], 0, v[110:111]
	global_store_short v[0:1], v2, off
	s_branch .LBB0_102

; DI f32x16 zero16() { f32x16 z; for (int i = 0; i < 16; ++i) z[i] = 0.f; return z; }
; DI void hy_conv(f32x16 (&acc)[4], const u16* abase, const u16* U, const u16* Zrow, int a0, int li, int g) {
; #pragma unroll
;   for (int i = 0; i < 4; ++i) acc[i] = zero16();
;   u32x4 W[14];
;   bf16x8 bf[8];
;   int d = a0 - 63;
; #pragma unroll
;   for (int x = 0; x < 14; ++x) W[x] = hy_afrag(abase, 8 * d + x - 7);
; DI void hyena_item(const P& p, int l, int c, char* smem) {
;     ...
;     const float w0 = cw[c], w1 = cw[1536 + c], w2 = cw[3072 + c], bs = cbias[c];
; #pragma unroll
;     for (int i = 0; i < 4; ++i) {
;       const int q = tid + NT * i;
;       const int bt = q >> 10, t8 = (q & 1023) * 8;
;       const u16* row = p.hyT + (size_t)c * HYP + bt * SEQ;
;       float o0[4], o1[4];
;       sconv4(row, t8, w0, w1, w2, bs, o0);
;       sconv4(row, t8 + 4, w0, w1, w2, bs, o1);
;       uint4 ov;
;       ov.x = pack2(o0[0], o0[1]); ov.y = pack2(o0[2], o0[3]); ov.z = pack2(o1[0], o1[1]); ov.w = pack2(o1[2], o1[3]);
;       *(uint4*)(U + (bt * 64 + (t8 >> 7)) * 136 + (t8 & 127)) = ov;
;     }
;   }
;   __syncthreads();
;   const float invn0 = 1.0f / (misc[4] + misc[5] + misc[6] + misc[7]);
;   const float invn1 = 1.0f / (misc[8] + misc[9] + misc[10] + misc[11]);
;   const u16* abase = (li & 1) ? (TbO + (8192 - li + 8 * g - 1)) : (TbE + (8192 - li + 8 * g));
;   const int bt = li >> 4;
;   const int a = a0 + (li & 15);
;   f32x16 acc[4];
;   if (cwv) hy_conv(acc, abase, U, Zrow, a0, li, g);
.LBB0_433:
	s_or_b64 exec, exec, s[78:79]
	s_waitcnt vmcnt(2)
	v_and_b32_e32 v26, 0xffff0000, v10
	v_mov_b32_e32 v18, v26
	v_lshlrev_b32_e32 v10, 16, v10
	v_pk_mul_f32 v[18:19], v[2:3], v[18:19]
	v_and_b32_e32 v12, 0xffff0000, v11
	s_waitcnt vmcnt(1)
	v_lshlrev_b32_e32 v13, 16, v14
	v_lshlrev_b32_e32 v27, 16, v11
	v_pk_fma_f32 v[2:3], v[2:3], v[10:11], v[18:19] op_sel:[0,0,1] op_sel_hi:[1,0,0]
	v_pk_mov_b32 v[28:29], v[26:27], v[12:13] op_sel:[1,0]
	v_pk_fma_f32 v[2:3], v[0:1], v[26:27], v[2:3]
	v_readlane_b32 s78, v248, 10
	v_pk_add_f32 v[10:11], v[4:5], v[2:3]
	v_pk_mul_f32 v[2:3], v[8:9], v[28:29]
	s_waitcnt vmcnt(0)
	v_and_b32_e32 v28, 0xffff0000, v16
	v_pk_fma_f32 v[2:3], v[6:7], v[26:27], v[2:3]
	v_lshlrev_b32_e32 v29, 16, v17
	v_pk_fma_f32 v[2:3], v[0:1], v[12:13], v[2:3]
	v_lshlrev_b32_e32 v13, 16, v16
	v_and_b32_e32 v27, 0xffff0000, v17
	v_mov_b32_e32 v26, v29
	v_mov_b32_e32 v16, v13
	v_mov_b32_e32 v17, v28
	v_pk_mul_f32 v[16:17], v[8:9], v[16:17]
	v_pk_mul_f32 v[8:9], v[8:9], v[26:27]
	v_pk_fma_f32 v[12:13], v[6:7], v[12:13], v[16:17]
	v_pk_fma_f32 v[6:7], v[6:7], v[28:29], v[8:9]
	v_mov_b32_e32 v14, v27
	v_pk_fma_f32 v[12:13], v[0:1], v[28:29], v[12:13]
	v_pk_fma_f32 v[0:1], v[0:1], v[14:15], v[6:7]
	v_pk_add_f32 v[18:19], v[4:5], v[2:3]
	v_pk_add_f32 v[0:1], v[4:5], v[0:1]
	v_pk_add_f32 v[12:13], v[4:5], v[12:13]
	v_cvt_pk_bf16_f32 v7, v0, v1
	v_lshrrev_b32_e32 v0, 7, v25
	v_lshl_or_b32 v0, v24, 6, v0
	v_and_b32_e32 v1, 0x78, v23
	v_mul_lo_u32 v0, v0, s97
	v_lshlrev_b32_e32 v1, 1, v1
	v_cvt_pk_bf16_f32 v4, v10, v11
	v_cvt_pk_bf16_f32 v5, v18, v19
	v_cvt_pk_bf16_f32 v6, v12, v13
	v_add3_u32 v0, s69, v0, v1
	ds_write_b128 v0, v[4:7]
	v_mov_b32_e32 v0, s78
	v_readlane_b32 s78, v248, 11
	v_lshrrev_b32_e32 v188, 5, v21
	v_and_b32_e32 v230, 31, v20
	v_mov_b32_e32 v1, s78
	s_waitcnt lgkmcnt(0)
	s_barrier
	ds_read_b128 v[68:71], v0
	ds_read_b128 v[64:67], v1
	v_and_b32_e32 v0, 1, v20
	v_lshlrev_b32_e32 v1, 3, v188
	v_readlane_b32 s78, v248, 12
	v_sub_u32_e32 v1, v1, v230
	v_cmp_eq_u32_e32 vcc, 0, v0
	v_mov_b32_e32 v3, s78
	v_lshlrev_b32_e32 v2, 4, v22
	v_cndmask_b32_e64 v0, v3, 0, vcc
	v_cndmask_b32_e32 v3, v217, v207, vcc
	v_lshlrev_b32_e32 v1, 1, v1
	v_and_b32_e32 v231, 48, v2
	v_add3_u32 v225, v0, v1, v3
	v_and_b32_e32 v223, 15, v20
	v_lshlrev_b32_e32 v0, 2, v230
	v_or_b32_e32 v226, 15, v231
	v_lshlrev_b32_e32 v222, 4, v188
	v_or_b32_e32 v227, 14, v231
	v_add_u32_e32 v229, v231, v223
	v_or_b32_e32 v228, 0xffffffc1, v2
	v_and_b32_e32 v224, 64, v0
	s_and_b64 vcc, exec, s[6:7]
	s_cbranch_vccnz .Lhy_pf_skip
	s_or_b32 s78, s72, 0x200
	s_mul_hi_u32 s79, s78, 0x8080
	s_mul_i32 s78, s78, 0x8080
	s_add_u32 s78, s36, s78
	s_addc_u32 s79, s37, s79
	v_and_b32_e32 v240, 0xff, v198
	v_lshlrev_b32_e32 v240, 7, v240
	global_load_dword v241, v240, s[78:79]
	s_add_u32 s78, s78, 0x1010000
	s_addc_u32 s79, s79, 0
	global_load_dword v242, v240, s[78:79]
	s_add_u32 s78, s78, 0x1010000
	s_addc_u32 s79, s79, 0
	global_load_dword v243, v240, s[78:79]
.Lhy_pf_skip:
	s_and_saveexec_b64 s[78:79], s[6:7]
	s_cbranch_execz .LBB0_437
	v_or_b32_e32 v232, 0xffffffc1, v2
	s_movk_i32 s88, 0xff00
	v_mad_i32_i24 v0, v232, s88, v225
	ds_read2_b32 v[156:157], v0 offset0:56 offset1:57
	ds_read2_b32 v[158:159], v0 offset0:58 offset1:59
	ds_read2_b32 v[152:153], v0 offset0:48 offset1:49
	ds_read2_b32 v[154:155], v0 offset0:50 offset1:51
	ds_read2_b32 v[144:145], v0 offset0:40 offset1:41
	ds_read2_b32 v[146:147], v0 offset0:42 offset1:43
	ds_read2_b32 v[140:141], v0 offset0:32 offset1:33
	ds_read2_b32 v[142:143], v0 offset0:34 offset1:35
	ds_read2_b32 v[128:129], v0 offset0:24 offset1:25
	ds_read2_b32 v[130:131], v0 offset0:26 offset1:27
	ds_read2_b32 v[132:133], v0 offset0:16 offset1:17
	ds_read2_b32 v[134:135], v0 offset0:18 offset1:19
	ds_read2_b32 v[120:121], v0 offset0:8 offset1:9
	ds_read2_b32 v[122:123], v0 offset0:10 offset1:11
	ds_read2_b32 v[124:125], v0 offset1:1
	ds_read2_b32 v[126:127], v0 offset0:2 offset1:3
	v_subrev_u32_e32 v1, 32, v0
	v_subrev_u32_e32 v2, 24, v0
	v_subrev_u32_e32 v3, 64, v0
	v_subrev_u32_e32 v4, 56, v0
	ds_read2_b32 v[104:105], v1 offset1:1
	ds_read2_b32 v[106:107], v2 offset1:1
	ds_read2_b32 v[96:97], v3 offset1:1
	ds_read2_b32 v[98:99], v4 offset1:1
	v_add_u32_e32 v1, 0xffffffa0, v0
	v_add_u32_e32 v2, 0xffffffa8, v0
	v_add_u32_e32 v3, 0xffffff80, v0
	v_add_u32_e32 v4, 0xffffff88, v0
	ds_read2_b32 v[100:101], v1 offset1:1
	ds_read2_b32 v[102:103], v2 offset1:1
	ds_read2_b32 v[108:109], v3 offset1:1
	ds_read2_b32 v[110:111], v4 offset1:1
	v_add_u32_e32 v1, 0xffffff60, v0
	v_add_u32_e32 v2, 0xffffff68, v0
	v_add_u32_e32 v3, 0xffffff40, v0
	v_add_u32_e32 v0, 0xffffff48, v0
	ds_read2_b32 v[112:113], v1 offset1:1
	ds_read2_b32 v[114:115], v2 offset1:1
	ds_read2_b32 v[116:117], v3 offset1:1
	ds_read2_b32 v[118:119], v0 offset1:1
	v_add_u32_e32 v0, v229, v224
	v_sub_u32_e32 v0, v0, v232
	v_mov_b32_e32 v1, s69
	v_mad_u32_u24 v233, v0, s97, v1
	v_mov_b32_e32 v0, 0
	v_sub_u32_e32 v234, v229, v232
	s_mov_b64 s[88:89], 0
	v_mov_b32_e32 v1, v0
	v_mov_b32_e32 v2, v0
	v_mov_b32_e32 v3, v0
	v_mov_b32_e32 v4, v0
	v_mov_b32_e32 v5, v0
	v_mov_b32_e32 v6, v0
	v_mov_b32_e32 v7, v0
	v_mov_b32_e32 v8, v0
	v_mov_b32_e32 v9, v0
	v_mov_b32_e32 v10, v0
	v_mov_b32_e32 v11, v0
	v_mov_b32_e32 v12, v0
	v_mov_b32_e32 v13, v0
	v_mov_b32_e32 v14, v0
	v_mov_b32_e32 v15, v0
	v_mov_b32_e32 v16, v0
	v_mov_b32_e32 v17, v0
	v_mov_b32_e32 v18, v0
	v_mov_b32_e32 v19, v0
	v_mov_b32_e32 v20, v0
	v_mov_b32_e32 v21, v0
	v_mov_b32_e32 v22, v0
	v_mov_b32_e32 v23, v0
	v_mov_b32_e32 v24, v0
	v_mov_b32_e32 v25, v0
	v_mov_b32_e32 v26, v0
	v_mov_b32_e32 v27, v0
	v_mov_b32_e32 v28, v0
	v_mov_b32_e32 v29, v0
	v_mov_b32_e32 v30, v0
	v_mov_b32_e32 v31, v0
	v_mov_b32_e32 v32, v0
	v_mov_b32_e32 v33, v0
	v_mov_b32_e32 v34, v0
	v_mov_b32_e32 v35, v0
	v_mov_b32_e32 v36, v0
	v_mov_b32_e32 v37, v0
	v_mov_b32_e32 v38, v0
	v_mov_b32_e32 v39, v0
	v_mov_b32_e32 v40, v0
	v_mov_b32_e32 v41, v0
	v_mov_b32_e32 v42, v0
	v_mov_b32_e32 v43, v0
	v_mov_b32_e32 v44, v0
	v_mov_b32_e32 v45, v0
	v_mov_b32_e32 v46, v0
	v_mov_b32_e32 v47, v0
	v_mov_b32_e32 v48, v0
	v_mov_b32_e32 v49, v0
	v_mov_b32_e32 v50, v0
	v_mov_b32_e32 v51, v0
	v_mov_b32_e32 v52, v0
	v_mov_b32_e32 v53, v0
	v_mov_b32_e32 v54, v0
	v_mov_b32_e32 v55, v0
	v_mov_b32_e32 v56, v0
	v_mov_b32_e32 v57, v0
	v_mov_b32_e32 v58, v0
	v_mov_b32_e32 v59, v0
	v_mov_b32_e32 v60, v0
	v_mov_b32_e32 v61, v0
	v_mov_b32_e32 v62, v0
	v_mov_b32_e32 v63, v0

; DI float bf2f(unsigned v) { return __uint_as_float(v << 16); }
; DI f32x16 zero16() { f32x16 z; for (int i = 0; i < 16; ++i) z[i] = 0.f; return z; }
; DI void attn_item(const P& p, int l, int item, char* smem) {
;     ...
;   const float lam_init = (l == 0) ? 0.2f : 0.35550906759096926f;
;   float lam;
;   {
;     float s1 = p.lq1[l * 64 + lane] * p.lk1[l * 64 + lane];
;     float s2 = p.lq2[l * 64 + lane] * p.lk2[l * 64 + lane];
; #pragma unroll
;     for (int m = 32; m >= 1; m >>= 1) { s1 += __shfl_xor(s1, m); s2 += __shfl_xor(s2, m); }
;     lam = __expf(s1) - __expf(s2) + lam_init;
;   }
;   const int tq = qb * 128 + qg * 32 + li;
;   bf16x8 qf[4];
;   float negm;
;   {
;     float q2 = 0.f;
; #pragma unroll
;     for (int ks = 0; ks < 4; ++ks) {
;       qf[ks] = *(const bf16x8*)(p.Qb + ((size_t)((bh * 2 + c) * SEQ + tq)) * 64 + 16 * ks + 8 * g);
; #pragma unroll
;       for (int j = 0; j < 8; ++j) { const float v = bf2f((unsigned)(u16)qf[ks][j]); q2 += v * v; }
;     }
;     q2 += __shfl_xor(q2, 32);
;     const float k2 = __uint_as_float(p.kmax[bh * 2 + c]);
;     negm = -(sqrtf(q2 * k2) * 1.01f + 1e-3f);
;   }
;   f32x16 O[4];
; #pragma unroll
;   for (int eb = 0; eb < 4; ++eb) O[eb] = zero16();
.LBB0_465:
	v_mov_b32_e32 v161, v198
	v_readlane_b32 s6, v248, 26
	v_and_b32_e32 v141, 63, v161
	v_readlane_b32 s72, v248, 30
	v_or_b32_e32 v188, s6, v141
	v_lshlrev_b64 v[0:1], 2, v[188:189]
	v_lshl_add_u64 v[2:3], s[22:23], 0, v[0:1]
	global_load_dword v4, v[2:3], off
	v_lshl_add_u64 v[2:3], s[24:25], 0, v[0:1]
	v_readlane_b32 s73, v248, 31
	global_load_dword v5, v[2:3], off
	v_lshl_add_u64 v[2:3], s[26:27], 0, v[0:1]
	v_lshl_add_u64 v[0:1], s[72:73], 0, v[0:1]
	global_load_dword v2, v[2:3], off
	v_and_b32_e32 v3, 64, v215
	global_load_dword v0, v[0:1], off
	v_add_u32_e32 v3, 64, v3
	v_xor_b32_e32 v7, 32, v215
	v_cmp_lt_i32_e32 vcc, v7, v3
	v_bfe_u32 v162, v161, 6, 2
	s_lshl_b32 s6, s95, 4
	v_cndmask_b32_e32 v7, v215, v7, vcc
	v_lshlrev_b32_e32 v158, 2, v7
	v_ashrrev_i32_e32 v160, 8, v161
	v_and_b32_e32 v17, 31, v161
	s_and_b32 s12, s95, 7
	s_and_b32 s6, s6, 0xffffff80
	v_bfe_u32 v159, v161, 5, 1
	v_lshlrev_b32_e32 v188, 4, v159
	s_and_b32 s13, s64, 7
	s_lshl_b32 s11, s13, 21
	v_mov_b32_e32 v143, v189
	v_ashrrev_i32_e32 v24, 3, v161
	s_movk_i32 s14, 0x4080
	v_mul_lo_u32 v170, v24, s94
	v_mov_b32_e32 v167, 0
	s_mov_b32 s10, 0
	v_mul_u32_u24_e32 v174, 0x90, v17
	v_mov_b32_e32 v38, v167
	v_mov_b32_e32 v39, v167
	v_mov_b32_e32 v40, v167
	v_mov_b32_e32 v41, v167
	v_mov_b32_e32 v42, v167
	v_mov_b32_e32 v43, v167
	v_mov_b32_e32 v44, v167
	v_mov_b32_e32 v45, v167
	v_mov_b32_e32 v46, v167
	v_mov_b32_e32 v47, v167
	v_mov_b32_e32 v48, 0
	v_mov_b32_e32 v49, v167
	v_mov_b32_e32 v50, v167
	v_mov_b32_e32 v51, v167
	v_mov_b32_e32 v52, v167
	v_mov_b32_e32 v53, v167
	v_mov_b32_e32 v54, v167
	v_mov_b32_e32 v55, v167
	v_mov_b32_e32 v56, v167
	v_mov_b32_e32 v57, v167
	v_mov_b32_e32 v58, v167
	v_mov_b32_e32 v59, v167
	v_mov_b32_e32 v60, v167
	v_mov_b32_e32 v61, v167
	v_mov_b32_e32 v62, v167
	v_mov_b32_e32 v63, v167
	v_mov_b32_e32 v64, 0
	v_mov_b32_e32 v65, v167
	v_mov_b32_e32 v66, v167
	v_mov_b32_e32 v67, v167
	v_mov_b32_e32 v68, v167
	v_mov_b32_e32 v69, v167
	v_mov_b32_e32 v70, v167
	v_mov_b32_e32 v71, v167
	v_mov_b32_e32 v72, v167
	v_mov_b32_e32 v73, v167
	v_mov_b32_e32 v74, v167
	v_mov_b32_e32 v75, v167
	v_mov_b32_e32 v76, v167
	v_mov_b32_e32 v77, v167
	v_mov_b32_e32 v78, v167
	v_mov_b32_e32 v79, v167
	v_readlane_b32 s74, v248, 32
	v_readlane_b32 s75, v248, 33
	s_waitcnt vmcnt(2)
	v_mul_f32_e32 v6, v4, v5
	ds_bpermute_b32 v6, v158, v6
	s_waitcnt vmcnt(0)
	v_mul_f32_e32 v1, v2, v0
	ds_bpermute_b32 v1, v158, v1
	s_waitcnt lgkmcnt(1)
	v_fmac_f32_e32 v6, v4, v5
	s_waitcnt lgkmcnt(0)
	v_fmac_f32_e32 v1, v2, v0
	v_xor_b32_e32 v0, 16, v215
	v_cmp_lt_i32_e32 vcc, v0, v3
	s_nop 1
	v_cndmask_b32_e32 v0, v215, v0, vcc
	v_lshlrev_b32_e32 v0, 2, v0
	ds_bpermute_b32 v2, v0, v6
	ds_bpermute_b32 v0, v0, v1
	s_waitcnt lgkmcnt(1)
	v_add_f32_e32 v2, v6, v2
	s_waitcnt lgkmcnt(0)
	v_add_f32_e32 v0, v1, v0
	v_xor_b32_e32 v1, 8, v215
	v_cmp_lt_i32_e32 vcc, v1, v3
	s_nop 1
	v_cndmask_b32_e32 v1, v215, v1, vcc
	v_lshlrev_b32_e32 v1, 2, v1
	ds_bpermute_b32 v4, v1, v2
	ds_bpermute_b32 v1, v1, v0
	s_waitcnt lgkmcnt(1)
	v_add_f32_e32 v2, v2, v4
	s_waitcnt lgkmcnt(0)
	v_add_f32_e32 v0, v0, v1
	v_xor_b32_e32 v1, 4, v215
	v_cmp_lt_i32_e32 vcc, v1, v3
	s_nop 1
	v_cndmask_b32_e32 v1, v215, v1, vcc
	v_lshlrev_b32_e32 v1, 2, v1
	ds_bpermute_b32 v4, v1, v2
	ds_bpermute_b32 v1, v1, v0
	s_waitcnt lgkmcnt(1)
	v_add_f32_e32 v2, v2, v4
	s_waitcnt lgkmcnt(0)
	v_add_f32_e32 v0, v0, v1
	v_xor_b32_e32 v1, 2, v215
	v_cmp_lt_i32_e32 vcc, v1, v3
	s_nop 1
	v_cndmask_b32_e32 v1, v215, v1, vcc
	v_lshlrev_b32_e32 v1, 2, v1
	ds_bpermute_b32 v4, v1, v2
	ds_bpermute_b32 v1, v1, v0
	s_waitcnt lgkmcnt(1)
	v_add_f32_e32 v163, v2, v4
	s_waitcnt lgkmcnt(0)
	v_add_f32_e32 v165, v0, v1
	v_xor_b32_e32 v0, 1, v215
	v_cmp_lt_i32_e32 vcc, v0, v3
	s_nop 1
	v_cndmask_b32_e32 v0, v215, v0, vcc
	v_lshlrev_b32_e32 v0, 2, v0
	ds_bpermute_b32 v164, v0, v163
	ds_bpermute_b32 v166, v0, v165
	v_lshlrev_b32_e32 v0, 5, v162
	v_or3_b32 v140, v0, s6, v17
	s_lshl_b32 s6, s12, 14
	v_lshlrev_b32_e32 v0, 13, v160
	v_add3_u32 v0, v0, s6, v140
	v_ashrrev_i32_e32 v1, 31, v0
	v_lshlrev_b64 v[0:1], 7, v[0:1]
	v_lshl_add_u64 v[0:1], s[38:39], 0, v[0:1]
	v_lshl_add_u64 v[0:1], v[0:1], 0, v[188:189]
	global_load_dwordx4 v[112:115], v[0:1], off
	global_load_dwordx4 v[116:119], v[0:1], off offset:32
	global_load_dwordx4 v[124:127], v[0:1], off offset:64
	global_load_dwordx4 v[120:123], v[0:1], off offset:96
	v_readlane_b32 s6, v248, 38
	v_readlane_b32 s7, v248, 39
	s_waitcnt vmcnt(3)
	v_and_b32_e32 v3, 0xffff0000, v112
	v_lshlrev_b32_e32 v2, 16, v112
	v_mul_f32_e32 v3, v3, v3
	v_fmac_f32_e32 v3, v2, v2
	v_lshlrev_b32_e32 v2, 16, v113
	v_fmac_f32_e32 v3, v2, v2
	v_and_b32_e32 v2, 0xffff0000, v113
	v_fmac_f32_e32 v3, v2, v2
	v_lshlrev_b32_e32 v2, 16, v114
	v_fmac_f32_e32 v3, v2, v2
	v_and_b32_e32 v2, 0xffff0000, v114
	v_fmac_f32_e32 v3, v2, v2
	v_lshlrev_b32_e32 v2, 16, v115
	v_fmac_f32_e32 v3, v2, v2
	v_and_b32_e32 v2, 0xffff0000, v115
	v_fmac_f32_e32 v3, v2, v2
	s_waitcnt vmcnt(2)
	v_lshlrev_b32_e32 v2, 16, v116
	v_fmac_f32_e32 v3, v2, v2
	v_and_b32_e32 v2, 0xffff0000, v116
	v_fmac_f32_e32 v3, v2, v2
	v_lshlrev_b32_e32 v2, 16, v117
	v_fmac_f32_e32 v3, v2, v2
	v_and_b32_e32 v2, 0xffff0000, v117
	v_fmac_f32_e32 v3, v2, v2
	v_lshlrev_b32_e32 v2, 16, v118
	v_fmac_f32_e32 v3, v2, v2
	v_and_b32_e32 v2, 0xffff0000, v118
	v_fmac_f32_e32 v3, v2, v2
	v_lshlrev_b32_e32 v2, 16, v119
	v_fmac_f32_e32 v3, v2, v2
	v_and_b32_e32 v2, 0xffff0000, v119
	v_fmac_f32_e32 v3, v2, v2
	s_waitcnt vmcnt(1)
; DI float bf2f(unsigned v) { return __uint_as_float(v << 16); }
; DI f32x16 zero16() { f32x16 z; for (int i = 0; i < 16; ++i) z[i] = 0.f; return z; }
; DI void attn_item(const P& p, int l, int item, char* smem) {
;     ...
;       for (int j = 0; j < 8; ++j) { const float v = bf2f((unsigned)(u16)qf[ks][j]); q2 += v * v; }
;     }
;     q2 += __shfl_xor(q2, 32);
;     const float k2 = __uint_as_float(p.kmax[bh * 2 + c]);
;     negm = -(sqrtf(q2 * k2) * 1.01f + 1e-3f);
;   }
;   f32x16 O[4];
; #pragma unroll
;   for (int eb = 0; eb < 4; ++eb) O[eb] = zero16();
;   float ls = 0.f;
;   u32x4 kreg[2], vreg[2];
;   const u16* kbase = p.Kb + (size_t)(bh * 2) * SEQ * 64;
;   const u16* vbase = p.VT + (size_t)(bh * 128) * VTP;
; #pragma unroll
;   for (int i = 0; i < 2; ++i) kreg[i] = *(const u32x4*)(kbase + ((size_t)i * SEQ) * 64 + tid * 8);
; #pragma unroll
;   for (int i = 0; i < 2; ++i) {
;     const int cid = tid + NT * i;
;     const int e = cid >> 3, kc = cid & 7;
;     vreg[i] = *(const u32x4*)(vbase + (size_t)e * VTP + kc * 8);
;   }
;   for (int kt = -1; kt < 128; ++kt) {
;     if (kt + 1 < 128) {
;       u16* Kd = Ks + ((kt + 1) & 1) * (256 * 72);
;       u16* Vd = Kd + 2 * 64 * 72;
; #pragma unroll
;       for (int i = 0; i < 2; ++i) {
;         const int row = tid >> 3, kc = tid & 7;
;         *(u32x4*)(Kd + (i * 64 + row) * 72 + kc * 8) = kreg[i];
;       }
; #pragma unroll
;       for (int i = 0; i < 2; ++i) {
;         const int cid = tid + NT * i;
;         const int e = cid >> 3, kc = cid & 7;
;         uint2 w0; w0.x = vreg[i][0]; w0.y = vreg[i][1];
;         uint2 w1; w1.x = vreg[i][2]; w1.y = vreg[i][3];
;         u16* vd = Vd + e * 72 + (kc >> 1) * 16 + (kc & 1) * 4;
;         *(uint2*)vd = w0;
;         *(uint2*)(vd + 8) = w1;
;       }
	v_lshlrev_b32_e32 v2, 16, v124
	v_fmac_f32_e32 v3, v2, v2
	v_and_b32_e32 v2, 0xffff0000, v124
	v_fmac_f32_e32 v3, v2, v2
	v_lshlrev_b32_e32 v2, 16, v125
	v_fmac_f32_e32 v3, v2, v2
	v_and_b32_e32 v2, 0xffff0000, v125
	v_fmac_f32_e32 v3, v2, v2
	v_lshlrev_b32_e32 v2, 16, v126
	v_fmac_f32_e32 v3, v2, v2
	v_and_b32_e32 v2, 0xffff0000, v126
	v_fmac_f32_e32 v3, v2, v2
	v_lshlrev_b32_e32 v2, 16, v127
	v_fmac_f32_e32 v3, v2, v2
	v_and_b32_e32 v2, 0xffff0000, v127
	v_fmac_f32_e32 v3, v2, v2
	s_waitcnt vmcnt(0)
	v_lshlrev_b32_e32 v0, 16, v120
	v_fmac_f32_e32 v3, v0, v0
	v_and_b32_e32 v0, 0xffff0000, v120
	v_fmac_f32_e32 v3, v0, v0
	v_and_b32_e32 v1, 0xffff0000, v121
	v_lshlrev_b32_e32 v0, 16, v121
	v_pk_mul_f32 v[0:1], v[0:1], v[0:1]
	s_nop 0
	v_add_f32_e32 v0, v0, v3
	v_add_f32_e32 v2, v1, v0
	v_and_b32_e32 v1, 0xffff0000, v122
	v_lshlrev_b32_e32 v0, 16, v122
	v_pk_mul_f32 v[0:1], v[0:1], v[0:1]
	s_nop 0
	v_add_f32_e32 v0, v0, v2
	v_add_f32_e32 v2, v1, v0
	v_and_b32_e32 v1, 0xffff0000, v123
	v_lshlrev_b32_e32 v0, 16, v123
	v_pk_mul_f32 v[0:1], v[0:1], v[0:1]
	s_nop 0
	v_add_f32_e32 v0, v0, v2
	v_add_f32_e32 v0, v1, v0
	ds_bpermute_b32 v1, v158, v0
	s_waitcnt lgkmcnt(0)
	v_add_f32_e32 v2, v0, v1
	v_lshl_add_u32 v0, s12, 1, v160
	v_ashrrev_i32_e32 v1, 31, v0
	v_lshl_add_u64 v[0:1], v[0:1], 2, s[6:7]
	global_load_dword v0, v[0:1], off
	s_mov_b32 s6, 0xf800000
	s_waitcnt vmcnt(0)
	v_mul_f32_e32 v0, v0, v2
	v_cmp_gt_f32_e32 vcc, s6, v0
	v_mul_f32_e32 v1, 0x4f800000, v0
	s_nop 0
	v_cndmask_b32_e32 v0, v0, v1, vcc
	v_sqrt_f32_e32 v1, v0
	s_nop 0
	v_add_u32_e32 v2, -1, v1
	v_fma_f32 v3, -v2, v1, v0
	v_cmp_ge_f32_e64 s[6:7], 0, v3
	v_add_u32_e32 v3, 1, v1
	s_nop 0
	v_cndmask_b32_e64 v2, v1, v2, s[6:7]
	v_fma_f32 v1, -v3, v1, v0
	v_cmp_lt_f32_e64 s[6:7], 0, v1
	s_nop 1
	v_cndmask_b32_e64 v1, v2, v3, s[6:7]
	v_mul_f32_e32 v2, 0x37800000, v1
	v_cndmask_b32_e32 v1, v1, v2, vcc
	v_cmp_class_f32_e32 vcc, v0, v208
	s_lshl_b32 s6, s12, 21
	s_add_u32 s6, s40, s6
	v_cndmask_b32_e32 v0, v1, v0, vcc
	v_fmamk_f32 v2, v0, 0x3f8147ae, v209
	v_lshlrev_b32_e32 v0, 3, v161
	v_ashrrev_i32_e32 v1, 31, v0
	s_addc_u32 s7, s41, 0
	v_lshlrev_b64 v[32:33], 1, v[0:1]
	v_lshl_add_u64 v[22:23], s[6:7], 0, v[32:33]
	s_mul_i32 s6, s12, 0x204000
	s_add_u32 s6, s42, s6
	v_and_b32_e32 v1, 56, v0
	s_addc_u32 s7, s43, 0
	v_lshlrev_b32_e32 v142, 1, v1
	v_add_u32_e32 v1, 0x200, v161
	v_lshl_add_u64 v[4:5], s[6:7], 0, v[142:143]
	v_ashrrev_i32_e32 v25, 3, v1
	v_mad_i64_i32 v[34:35], s[6:7], v24, s14, 0
	v_mad_i64_i32 v[36:37], s[6:7], v25, s14, 0
	v_mad_i64_i32 v[18:19], s[6:7], v25, s14, v[4:5]
	v_mad_i64_i32 v[20:21], s[6:7], v24, s14, v[4:5]
	s_mov_b32 s6, 0x100000
	s_nop 0
	v_add_co_u32_e32 v8, vcc, s6, v22
	v_and_b32_e32 v26, 48, v0
	v_lshlrev_b32_e32 v0, 2, v161
	v_addc_co_u32_e32 v9, vcc, 0, v23, vcc
	v_xor_b32_e32 v16, 0x80000000, v2
	v_and_b32_e32 v27, 4, v0
	global_load_dwordx4 v[0:3], v[18:19], off
	global_load_dwordx4 v[4:7], v[20:21], off
	s_nop 0
	global_load_dwordx4 v[8:11], v[8:9], off
	s_nop 0
	global_load_dwordx4 v[12:15], v[22:23], off
	v_add_u32_e32 v28, 0, v142
	v_add_u32_e32 v168, v28, v170
	v_lshlrev_b32_e32 v171, 1, v26
	v_lshlrev_b32_e32 v172, 1, v27
	s_waitcnt vmcnt(0)
	ds_write_b128 v168, v[12:15]
	ds_write_b128 v168, v[8:11] offset:9216
	v_add3_u32 v8, 0, v171, v172
	v_add_u32_e32 v169, v8, v170
	v_mul_lo_u32 v173, v25, s94
	v_add_u32_e32 v9, 0x4800, v169
	v_add_u32_e32 v143, v8, v173
	ds_write2_b64 v9, v[4:5], v[6:7] offset1:2
	v_add_u32_e32 v4, 0x4800, v143
	ds_write2_b64 v4, v[0:1], v[2:3] offset1:2
	v_add_co_u32_e32 v0, vcc, s65, v22
	s_mov_b32 s6, 0x102000
	s_nop 0
	v_addc_co_u32_e32 v1, vcc, 0, v23, vcc
	global_load_dwordx4 v[228:231], v[0:1], off
	v_add_co_u32_e32 v0, vcc, s6, v22
	v_lshlrev_b32_e32 v2, 4, v161
	s_nop 0
	v_addc_co_u32_e32 v1, vcc, 0, v23, vcc
	global_load_dwordx4 v[232:235], v[0:1], off
	global_load_dwordx4 v[236:239], v[20:21], off offset:128
	global_load_dwordx4 v[240:243], v[18:19], off offset:128
	v_lshl_or_b32 v0, v160, 6, v17
	v_mul_lo_u32 v175, v0, s94
	v_mad_u64_u32 v[0:1], s[6:7], s13, v219, v[36:37]
	v_and_b32_e32 v2, 0x70, v2
	v_or_b32_e32 v0, v0, v2
	v_lshl_add_u64 v[144:145], s[70:71], 0, v[0:1]
	v_mad_u64_u32 v[0:1], s[6:7], s13, v219, v[34:35]
	v_readlane_b32 s6, v248, 42
	s_add_u32 s6, s6, s11
	v_readlane_b32 s7, v248, 43
	v_or_b32_e32 v0, v0, v2
	s_addc_u32 s7, s7, 0
	v_mov_b32_e32 v17, v16
	v_mov_b32_e32 v18, v16
	v_mov_b32_e32 v19, v16
	v_mov_b32_e32 v20, v16
	v_mov_b32_e32 v21, v16
	v_mov_b32_e32 v22, v16
	v_mov_b32_e32 v23, v16
	v_mov_b32_e32 v24, v16
	v_mov_b32_e32 v25, v16
	v_mov_b32_e32 v26, v16
	v_mov_b32_e32 v27, v16
	v_mov_b32_e32 v28, v16
	v_mov_b32_e32 v29, v16
	v_mov_b32_e32 v30, v16
	v_mov_b32_e32 v31, v16
	v_lshl_add_u64 v[146:147], s[70:71], 0, v[0:1]
	v_lshl_add_u64 v[148:149], s[6:7], 0, v[32:33]
	v_mov_b32_e32 v0, 0
	v_mov_b32_e32 v1, v167
	v_mov_b32_e32 v2, v167
	v_mov_b32_e32 v3, v167
	v_mov_b32_e32 v4, v167
	v_mov_b32_e32 v5, v167
	v_mov_b32_e32 v6, v167
	v_mov_b32_e32 v7, v167
	v_mov_b32_e32 v8, v167
	v_mov_b32_e32 v9, v167
	v_mov_b32_e32 v10, v167
	v_mov_b32_e32 v11, v167
	v_mov_b32_e32 v12, v167
	v_mov_b32_e32 v13, v167
	v_mov_b32_e32 v14, v167
	v_mov_b32_e32 v15, v167
	v_mov_b32_e32 v32, 0
	v_mov_b32_e32 v33, v167
	v_mov_b32_e32 v34, v167
	v_mov_b32_e32 v35, v167
	v_mov_b32_e32 v36, v167
	v_mov_b32_e32 v37, v167
	s_waitcnt lgkmcnt(0)
	s_barrier
; #define MFMA(a, b, c) __builtin_amdgcn_mfma_f32_32x32x16_bf16((a), (b), (c), 0, 0, 0)
; DI void attn_item(const P& p, int l, int item, char* smem) {
;     ...
;         *(u32x4*)(Kd + (i * 64 + row) * 72 + kc * 8) = kreg[i];
;       }
; #pragma unroll
;       for (int i = 0; i < 2; ++i) {
;         const int cid = tid + NT * i;
;         const int e = cid >> 3, kc = cid & 7;
;         uint2 w0; w0.x = vreg[i][0]; w0.y = vreg[i][1];
;         uint2 w1; w1.x = vreg[i][2]; w1.y = vreg[i][3];
;         u16* vd = Vd + e * 72 + (kc >> 1) * 16 + (kc & 1) * 4;
;         *(uint2*)vd = w0;
;         *(uint2*)(vd + 8) = w1;
;     ...
;     if (kt >= 0) {
;       const u16* Kc = Ks + (kt & 1) * (256 * 72);
;       const u16* Vc = Kc + 2 * 64 * 72;
;       bf16x8 kf[8];
; #pragma unroll
;       for (int i = 0; i < 8; ++i)
;         kf[i] = *(const bf16x8*)(Kc + (c * 64 + 32 * (i & 1) + li) * 72 + 16 * (i >> 1) + 8 * g);
;       u32x4 vf[16];
; #pragma unroll
;       for (int i = 0; i < 16; ++i) {
;         const int eb = i & 3, s = (i >> 2) & 1, kb = i >> 3;
;         vf[i] = *(const u32x4*)(Vc + (32 * eb + li) * 72 + 32 * kb + 16 * s + 8 * g);
;       }
;       f32x16 S[2];
; #pragma unroll
;       for (int kb = 0; kb < 2; ++kb)
; #pragma unroll
;         for (int r = 0; r < 16; ++r) S[kb][r] = negm;
; #pragma unroll
;       for (int i = 0; i < 8; ++i) S[i & 1] = MFMA(kf[i], qf[i >> 1], S[i & 1]);
;       u32x4 pk[4];
;       float sum = 0.f;
; #pragma unroll
;       for (int ch = 0; ch < 4; ++ch) {
;         const int kb = ch >> 1, s = ch & 1;
; #pragma unroll
;         for (int j2 = 0; j2 < 4; ++j2) {
;           const float p0 = __builtin_amdgcn_exp2f(S[kb][8 * s + 2 * j2]);
;           const float p1 = __builtin_amdgcn_exp2f(S[kb][8 * s + 2 * j2 + 1]);
;           sum += p0 + p1;
;           pk[ch][j2] = pack2(p0, p1);
;         }
;       }
;       ls += sum;
; #pragma unroll
;       for (int i = 0; i < 16; ++i) {
;         const int eb = i & 3, ch = i >> 2;
;         O[eb] = MFMA(__builtin_bit_cast(bf16x8, vf[i]), __builtin_bit_cast(bf16x8, pk[ch]), O[eb]);
;       }
	v_add_u32_e32 v150, v175, v188
	v_add_u32_e32 v151, v174, v188
	s_mov_b32 s10, 0xfff00000
	v_add_co_u32_e32 v156, vcc, s10, v148
	v_add_u32_e32 v151, 0x4800, v151
	s_mov_b64 s[14:15], 0x2000
	v_addc_co_u32_e32 v157, vcc, -1, v149, vcc
	v_mov_b32_e32 v190, 0
	v_mov_b32_e32 v191, 0
	v_mov_b32_e32 v196, 0
	s_movk_i32 s10, 63
	ds_read_b128 v[128:131], v150 offset:0
	ds_read_b128 v[132:135], v150 offset:32
	ds_read_b128 v[136:139], v150 offset:64
	ds_read_b128 v[152:155], v150 offset:96
	ds_read_b128 v[224:227], v150 offset:4608
	ds_read_b128 v[244:247], v150 offset:4640
	s_waitcnt lgkmcnt(4)
	v_mfma_f32_32x32x16_bf16 v[96:111], v[128:131], v[112:115], v[16:31]
	ds_read_b128 v[128:131], v150 offset:4672
	v_mfma_f32_32x32x16_bf16 v[96:111], v[132:135], v[116:119], v[96:111]
	ds_read_b128 v[132:135], v150 offset:4704
	s_waitcnt lgkmcnt(4)
	v_mfma_f32_32x32x16_bf16 v[96:111], v[136:139], v[124:127], v[96:111]
	ds_read_b128 v[136:139], v151 offset:0
	v_mfma_f32_32x32x16_bf16 v[96:111], v[152:155], v[120:123], v[96:111]
	ds_read_b128 v[152:155], v151 offset:4608
	s_waitcnt lgkmcnt(4)
	v_mfma_f32_32x32x16_bf16 v[80:95], v[224:227], v[112:115], v[16:31]
	ds_read_b128 v[224:227], v151 offset:9216
	v_mfma_f32_32x32x16_bf16 v[80:95], v[244:247], v[116:119], v[80:95]
	ds_read_b128 v[244:247], v151 offset:13824
	s_nop 6
	v_exp_f32_e32 v96, v96
	v_exp_f32_e32 v97, v97
	s_waitcnt lgkmcnt(4)
	v_mfma_f32_32x32x16_bf16 v[80:95], v[128:131], v[124:127], v[80:95]
	ds_read_b128 v[128:131], v151 offset:32
	v_exp_f32_e32 v98, v98
	v_exp_f32_e32 v99, v99
	v_exp_f32_e32 v100, v100
	v_mfma_f32_32x32x16_bf16 v[80:95], v[132:135], v[120:123], v[80:95]
	ds_read_b128 v[132:135], v151 offset:4640
	v_exp_f32_e32 v101, v101
	v_exp_f32_e32 v102, v102
	v_exp_f32_e32 v103, v103
	v_add_f32_e32 v167, v167, v96
	v_add_f32_e32 v190, v190, v97
	v_add_f32_e32 v191, v191, v98
	v_cvt_pk_bf16_f32 v176, v96, v97
	v_cvt_pk_bf16_f32 v177, v98, v99
	v_cvt_pk_bf16_f32 v178, v100, v101
	v_cvt_pk_bf16_f32 v179, v102, v103
	v_add_f32_e32 v196, v196, v99
	v_add_f32_e32 v167, v167, v100
	v_add_f32_e32 v190, v190, v101
	v_add_f32_e32 v191, v191, v102
	v_add_f32_e32 v196, v196, v103
.Lat_loop:
	s_waitcnt lgkmcnt(4)
	v_mfma_f32_32x32x16_bf16 v[64:79], v[136:139], v[176:179], v[64:79]
	ds_read_b128 v[136:139], v151 offset:9248
	v_exp_f32_e32 v104, v104
	v_exp_f32_e32 v105, v105
	v_mfma_f32_32x32x16_bf16 v[48:63], v[152:155], v[176:179], v[48:63]
	ds_read_b128 v[152:155], v151 offset:13856
	v_exp_f32_e32 v106, v106
	v_exp_f32_e32 v107, v107
	v_cvt_pk_bf16_f32 v180, v104, v105
	s_waitcnt lgkmcnt(4)
	v_mfma_f32_32x32x16_bf16 v[32:47], v[224:227], v[176:179], v[32:47]
	ds_read_b128 v[224:227], v151 offset:64
	v_exp_f32_e32 v108, v108
	v_exp_f32_e32 v109, v109
	v_cvt_pk_bf16_f32 v181, v106, v107
	v_mfma_f32_32x32x16_bf16 v[0:15], v[244:247], v[176:179], v[0:15]
	ds_read_b128 v[244:247], v151 offset:4672
	v_exp_f32_e32 v110, v110
	v_exp_f32_e32 v111, v111
	v_cvt_pk_bf16_f32 v182, v108, v109
	v_cvt_pk_bf16_f32 v183, v110, v111
	s_nop 0
	s_waitcnt lgkmcnt(4)
	v_mfma_f32_32x32x16_bf16 v[64:79], v[128:131], v[180:183], v[64:79]
	ds_read_b128 v[128:131], v151 offset:9280
	v_exp_f32_e32 v80, v80
	v_exp_f32_e32 v81, v81
	v_mfma_f32_32x32x16_bf16 v[48:63], v[132:135], v[180:183], v[48:63]
	ds_read_b128 v[132:135], v151 offset:13888
	v_exp_f32_e32 v82, v82
	v_exp_f32_e32 v83, v83
	v_cvt_pk_bf16_f32 v184, v80, v81
	s_waitcnt lgkmcnt(4)
	v_mfma_f32_32x32x16_bf16 v[32:47], v[136:139], v[180:183], v[32:47]
	ds_read_b128 v[136:139], v151 offset:96
	v_exp_f32_e32 v84, v84
	v_exp_f32_e32 v85, v85
	v_cvt_pk_bf16_f32 v185, v82, v83
	v_mfma_f32_32x32x16_bf16 v[0:15], v[152:155], v[180:183], v[0:15]
	ds_read_b128 v[152:155], v151 offset:4704
	v_exp_f32_e32 v86, v86
	v_exp_f32_e32 v87, v87
	v_cvt_pk_bf16_f32 v186, v84, v85
	v_cvt_pk_bf16_f32 v187, v86, v87
	s_nop 0
	s_waitcnt lgkmcnt(4)
	v_mfma_f32_32x32x16_bf16 v[64:79], v[224:227], v[184:187], v[64:79]
	ds_read_b128 v[224:227], v151 offset:9312
	v_exp_f32_e32 v88, v88
	v_exp_f32_e32 v89, v89
	v_mfma_f32_32x32x16_bf16 v[48:63], v[244:247], v[184:187], v[48:63]
	ds_read_b128 v[244:247], v151 offset:13920
	v_exp_f32_e32 v90, v90
	v_exp_f32_e32 v91, v91
	v_cvt_pk_bf16_f32 v192, v88, v89
	s_waitcnt lgkmcnt(4)
	v_mfma_f32_32x32x16_bf16 v[32:47], v[128:131], v[184:187], v[32:47]
	v_exp_f32_e32 v92, v92
	v_exp_f32_e32 v93, v93
	v_cvt_pk_bf16_f32 v193, v90, v91
	s_waitcnt vmcnt(0)
	ds_write_b128 v168, v[228:231] offset:36864
	ds_write_b128 v168, v[232:235] offset:46080
	v_mfma_f32_32x32x16_bf16 v[0:15], v[132:135], v[184:187], v[0:15]
	v_exp_f32_e32 v94, v94
	v_exp_f32_e32 v95, v95
	v_cvt_pk_bf16_f32 v194, v92, v93
	v_cvt_pk_bf16_f32 v195, v94, v95
	s_nop 0
	ds_write_b64 v169, v[236:237] offset:55296
	ds_write_b64 v169, v[238:239] offset:55312
	s_waitcnt lgkmcnt(6)
	v_mfma_f32_32x32x16_bf16 v[64:79], v[136:139], v[192:195], v[64:79]
	v_add_f32_e32 v167, v167, v104
	v_add_f32_e32 v190, v190, v105
	v_add_f32_e32 v191, v191, v106
	v_add_f32_e32 v196, v196, v107
	ds_write_b64 v143, v[240:241] offset:55296
	ds_write_b64 v143, v[242:243] offset:55312
	v_mfma_f32_32x32x16_bf16 v[48:63], v[152:155], v[192:195], v[48:63]
	v_add_f32_e32 v167, v167, v108
	v_add_f32_e32 v190, v190, v109
	v_add_f32_e32 v191, v191, v110
	v_add_f32_e32 v196, v196, v111
	s_waitcnt lgkmcnt(6)
	v_mfma_f32_32x32x16_bf16 v[32:47], v[224:227], v[192:195], v[32:47]
	v_add_f32_e32 v167, v167, v80
	v_add_f32_e32 v190, v190, v81
	v_add_f32_e32 v191, v191, v82
	v_add_f32_e32 v196, v196, v83
	v_mfma_f32_32x32x16_bf16 v[0:15], v[244:247], v[192:195], v[0:15]
	v_add_f32_e32 v167, v167, v84
	v_add_f32_e32 v190, v190, v85
	v_add_f32_e32 v191, v191, v86
	v_add_f32_e32 v196, v196, v87
	s_waitcnt lgkmcnt(0)
	s_barrier
; DI void attn_item(const P& p, int l, int item, char* smem) {
;     ...
;         *(u32x4*)(Kd + (i * 64 + row) * 72 + kc * 8) = kreg[i];
;       }
; #pragma unroll
;       for (int i = 0; i < 2; ++i) {
;         const int cid = tid + NT * i;
;         const int e = cid >> 3, kc = cid & 7;
;         uint2 w0; w0.x = vreg[i][0]; w0.y = vreg[i][1];
;         uint2 w1; w1.x = vreg[i][2]; w1.y = vreg[i][3];
;         u16* vd = Vd + e * 72 + (kc >> 1) * 16 + (kc & 1) * 4;
;         *(uint2*)vd = w0;
;         *(uint2*)(vd + 8) = w1;
;       }
;     }
;     if (kt + 2 < 128) {
;       const int kn = kt + 2;
; #pragma unroll
;       for (int i = 0; i < 2; ++i) kreg[i] = *(const u32x4*)(kbase + ((size_t)i * SEQ + kn * 64) * 64 + tid * 8);
; #pragma unroll
;       for (int i = 0; i < 2; ++i) {
;         const int cid = tid + NT * i;
;         const int e = cid >> 3, kc = cid & 7;
;     ...
;     if (kt >= 0) {
;       const u16* Kc = Ks + (kt & 1) * (256 * 72);
;       const u16* Vc = Kc + 2 * 64 * 72;
;       bf16x8 kf[8];
; #pragma unroll
;       for (int i = 0; i < 8; ++i)
;         kf[i] = *(const bf16x8*)(Kc + (c * 64 + 32 * (i & 1) + li) * 72 + 16 * (i >> 1) + 8 * g);
;       u32x4 vf[16];
; #pragma unroll
;       for (int i = 0; i < 16; ++i) {
;         const int eb = i & 3, s = (i >> 2) & 1, kb = i >> 3;
;         vf[i] = *(const u32x4*)(Vc + (32 * eb + li) * 72 + 32 * kb + 16 * s + 8 * g);
;       }
;       f32x16 S[2];
; #pragma unroll
;       for (int kb = 0; kb < 2; ++kb)
; #pragma unroll
;         for (int r = 0; r < 16; ++r) S[kb][r] = negm;
; #pragma unroll
;       for (int i = 0; i < 8; ++i) S[i & 1] = MFMA(kf[i], qf[i >> 1], S[i & 1]);
;       u32x4 pk[4];
;       float sum = 0.f;
; #pragma unroll
;       for (int ch = 0; ch < 4; ++ch) {
;         const int kb = ch >> 1, s = ch & 1;
; #pragma unroll
;         for (int j2 = 0; j2 < 4; ++j2) {
;           const float p0 = __builtin_amdgcn_exp2f(S[kb][8 * s + 2 * j2]);
;           const float p1 = __builtin_amdgcn_exp2f(S[kb][8 * s + 2 * j2 + 1]);
;           sum += p0 + p1;
;           pk[ch][j2] = pack2(p0, p1);
;         }
;       }
;       ls += sum;
; #pragma unroll
;       for (int i = 0; i < 16; ++i) {
;         const int eb = i & 3, ch = i >> 2;
;         O[eb] = MFMA(__builtin_bit_cast(bf16x8, vf[i]), __builtin_bit_cast(bf16x8, pk[ch]), O[eb]);
;       }
;     }
;     __syncthreads();
	ds_read_b128 v[128:131], v150 offset:36864
	ds_read_b128 v[132:135], v150 offset:36896
	ds_read_b128 v[136:139], v150 offset:36928
	ds_read_b128 v[152:155], v150 offset:36960
	ds_read_b128 v[224:227], v150 offset:41472
	ds_read_b128 v[244:247], v150 offset:41504
	global_load_dwordx4 v[232:235], v[148:149], off
	global_load_dwordx4 v[228:231], v[156:157], off
	global_load_dwordx4 v[236:239], v[146:147], off
	global_load_dwordx4 v[240:243], v[144:145], off
	s_waitcnt lgkmcnt(4)
	v_mfma_f32_32x32x16_bf16 v[96:111], v[128:131], v[112:115], v[16:31]
	ds_read_b128 v[128:131], v150 offset:41536
	v_add_f32_e32 v167, v167, v88
	v_add_f32_e32 v190, v190, v89
	v_mfma_f32_32x32x16_bf16 v[96:111], v[132:135], v[116:119], v[96:111]
	ds_read_b128 v[132:135], v150 offset:41568
	v_add_f32_e32 v191, v191, v90
	v_add_f32_e32 v196, v196, v91
	s_waitcnt lgkmcnt(4)
	v_mfma_f32_32x32x16_bf16 v[96:111], v[136:139], v[124:127], v[96:111]
	ds_read_b128 v[136:139], v151 offset:36864
	v_add_f32_e32 v167, v167, v92
	v_add_f32_e32 v190, v190, v93
	v_mfma_f32_32x32x16_bf16 v[96:111], v[152:155], v[120:123], v[96:111]
	ds_read_b128 v[152:155], v151 offset:41472
	v_add_f32_e32 v191, v191, v94
	v_add_f32_e32 v196, v196, v95
	v_lshl_add_u64 v[148:149], v[148:149], 0, s[14:15]
	v_lshl_add_u64 v[156:157], v[156:157], 0, s[14:15]
	s_waitcnt lgkmcnt(4)
	v_mfma_f32_32x32x16_bf16 v[80:95], v[224:227], v[112:115], v[16:31]
	ds_read_b128 v[224:227], v151 offset:46080
	v_lshl_add_u64 v[146:147], v[146:147], 0, s[58:59]
	v_lshl_add_u64 v[144:145], v[144:145], 0, s[58:59]
	v_mfma_f32_32x32x16_bf16 v[80:95], v[244:247], v[116:119], v[80:95]
	ds_read_b128 v[244:247], v151 offset:50688
	s_nop 2
	v_exp_f32_e32 v96, v96
	v_exp_f32_e32 v97, v97
	s_waitcnt lgkmcnt(4)
	v_mfma_f32_32x32x16_bf16 v[80:95], v[128:131], v[124:127], v[80:95]
	ds_read_b128 v[128:131], v151 offset:36896
	v_exp_f32_e32 v98, v98
	v_exp_f32_e32 v99, v99
	v_exp_f32_e32 v100, v100
	v_mfma_f32_32x32x16_bf16 v[80:95], v[132:135], v[120:123], v[80:95]
	ds_read_b128 v[132:135], v151 offset:41504
	v_exp_f32_e32 v101, v101
	v_exp_f32_e32 v102, v102
	v_exp_f32_e32 v103, v103
	v_add_f32_e32 v167, v167, v96
	v_add_f32_e32 v190, v190, v97
	v_add_f32_e32 v191, v191, v98
	v_cvt_pk_bf16_f32 v176, v96, v97
	v_cvt_pk_bf16_f32 v177, v98, v99
	v_cvt_pk_bf16_f32 v178, v100, v101
	v_cvt_pk_bf16_f32 v179, v102, v103
	v_add_f32_e32 v196, v196, v99
	v_add_f32_e32 v167, v167, v100
	v_add_f32_e32 v190, v190, v101
	v_add_f32_e32 v191, v191, v102
	v_add_f32_e32 v196, v196, v103
	s_waitcnt lgkmcnt(4)
	v_mfma_f32_32x32x16_bf16 v[64:79], v[136:139], v[176:179], v[64:79]
	ds_read_b128 v[136:139], v151 offset:46112
	v_exp_f32_e32 v104, v104
	v_exp_f32_e32 v105, v105
	v_mfma_f32_32x32x16_bf16 v[48:63], v[152:155], v[176:179], v[48:63]
	ds_read_b128 v[152:155], v151 offset:50720
	v_exp_f32_e32 v106, v106
	v_exp_f32_e32 v107, v107
	v_cvt_pk_bf16_f32 v180, v104, v105
	s_waitcnt lgkmcnt(4)
	v_mfma_f32_32x32x16_bf16 v[32:47], v[224:227], v[176:179], v[32:47]
	ds_read_b128 v[224:227], v151 offset:36928
	v_exp_f32_e32 v108, v108
	v_exp_f32_e32 v109, v109
	v_cvt_pk_bf16_f32 v181, v106, v107
	v_mfma_f32_32x32x16_bf16 v[0:15], v[244:247], v[176:179], v[0:15]
	ds_read_b128 v[244:247], v151 offset:41536
	v_exp_f32_e32 v110, v110
	v_exp_f32_e32 v111, v111
	v_cvt_pk_bf16_f32 v182, v108, v109
	v_cvt_pk_bf16_f32 v183, v110, v111
	s_nop 0
	s_waitcnt lgkmcnt(4)
	v_mfma_f32_32x32x16_bf16 v[64:79], v[128:131], v[180:183], v[64:79]
	ds_read_b128 v[128:131], v151 offset:46144
	v_exp_f32_e32 v80, v80
	v_exp_f32_e32 v81, v81
	v_mfma_f32_32x32x16_bf16 v[48:63], v[132:135], v[180:183], v[48:63]
	ds_read_b128 v[132:135], v151 offset:50752
	v_exp_f32_e32 v82, v82
	v_exp_f32_e32 v83, v83
	v_cvt_pk_bf16_f32 v184, v80, v81
	s_waitcnt lgkmcnt(4)
	v_mfma_f32_32x32x16_bf16 v[32:47], v[136:139], v[180:183], v[32:47]
	ds_read_b128 v[136:139], v151 offset:36960
	v_exp_f32_e32 v84, v84
	v_exp_f32_e32 v85, v85
	v_cvt_pk_bf16_f32 v185, v82, v83
	v_mfma_f32_32x32x16_bf16 v[0:15], v[152:155], v[180:183], v[0:15]
	ds_read_b128 v[152:155], v151 offset:41568
	v_exp_f32_e32 v86, v86
	v_exp_f32_e32 v87, v87
	v_cvt_pk_bf16_f32 v186, v84, v85
	v_cvt_pk_bf16_f32 v187, v86, v87
	s_nop 0
	s_waitcnt lgkmcnt(4)
	v_mfma_f32_32x32x16_bf16 v[64:79], v[224:227], v[184:187], v[64:79]
	ds_read_b128 v[224:227], v151 offset:46176
	v_exp_f32_e32 v88, v88
	v_exp_f32_e32 v89, v89
	v_mfma_f32_32x32x16_bf16 v[48:63], v[244:247], v[184:187], v[48:63]
	ds_read_b128 v[244:247], v151 offset:50784
	v_exp_f32_e32 v90, v90
	v_exp_f32_e32 v91, v91
	v_cvt_pk_bf16_f32 v192, v88, v89
	s_waitcnt lgkmcnt(4)
	v_mfma_f32_32x32x16_bf16 v[32:47], v[128:131], v[184:187], v[32:47]
	v_exp_f32_e32 v92, v92
	v_exp_f32_e32 v93, v93
	v_cvt_pk_bf16_f32 v193, v90, v91
	s_waitcnt vmcnt(0)
	ds_write_b128 v168, v[228:231] offset:0
	ds_write_b128 v168, v[232:235] offset:9216
	v_mfma_f32_32x32x16_bf16 v[0:15], v[132:135], v[184:187], v[0:15]
	v_exp_f32_e32 v94, v94
	v_exp_f32_e32 v95, v95
	v_cvt_pk_bf16_f32 v194, v92, v93
	v_cvt_pk_bf16_f32 v195, v94, v95
	s_nop 0
	ds_write_b64 v169, v[236:237] offset:18432
	ds_write_b64 v169, v[238:239] offset:18448
	s_waitcnt lgkmcnt(6)
	v_mfma_f32_32x32x16_bf16 v[64:79], v[136:139], v[192:195], v[64:79]
	v_add_f32_e32 v167, v167, v104
	v_add_f32_e32 v190, v190, v105
	v_add_f32_e32 v191, v191, v106
	v_add_f32_e32 v196, v196, v107
	ds_write_b64 v143, v[240:241] offset:18432
	ds_write_b64 v143, v[242:243] offset:18448
	v_mfma_f32_32x32x16_bf16 v[48:63], v[152:155], v[192:195], v[48:63]
	v_add_f32_e32 v167, v167, v108
	v_add_f32_e32 v190, v190, v109
	v_add_f32_e32 v191, v191, v110
	v_add_f32_e32 v196, v196, v111
	s_waitcnt lgkmcnt(6)
	v_mfma_f32_32x32x16_bf16 v[32:47], v[224:227], v[192:195], v[32:47]
	v_add_f32_e32 v167, v167, v80
	v_add_f32_e32 v190, v190, v81
	v_add_f32_e32 v191, v191, v82
	v_add_f32_e32 v196, v196, v83
	v_mfma_f32_32x32x16_bf16 v[0:15], v[244:247], v[192:195], v[0:15]
	v_add_f32_e32 v167, v167, v84
	v_add_f32_e32 v190, v190, v85
	v_add_f32_e32 v191, v191, v86
	v_add_f32_e32 v196, v196, v87
	s_waitcnt lgkmcnt(0)
	s_barrier
; #define MFMA(a, b, c) __builtin_amdgcn_mfma_f32_32x32x16_bf16((a), (b), (c), 0, 0, 0)
; DI void attn_item(const P& p, int l, int item, char* smem) {
;     ...
;         *(u32x4*)(Kd + (i * 64 + row) * 72 + kc * 8) = kreg[i];
;       }
; #pragma unroll
;       for (int i = 0; i < 2; ++i) {
;         const int cid = tid + NT * i;
;         const int e = cid >> 3, kc = cid & 7;
;         uint2 w0; w0.x = vreg[i][0]; w0.y = vreg[i][1];
;         uint2 w1; w1.x = vreg[i][2]; w1.y = vreg[i][3];
;         u16* vd = Vd + e * 72 + (kc >> 1) * 16 + (kc & 1) * 4;
;         *(uint2*)vd = w0;
;         *(uint2*)(vd + 8) = w1;
;       }
;     }
;     if (kt + 2 < 128) {
;       const int kn = kt + 2;
; #pragma unroll
;       for (int i = 0; i < 2; ++i) kreg[i] = *(const u32x4*)(kbase + ((size_t)i * SEQ + kn * 64) * 64 + tid * 8);
;     ...
;     if (kt >= 0) {
;       const u16* Kc = Ks + (kt & 1) * (256 * 72);
;       const u16* Vc = Kc + 2 * 64 * 72;
;       bf16x8 kf[8];
; #pragma unroll
;       for (int i = 0; i < 8; ++i)
;         kf[i] = *(const bf16x8*)(Kc + (c * 64 + 32 * (i & 1) + li) * 72 + 16 * (i >> 1) + 8 * g);
;       u32x4 vf[16];
; #pragma unroll
;       for (int i = 0; i < 16; ++i) {
;         const int eb = i & 3, s = (i >> 2) & 1, kb = i >> 3;
;         vf[i] = *(const u32x4*)(Vc + (32 * eb + li) * 72 + 32 * kb + 16 * s + 8 * g);
;       }
;       f32x16 S[2];
; #pragma unroll
;       for (int kb = 0; kb < 2; ++kb)
; #pragma unroll
;         for (int r = 0; r < 16; ++r) S[kb][r] = negm;
; #pragma unroll
;       for (int i = 0; i < 8; ++i) S[i & 1] = MFMA(kf[i], qf[i >> 1], S[i & 1]);
;       u32x4 pk[4];
;       float sum = 0.f;
; #pragma unroll
;       for (int ch = 0; ch < 4; ++ch) {
;         const int kb = ch >> 1, s = ch & 1;
; #pragma unroll
;         for (int j2 = 0; j2 < 4; ++j2) {
;           const float p0 = __builtin_amdgcn_exp2f(S[kb][8 * s + 2 * j2]);
;           const float p1 = __builtin_amdgcn_exp2f(S[kb][8 * s + 2 * j2 + 1]);
;           sum += p0 + p1;
;           pk[ch][j2] = pack2(p0, p1);
;         }
;       }
;       ls += sum;
; #pragma unroll
;       for (int i = 0; i < 16; ++i) {
;         const int eb = i & 3, ch = i >> 2;
;         O[eb] = MFMA(__builtin_bit_cast(bf16x8, vf[i]), __builtin_bit_cast(bf16x8, pk[ch]), O[eb]);
;       }
	s_add_i32 s10, s10, -1
	s_cmp_eq_u32 s10, 0
	s_cbranch_scc1 .Lat_exit
	ds_read_b128 v[128:131], v150 offset:0
	ds_read_b128 v[132:135], v150 offset:32
	ds_read_b128 v[136:139], v150 offset:64
	ds_read_b128 v[152:155], v150 offset:96
	ds_read_b128 v[224:227], v150 offset:4608
	ds_read_b128 v[244:247], v150 offset:4640
	global_load_dwordx4 v[232:235], v[148:149], off
	global_load_dwordx4 v[228:231], v[156:157], off
	global_load_dwordx4 v[236:239], v[146:147], off
	global_load_dwordx4 v[240:243], v[144:145], off
	s_waitcnt lgkmcnt(4)
	v_mfma_f32_32x32x16_bf16 v[96:111], v[128:131], v[112:115], v[16:31]
	ds_read_b128 v[128:131], v150 offset:4672
	v_add_f32_e32 v167, v167, v88
	v_add_f32_e32 v190, v190, v89
	v_mfma_f32_32x32x16_bf16 v[96:111], v[132:135], v[116:119], v[96:111]
	ds_read_b128 v[132:135], v150 offset:4704
	v_add_f32_e32 v191, v191, v90
	v_add_f32_e32 v196, v196, v91
	s_waitcnt lgkmcnt(4)
	v_mfma_f32_32x32x16_bf16 v[96:111], v[136:139], v[124:127], v[96:111]
	ds_read_b128 v[136:139], v151 offset:0
	v_add_f32_e32 v167, v167, v92
	v_add_f32_e32 v190, v190, v93
	v_mfma_f32_32x32x16_bf16 v[96:111], v[152:155], v[120:123], v[96:111]
	ds_read_b128 v[152:155], v151 offset:4608
	v_add_f32_e32 v191, v191, v94
	v_add_f32_e32 v196, v196, v95
	v_lshl_add_u64 v[148:149], v[148:149], 0, s[14:15]
	v_lshl_add_u64 v[156:157], v[156:157], 0, s[14:15]
	s_waitcnt lgkmcnt(4)
	v_mfma_f32_32x32x16_bf16 v[80:95], v[224:227], v[112:115], v[16:31]
	ds_read_b128 v[224:227], v151 offset:9216
	v_lshl_add_u64 v[146:147], v[146:147], 0, s[58:59]
	v_lshl_add_u64 v[144:145], v[144:145], 0, s[58:59]
	v_mfma_f32_32x32x16_bf16 v[80:95], v[244:247], v[116:119], v[80:95]
	ds_read_b128 v[244:247], v151 offset:13824
	s_nop 2
	v_exp_f32_e32 v96, v96
	v_exp_f32_e32 v97, v97
	s_waitcnt lgkmcnt(4)
	v_mfma_f32_32x32x16_bf16 v[80:95], v[128:131], v[124:127], v[80:95]
	ds_read_b128 v[128:131], v151 offset:32
	v_exp_f32_e32 v98, v98
	v_exp_f32_e32 v99, v99
	v_exp_f32_e32 v100, v100
	v_mfma_f32_32x32x16_bf16 v[80:95], v[132:135], v[120:123], v[80:95]
	ds_read_b128 v[132:135], v151 offset:4640
	v_exp_f32_e32 v101, v101
	v_exp_f32_e32 v102, v102
	v_exp_f32_e32 v103, v103
	v_add_f32_e32 v167, v167, v96
	v_add_f32_e32 v190, v190, v97
	v_add_f32_e32 v191, v191, v98
	v_cvt_pk_bf16_f32 v176, v96, v97
	v_cvt_pk_bf16_f32 v177, v98, v99
	v_cvt_pk_bf16_f32 v178, v100, v101
	v_cvt_pk_bf16_f32 v179, v102, v103
	v_add_f32_e32 v196, v196, v99
	v_add_f32_e32 v167, v167, v100
	v_add_f32_e32 v190, v190, v101
	v_add_f32_e32 v191, v191, v102
	v_add_f32_e32 v196, v196, v103
	s_branch .Lat_loop
.Lat_exit:
	global_load_dwordx4 v[232:235], v[148:149], off
	global_load_dwordx4 v[228:231], v[156:157], off
	global_load_dwordx4 v[236:239], v[146:147], off
	global_load_dwordx4 v[240:243], v[144:145], off
	v_add_f32_e32 v167, v167, v190
	v_add_f32_e32 v191, v191, v196
	s_nop 0
	v_add_f32_e32 v167, v167, v191
	v_add_u32_e32 v80, 0xd800, v169
	s_waitcnt vmcnt(2)
	ds_write_b128 v168, v[228:231] offset:36864
	ds_write_b128 v168, v[232:235] offset:46080
	s_waitcnt vmcnt(1)
	ds_write2_b64 v80, v[236:237], v[238:239] offset1:2
	v_add_u32_e32 v80, 0xd800, v143
	s_waitcnt vmcnt(0)
	ds_write2_b64 v80, v[240:241], v[242:243] offset1:2
	v_add3_u32 v129, 0, v175, v188
	ds_read_b128 v[80:83], v129
	ds_read_b128 v[130:133], v129 offset:4608
	v_add3_u32 v128, 0, v174, v188
	ds_read_b128 v[134:137], v128 offset:18432
	v_readlane_b32 s6, v248, 5
	s_waitcnt lgkmcnt(2)
	v_mfma_f32_32x32x16_bf16 v[96:111], v[80:83], v[112:115], v[16:31]
	s_waitcnt lgkmcnt(1)
	v_mfma_f32_32x32x16_bf16 v[80:95], v[130:133], v[112:115], v[16:31]
	ds_read_b128 v[130:133], v129 offset:32
	s_waitcnt lgkmcnt(0)
	v_mfma_f32_32x32x16_bf16 v[96:111], v[130:133], v[116:119], v[96:111]
	ds_read_b128 v[130:133], v129 offset:4640
	s_waitcnt lgkmcnt(0)
	v_mfma_f32_32x32x16_bf16 v[80:95], v[130:133], v[116:119], v[80:95]
	ds_read_b128 v[130:133], v129 offset:64
	s_waitcnt lgkmcnt(0)
	v_mfma_f32_32x32x16_bf16 v[96:111], v[130:133], v[124:127], v[96:111]
	ds_read_b128 v[130:133], v129 offset:4672
	s_waitcnt lgkmcnt(0)
	v_mfma_f32_32x32x16_bf16 v[80:95], v[130:133], v[124:127], v[80:95]
	ds_read_b128 v[130:133], v129 offset:96
	s_waitcnt lgkmcnt(0)
	v_mfma_f32_32x32x16_bf16 v[96:111], v[130:133], v[120:123], v[96:111]
	ds_read_b128 v[130:133], v129 offset:4704
	s_nop 10
	v_exp_f32_e32 v144, v100
	v_exp_f32_e32 v145, v101
	v_exp_f32_e32 v146, v102
	v_exp_f32_e32 v147, v103
	ds_read_b128 v[100:103], v128 offset:23040
	v_exp_f32_e32 v138, v96
	v_exp_f32_e32 v139, v97
	v_exp_f32_e32 v142, v98
	v_exp_f32_e32 v143, v99
	v_cvt_pk_bf16_f32 v98, v144, v145
	v_cvt_pk_bf16_f32 v96, v138, v139
	v_cvt_pk_bf16_f32 v99, v146, v147
	v_cvt_pk_bf16_f32 v97, v142, v143
	v_exp_f32_e32 v108, v108
	v_exp_f32_e32 v109, v109
	s_waitcnt lgkmcnt(0)
	v_mfma_f32_32x32x16_bf16 v[48:63], v[100:103], v[96:99], v[48:63]
	ds_read_b128 v[100:103], v128 offset:27648
	v_exp_f32_e32 v110, v110
	v_exp_f32_e32 v111, v111
	v_mfma_f32_32x32x16_bf16 v[80:95], v[130:133], v[120:123], v[80:95]
	s_waitcnt lgkmcnt(0)
	v_mfma_f32_32x32x16_bf16 v[32:47], v[100:103], v[96:99], v[32:47]
	ds_read_b128 v[100:103], v128 offset:32256
	ds_read_b128 v[130:133], v128 offset:18464
	s_nop 7
	v_exp_f32_e32 v148, v84
	v_exp_f32_e32 v149, v85
	v_exp_f32_e32 v150, v86
	v_exp_f32_e32 v151, v87
	v_exp_f32_e32 v152, v88
	v_exp_f32_e32 v153, v89
	s_waitcnt lgkmcnt(1)
; #define MFMA(a, b, c) __builtin_amdgcn_mfma_f32_32x32x16_bf16((a), (b), (c), 0, 0, 0)
; DI void attn_item(const P& p, int l, int item, char* smem) {
;     ...
;     lam = __expf(s1) - __expf(s2) + lam_init;
;     ...
;         kf[i] = *(const bf16x8*)(Kc + (c * 64 + 32 * (i & 1) + li) * 72 + 16 * (i >> 1) + 8 * g);
;       u32x4 vf[16];
; #pragma unroll
;       for (int i = 0; i < 16; ++i) {
;         const int eb = i & 3, s = (i >> 2) & 1, kb = i >> 3;
;         vf[i] = *(const u32x4*)(Vc + (32 * eb + li) * 72 + 32 * kb + 16 * s + 8 * g);
;       }
;       f32x16 S[2];
; #pragma unroll
;       for (int kb = 0; kb < 2; ++kb)
; #pragma unroll
;         for (int r = 0; r < 16; ++r) S[kb][r] = negm;
; #pragma unroll
;       for (int i = 0; i < 8; ++i) S[i & 1] = MFMA(kf[i], qf[i >> 1], S[i & 1]);
;       u32x4 pk[4];
;       float sum = 0.f;
; #pragma unroll
;       for (int ch = 0; ch < 4; ++ch) {
;         const int kb = ch >> 1, s = ch & 1;
; #pragma unroll
;         for (int j2 = 0; j2 < 4; ++j2) {
;           const float p0 = __builtin_amdgcn_exp2f(S[kb][8 * s + 2 * j2]);
;           const float p1 = __builtin_amdgcn_exp2f(S[kb][8 * s + 2 * j2 + 1]);
;           sum += p0 + p1;
;           pk[ch][j2] = pack2(p0, p1);
;         }
;       }
;       ls += sum;
; #pragma unroll
;       for (int i = 0; i < 16; ++i) {
;         const int eb = i & 3, ch = i >> 2;
;         O[eb] = MFMA(__builtin_bit_cast(bf16x8, vf[i]), __builtin_bit_cast(bf16x8, pk[ch]), O[eb]);
;       }
	v_mfma_f32_32x32x16_bf16 v[0:15], v[100:103], v[96:99], v[0:15]
	ds_read_b128 v[100:103], v128 offset:23072
	v_exp_f32_e32 v154, v90
	v_exp_f32_e32 v155, v91
	v_exp_f32_e32 v156, v92
	v_exp_f32_e32 v157, v93
	v_exp_f32_e32 v168, v94
	v_exp_f32_e32 v169, v95
	v_mfma_f32_32x32x16_bf16 v[64:79], v[134:137], v[96:99], v[64:79]
	v_exp_f32_e32 v134, v104
	v_exp_f32_e32 v135, v105
	v_exp_f32_e32 v136, v106
	v_exp_f32_e32 v137, v107
	v_cvt_pk_bf16_f32 v98, v108, v109
	v_cvt_pk_bf16_f32 v96, v134, v135
	v_cvt_pk_bf16_f32 v99, v110, v111
	v_cvt_pk_bf16_f32 v97, v136, v137
	v_add_f32_e32 v88, v165, v166
	v_mul_f32_e32 v165, 0x3fb8aa3b, v88
	s_waitcnt lgkmcnt(0)
	v_mfma_f32_32x32x16_bf16 v[48:63], v[100:103], v[96:99], v[48:63]
	ds_read_b128 v[100:103], v128 offset:27680
	v_add_f32_e32 v134, v134, v135
	s_waitcnt lgkmcnt(0)
	v_mfma_f32_32x32x16_bf16 v[32:47], v[100:103], v[96:99], v[32:47]
	ds_read_b128 v[100:103], v128 offset:32288
	ds_read_b128 v[104:107], v128 offset:18496
	ds_read_b128 v[84:87], v128 offset:23104
	v_mfma_f32_32x32x16_bf16 v[64:79], v[130:133], v[96:99], v[64:79]
	v_exp_f32_e32 v130, v80
	v_exp_f32_e32 v131, v81
	v_exp_f32_e32 v132, v82
	v_exp_f32_e32 v133, v83
	v_cvt_pk_bf16_f32 v82, v148, v149
	v_cvt_pk_bf16_f32 v80, v130, v131
	v_cvt_pk_bf16_f32 v83, v150, v151
	v_cvt_pk_bf16_f32 v81, v132, v133
	s_waitcnt lgkmcnt(2)
	v_mfma_f32_32x32x16_bf16 v[0:15], v[100:103], v[96:99], v[0:15]
	s_waitcnt lgkmcnt(0)
	v_mfma_f32_32x32x16_bf16 v[48:63], v[84:87], v[80:83], v[48:63]
	ds_read_b128 v[84:87], v128 offset:27712
	s_waitcnt lgkmcnt(0)
	v_mfma_f32_32x32x16_bf16 v[32:47], v[84:87], v[80:83], v[32:47]
	ds_read_b128 v[84:87], v128 offset:32320
	ds_read_b128 v[96:99], v128 offset:18528
	s_waitcnt lgkmcnt(1)
	v_mfma_f32_32x32x16_bf16 v[0:15], v[84:87], v[80:83], v[0:15]
	ds_read_b128 v[84:87], v128 offset:23136
	v_mfma_f32_32x32x16_bf16 v[64:79], v[104:107], v[80:83], v[64:79]
	v_cvt_pk_bf16_f32 v80, v152, v153
	v_cvt_pk_bf16_f32 v81, v154, v155
	v_cvt_pk_bf16_f32 v82, v156, v157
	v_cvt_pk_bf16_f32 v83, v168, v169
	s_waitcnt lgkmcnt(0)
	s_nop 0
	v_mfma_f32_32x32x16_bf16 v[48:63], v[84:87], v[80:83], v[48:63]
	ds_read_b128 v[84:87], v128 offset:27744
	s_waitcnt lgkmcnt(0)
	v_mfma_f32_32x32x16_bf16 v[32:47], v[84:87], v[80:83], v[32:47]
	ds_read_b128 v[84:87], v128 offset:32352
	s_waitcnt lgkmcnt(0)
	s_barrier
	v_mfma_f32_32x32x16_bf16 v[64:79], v[96:99], v[80:83], v[64:79]
	ds_read_b128 v[96:99], v129 offset:36864
	ds_read_b128 v[100:103], v129 offset:41472
	ds_read_b128 v[104:107], v129 offset:36896
	v_mfma_f32_32x32x16_bf16 v[0:15], v[84:87], v[80:83], v[0:15]
	v_add_f32_e32 v80, v138, v139
	v_add_f32_e32 v80, 0, v80
	v_add_f32_e32 v81, v142, v143
	v_add_f32_e32 v138, v81, v80
	v_exp_f32_e32 v139, v165
	s_waitcnt lgkmcnt(2)
	v_mfma_f32_32x32x16_bf16 v[80:95], v[96:99], v[112:115], v[16:31]
	v_add_f32_e32 v96, v144, v145
	v_add_f32_e32 v96, v96, v138
	v_add_f32_e32 v97, v146, v147
	v_add_f32_e32 v138, v97, v96
	v_add_f32_e32 v134, v134, v138
	ds_read_b128 v[96:99], v129 offset:41504
	s_waitcnt lgkmcnt(2)
	v_mfma_f32_32x32x16_bf16 v[16:31], v[100:103], v[112:115], v[16:31]
	v_add_f32_e32 v100, v136, v137
	v_add_f32_e32 v100, v100, v134
	v_add_f32_e32 v101, v108, v109
	v_add_f32_e32 v100, v101, v100
	v_add_f32_e32 v101, v110, v111
	v_add_f32_e32 v100, v101, v100
	v_add_f32_e32 v101, v130, v131
	v_add_f32_e32 v100, v101, v100
	v_add_f32_e32 v101, v132, v133
	s_waitcnt lgkmcnt(1)
	v_mfma_f32_32x32x16_bf16 v[80:95], v[104:107], v[116:119], v[80:95]
	v_add_f32_e32 v104, v101, v100
	ds_read_b128 v[100:103], v129 offset:36928
	v_add_f32_e32 v105, v148, v149
	v_add_f32_e32 v104, v105, v104
	v_add_f32_e32 v105, v150, v151
	v_add_f32_e32 v108, v105, v104
	v_add_f32_e32 v109, v152, v153
	s_waitcnt lgkmcnt(0)
	v_mfma_f32_32x32x16_bf16 v[80:95], v[100:103], v[124:127], v[80:95]
	v_add_f32_e32 v110, v154, v155
	v_add_f32_e32 v100, v109, v108
	v_add_f32_e32 v111, v156, v157
	v_add_f32_e32 v100, v110, v100
	v_add_f32_e32 v112, v168, v169
	v_add_f32_e32 v100, v111, v100
	v_add_f32_e32 v108, v112, v100
	v_mfma_f32_32x32x16_bf16 v[16:31], v[96:99], v[116:119], v[16:31]
	ds_read_b128 v[96:99], v129 offset:41536
	ds_read_b128 v[104:107], v129 offset:36960
	ds_read_b128 v[100:103], v129 offset:41568
	v_add_f32_e32 v129, v167, v108
	v_add_f32_e32 v108, v163, v164
	v_mul_f32_e32 v138, 0x3fb8aa3b, v108
	v_add_u32_e32 v150, 0xd800, v128
	s_waitcnt lgkmcnt(1)
	v_mfma_f32_32x32x16_bf16 v[80:95], v[104:107], v[120:123], v[80:95]
	v_mfma_f32_32x32x16_bf16 v[16:31], v[96:99], v[124:127], v[16:31]
	s_nop 10
	v_exp_f32_e32 v154, v80
	v_exp_f32_e32 v155, v81
	v_exp_f32_e32 v156, v82
	v_exp_f32_e32 v157, v83
	v_exp_f32_e32 v163, v84
	v_exp_f32_e32 v164, v85
	v_exp_f32_e32 v165, v86
	v_exp_f32_e32 v166, v87
	ds_read_b128 v[96:99], v128 offset:55296
	ds_read_b128 v[108:111], v128 offset:55328
	ds_read_b128 v[112:115], v128 offset:59904
	ds_read_b128 v[116:119], v128 offset:59936
	s_waitcnt lgkmcnt(4)
	v_mfma_f32_32x32x16_bf16 v[16:31], v[100:103], v[120:123], v[16:31]
	ds_read_b128 v[84:87], v128 offset:64512
	ds_read_b128 v[100:103], v128 offset:64544
	v_cvt_pk_bf16_f32 v80, v154, v155
	v_cvt_pk_bf16_f32 v81, v156, v157
	v_cvt_pk_bf16_f32 v82, v163, v164
	v_cvt_pk_bf16_f32 v83, v165, v166
	s_nop 5
	v_exp_f32_e32 v16, v16
	s_waitcnt lgkmcnt(5)
	v_mfma_f32_32x32x16_bf16 v[64:79], v[96:99], v[80:83], v[64:79]
	ds_read_b128 v[96:99], v150 offset:13824
	ds_read_b128 v[104:107], v150 offset:13856
	ds_read_b128 v[120:123], v128 offset:55360
	ds_read_b128 v[124:127], v128 offset:55392
	ds_read_b128 v[130:133], v128 offset:59968
	ds_read_b128 v[134:137], v128 offset:60000
	ds_read_b128 v[142:145], v128 offset:64576
	v_exp_f32_e32 v17, v17
	v_exp_f32_e32 v18, v18
	v_exp_f32_e32 v19, v19
	v_exp_f32_e32 v20, v20
	v_exp_f32_e32 v21, v21
	v_exp_f32_e32 v22, v22
	s_waitcnt lgkmcnt(10)
; #define MFMA(a, b, c) __builtin_amdgcn_mfma_f32_32x32x16_bf16((a), (b), (c), 0, 0, 0)
; DI void attn_item(const P& p, int l, int item, char* smem) {
;     ...
;           const float p0 = __builtin_amdgcn_exp2f(S[kb][8 * s + 2 * j2]);
;           const float p1 = __builtin_amdgcn_exp2f(S[kb][8 * s + 2 * j2 + 1]);
;           sum += p0 + p1;
;           pk[ch][j2] = pack2(p0, p1);
;         }
;       }
;       ls += sum;
; #pragma unroll
;       for (int i = 0; i < 16; ++i) {
;         const int eb = i & 3, ch = i >> 2;
;         O[eb] = MFMA(__builtin_bit_cast(bf16x8, vf[i]), __builtin_bit_cast(bf16x8, pk[ch]), O[eb]);
;       }
;     }
;     __syncthreads();
;   }
;   const float lt = ls + __shfl_xor(ls, 32);
;   const float inv = (c == 0) ? (1.0f / lt) : (lam / lt);
;   float* exch = (float*)smem + qg * (64 * 64);
;   if (c == 1) {
	v_mfma_f32_32x32x16_bf16 v[48:63], v[112:115], v[80:83], v[48:63]
	ds_read_b128 v[112:115], v128 offset:64608
	ds_read_b128 v[146:149], v150 offset:13888
	ds_read_b128 v[150:153], v150 offset:13920
	v_add_f32_e32 v128, v154, v155
	v_add_f32_e32 v128, 0, v128
	v_add_f32_e32 v154, v156, v157
	v_add_f32_e32 v128, v154, v128
	v_exp_f32_e32 v23, v23
	s_waitcnt lgkmcnt(0)
	v_mfma_f32_32x32x16_bf16 v[32:47], v[84:87], v[80:83], v[32:47]
	v_exp_f32_e32 v85, v88
	v_exp_f32_e32 v86, v89
	v_exp_f32_e32 v87, v90
	v_exp_f32_e32 v88, v91
	v_add_f32_e32 v84, v163, v164
	v_exp_f32_e32 v89, v92
	v_exp_f32_e32 v90, v93
	v_add_f32_e32 v84, v84, v128
	v_mfma_f32_32x32x16_bf16 v[0:15], v[96:99], v[80:83], v[0:15]
	v_exp_f32_e32 v91, v94
	v_exp_f32_e32 v92, v95
	v_add_f32_e32 v93, v165, v166
	v_cvt_pk_bf16_f32 v80, v85, v86
	v_add_f32_e32 v84, v93, v84
	v_add_f32_e32 v85, v85, v86
	v_add_f32_e32 v84, v85, v84
	v_add_f32_e32 v85, v87, v88
	v_add_f32_e32 v84, v85, v84
	v_add_f32_e32 v85, v89, v90
	v_add_f32_e32 v84, v85, v84
	v_add_f32_e32 v85, v91, v92
	v_add_f32_e32 v84, v85, v84
	v_add_f32_e32 v85, v16, v17
	v_add_f32_e32 v84, v85, v84
	v_cvt_pk_bf16_f32 v16, v16, v17
	v_add_f32_e32 v17, v18, v19
	v_cvt_pk_bf16_f32 v81, v87, v88
	v_cvt_pk_bf16_f32 v82, v89, v90
	v_cvt_pk_bf16_f32 v83, v91, v92
	v_add_f32_e32 v84, v17, v84
	v_cvt_pk_bf16_f32 v17, v18, v19
	v_add_f32_e32 v18, v20, v21
	v_mfma_f32_32x32x16_bf16 v[64:79], v[108:111], v[80:83], v[64:79]
	v_cvt_pk_bf16_f32 v19, v22, v23
	s_barrier
	v_mfma_f32_32x32x16_bf16 v[48:63], v[116:119], v[80:83], v[48:63]
	v_mfma_f32_32x32x16_bf16 v[32:47], v[100:103], v[80:83], v[32:47]
	v_mfma_f32_32x32x16_bf16 v[0:15], v[104:107], v[80:83], v[0:15]
	v_add_f32_e32 v80, v18, v84
	v_cvt_pk_bf16_f32 v18, v20, v21
	v_add_f32_e32 v20, v22, v23
	v_exp_f32_e32 v21, v24
	v_exp_f32_e32 v22, v25
	v_exp_f32_e32 v23, v26
	v_exp_f32_e32 v25, v27
	v_add_f32_e32 v24, v20, v80
	v_add_f32_e32 v26, v21, v22
	v_cvt_pk_bf16_f32 v20, v21, v22
	v_add_f32_e32 v27, v23, v25
	v_cvt_pk_bf16_f32 v21, v23, v25
	v_exp_f32_e32 v22, v28
	v_exp_f32_e32 v23, v29
	v_exp_f32_e32 v25, v30
	v_exp_f32_e32 v28, v31
	v_add_f32_e32 v24, v26, v24
	v_add_f32_e32 v29, v22, v23
	v_add_f32_e32 v24, v27, v24
	v_add_f32_e32 v30, v25, v28
	v_add_f32_e32 v24, v29, v24
	v_mfma_f32_32x32x16_bf16 v[64:79], v[120:123], v[16:19], v[64:79]
	v_cvt_pk_bf16_f32 v22, v22, v23
	v_cvt_pk_bf16_f32 v23, v25, v28
	v_mfma_f32_32x32x16_bf16 v[48:63], v[130:133], v[16:19], v[48:63]
	v_mfma_f32_32x32x16_bf16 v[32:47], v[142:145], v[16:19], v[32:47]
	v_mfma_f32_32x32x16_bf16 v[0:15], v[146:149], v[16:19], v[0:15]
	v_add_f32_e32 v16, v30, v24
	v_exp_f32_e32 v17, v138
	v_add_f32_e32 v16, v129, v16
	ds_bpermute_b32 v18, v158, v16
	v_sub_f32_e32 v17, v17, v139
	v_add_f32_e32 v17, s6, v17
	s_movk_i32 s6, 0x100
	v_cmp_gt_u32_e64 s[6:7], s6, v161
	s_waitcnt lgkmcnt(0)
	v_add_f32_e32 v16, v16, v18
	v_mfma_f32_32x32x16_bf16 v[64:79], v[124:127], v[20:23], v[64:79]
	v_cndmask_b32_e64 v17, v17, 1.0, s[6:7]
	v_div_scale_f32 v18, s[10:11], v16, v16, v17
	v_rcp_f32_e32 v19, v18
	s_nop 0
	v_fma_f32 v24, -v18, v19, 1.0
	v_mfma_f32_32x32x16_bf16 v[48:63], v[134:137], v[20:23], v[48:63]
	v_fmac_f32_e32 v19, v24, v19
	v_div_scale_f32 v24, vcc, v17, v16, v17
	v_mul_f32_e32 v25, v24, v19
	v_fma_f32 v26, -v18, v25, v24
	v_fmac_f32_e32 v25, v26, v19
	v_fma_f32 v18, -v18, v25, v24
	v_mfma_f32_32x32x16_bf16 v[32:47], v[112:115], v[20:23], v[32:47]
	v_div_fmas_f32 v18, v18, v19, v25
	v_div_fixup_f32 v80, v18, v16, v17
	v_lshl_add_u32 v16, v162, 14, 0
	v_cmp_eq_u32_e32 vcc, 1, v160
	v_lshl_add_u32 v18, v141, 2, v16
	v_mfma_f32_32x32x16_bf16 v[0:15], v[150:153], v[20:23], v[0:15]
	s_and_saveexec_b64 s[10:11], vcc
	s_cbranch_execz .LBB0_469
; DI void attn_item(const P& p, int l, int item, char* smem) {
;     ...
;   if (c == 1) {
; #pragma unroll
;     for (int eb = 0; eb < 4; ++eb)
; #pragma unroll
;       for (int r = 0; r < 16; ++r) exch[(eb * 16 + r) * 64 + lane] = O[eb][r] * inv;
;   }
	v_mul_f32_e32 v16, v64, v80
	v_mul_f32_e32 v17, v65, v80
	ds_write2st64_b32 v18, v16, v17 offset1:1
	v_mul_f32_e32 v16, v66, v80
	v_mul_f32_e32 v17, v67, v80
	ds_write2st64_b32 v18, v16, v17 offset0:2 offset1:3
	v_mul_f32_e32 v16, v68, v80
	v_mul_f32_e32 v17, v69, v80
	ds_write2st64_b32 v18, v16, v17 offset0:4 offset1:5
	v_mul_f32_e32 v16, v70, v80
	v_mul_f32_e32 v17, v71, v80
	ds_write2st64_b32 v18, v16, v17 offset0:6 offset1:7
	v_mul_f32_e32 v16, v72, v80
	v_mul_f32_e32 v17, v73, v80
	ds_write2st64_b32 v18, v16, v17 offset0:8 offset1:9
	v_mul_f32_e32 v16, v74, v80
	v_mul_f32_e32 v17, v75, v80
	ds_write2st64_b32 v18, v16, v17 offset0:10 offset1:11
	v_mul_f32_e32 v16, v76, v80
	v_mul_f32_e32 v17, v77, v80
	ds_write2st64_b32 v18, v16, v17 offset0:12 offset1:13
	v_mul_f32_e32 v16, v78, v80
	v_mul_f32_e32 v17, v79, v80
	ds_write2st64_b32 v18, v16, v17 offset0:14 offset1:15
	v_mul_f32_e32 v16, v48, v80
	v_mul_f32_e32 v17, v49, v80
	ds_write2st64_b32 v18, v16, v17 offset0:16 offset1:17
	v_mul_f32_e32 v16, v50, v80
	v_mul_f32_e32 v17, v51, v80
	ds_write2st64_b32 v18, v16, v17 offset0:18 offset1:19
	v_mul_f32_e32 v16, v52, v80
	v_mul_f32_e32 v17, v53, v80
	ds_write2st64_b32 v18, v16, v17 offset0:20 offset1:21
	v_mul_f32_e32 v16, v54, v80
	v_mul_f32_e32 v17, v55, v80
	ds_write2st64_b32 v18, v16, v17 offset0:22 offset1:23
	v_mul_f32_e32 v16, v56, v80
	v_mul_f32_e32 v17, v57, v80
	ds_write2st64_b32 v18, v16, v17 offset0:24 offset1:25
	v_mul_f32_e32 v16, v58, v80
	v_mul_f32_e32 v17, v59, v80
	ds_write2st64_b32 v18, v16, v17 offset0:26 offset1:27
	v_mul_f32_e32 v16, v60, v80
	v_mul_f32_e32 v17, v61, v80
	ds_write2st64_b32 v18, v16, v17 offset0:28 offset1:29
	v_mul_f32_e32 v16, v62, v80
	v_mul_f32_e32 v17, v63, v80
	ds_write2st64_b32 v18, v16, v17 offset0:30 offset1:31
	v_mul_f32_e32 v16, v32, v80
	v_mul_f32_e32 v17, v33, v80
	ds_write2st64_b32 v18, v16, v17 offset0:32 offset1:33
	v_mul_f32_e32 v16, v34, v80
	v_mul_f32_e32 v17, v35, v80
	ds_write2st64_b32 v18, v16, v17 offset0:34 offset1:35
	v_mul_f32_e32 v16, v36, v80
	v_mul_f32_e32 v17, v37, v80
	ds_write2st64_b32 v18, v16, v17 offset0:36 offset1:37
	v_mul_f32_e32 v16, v38, v80
	v_mul_f32_e32 v17, v39, v80
	ds_write2st64_b32 v18, v16, v17 offset0:38 offset1:39
	v_mul_f32_e32 v16, v40, v80
	v_mul_f32_e32 v17, v41, v80
	ds_write2st64_b32 v18, v16, v17 offset0:40 offset1:41
	v_mul_f32_e32 v16, v42, v80
	v_mul_f32_e32 v17, v43, v80
	ds_write2st64_b32 v18, v16, v17 offset0:42 offset1:43
	v_mul_f32_e32 v16, v44, v80
	v_mul_f32_e32 v17, v45, v80
	ds_write2st64_b32 v18, v16, v17 offset0:44 offset1:45
	v_mul_f32_e32 v16, v46, v80
	v_mul_f32_e32 v17, v47, v80
	ds_write2st64_b32 v18, v16, v17 offset0:46 offset1:47
	v_mul_f32_e32 v16, v0, v80
	v_mul_f32_e32 v17, v1, v80
	ds_write2st64_b32 v18, v16, v17 offset0:48 offset1:49
	v_mul_f32_e32 v16, v2, v80
	v_mul_f32_e32 v17, v3, v80
	ds_write2st64_b32 v18, v16, v17 offset0:50 offset1:51
	v_mul_f32_e32 v16, v4, v80
	v_mul_f32_e32 v17, v5, v80
	ds_write2st64_b32 v18, v16, v17 offset0:52 offset1:53
	v_mul_f32_e32 v16, v6, v80
	v_mul_f32_e32 v17, v7, v80
	ds_write2st64_b32 v18, v16, v17 offset0:54 offset1:55
	v_mul_f32_e32 v16, v8, v80
	v_mul_f32_e32 v17, v9, v80
	ds_write2st64_b32 v18, v16, v17 offset0:56 offset1:57
	v_mul_f32_e32 v16, v10, v80
	v_mul_f32_e32 v17, v11, v80
	ds_write2st64_b32 v18, v16, v17 offset0:58 offset1:59
	v_mul_f32_e32 v16, v12, v80
	v_mul_f32_e32 v17, v13, v80
	ds_write2st64_b32 v18, v16, v17 offset0:60 offset1:61
	v_mul_f32_e32 v16, v14, v80
	v_mul_f32_e32 v17, v15, v80
	ds_write2st64_b32 v18, v16, v17 offset0:62 offset1:63

; __global__ void __launch_bounds__(NT) mega(P p) {
	.amdhsa_kernel _Z4mega1P
		.amdhsa_group_segment_fixed_size 0
		.amdhsa_private_segment_fixed_size 0
		.amdhsa_kernarg_size 560
		.amdhsa_user_sgpr_count 2
		.amdhsa_user_sgpr_dispatch_ptr 0
		.amdhsa_user_sgpr_queue_ptr 0
		.amdhsa_user_sgpr_kernarg_segment_ptr 1
		.amdhsa_user_sgpr_dispatch_id 0
		.amdhsa_user_sgpr_kernarg_preload_length 0
		.amdhsa_user_sgpr_kernarg_preload_offset 0
		.amdhsa_user_sgpr_private_segment_size 0
		.amdhsa_uses_dynamic_stack 0
		.amdhsa_enable_private_segment 0
		.amdhsa_system_sgpr_workgroup_id_x 1
		.amdhsa_system_sgpr_workgroup_id_y 0
		.amdhsa_system_sgpr_workgroup_id_z 0
		.amdhsa_system_sgpr_workgroup_info 0
		.amdhsa_system_vgpr_workitem_id 2
		.amdhsa_next_free_vgpr 252
		.amdhsa_next_free_sgpr 98
		.amdhsa_accum_offset 252
		.amdhsa_reserve_vcc 1
		.amdhsa_float_round_mode_32 0
		.amdhsa_float_round_mode_16_64 0
		.amdhsa_float_denorm_mode_32 3
		.amdhsa_float_denorm_mode_16_64 3
		.amdhsa_dx10_clamp 1
		.amdhsa_ieee_mode 1
		.amdhsa_fp16_overflow 0
		.amdhsa_tg_split 0
		.amdhsa_exception_fp_ieee_invalid_op 0
		.amdhsa_exception_fp_denorm_src 0
		.amdhsa_exception_fp_ieee_div_zero 0
		.amdhsa_exception_fp_ieee_overflow 0
		.amdhsa_exception_fp_ieee_underflow 0
		.amdhsa_exception_fp_ieee_inexact 0
		.amdhsa_exception_int_div_zero 0
	.end_amdhsa_kernel

; __global__ void __launch_bounds__(NT) mega(P p) {
amdhsa.kernels:
  - .agpr_count:     0
    .args:
      - .offset:         0
        .size:           304
        .value_kind:     by_value
      - .offset:         304
        .size:           4
        .value_kind:     hidden_block_count_x
      - .offset:         308
        .size:           4
        .value_kind:     hidden_block_count_y
      - .offset:         312
        .size:           4
        .value_kind:     hidden_block_count_z
      - .offset:         316
        .size:           2
        .value_kind:     hidden_group_size_x
      - .offset:         318
        .size:           2
        .value_kind:     hidden_group_size_y
      - .offset:         320
        .size:           2
        .value_kind:     hidden_group_size_z
      - .offset:         322
        .size:           2
        .value_kind:     hidden_remainder_x
      - .offset:         324
        .size:           2
        .value_kind:     hidden_remainder_y
      - .offset:         326
        .size:           2
        .value_kind:     hidden_remainder_z
      - .offset:         344
        .size:           8
        .value_kind:     hidden_global_offset_x
      - .offset:         352
        .size:           8
        .value_kind:     hidden_global_offset_y
      - .offset:         360
        .size:           8
        .value_kind:     hidden_global_offset_z
      - .offset:         368
        .size:           2
        .value_kind:     hidden_grid_dims
      - .offset:         392
        .size:           8
        .value_kind:     hidden_multigrid_sync_arg
      - .offset:         424
        .size:           4
        .value_kind:     hidden_dynamic_lds_size
    .group_segment_fixed_size: 0
    .kernarg_segment_align: 8
    .kernarg_segment_size: 560
    .language:       OpenCL C
    .language_version:
      - 2
      - 0
    .max_flat_workgroup_size: 512
    .name:           _Z4mega1P
    .private_segment_fixed_size: 0
    .sgpr_count:     104
    .sgpr_spill_count: 54
    .symbol:         _Z4mega1P.kd
    .uniform_work_group_size: 1
    .uses_dynamic_stack: false
    .vgpr_count:     252
    .vgpr_spill_count: 0
    .wavefront_size: 64
